# v044 + WO int8 residual epilogue: 8 per-row arow scales preloaded up front, per-row waits counted (vmcnt(12)/(8)/(4)) instead of vmcnt(0) drains, so the next row's X loads stay in flight (4 layers)
# speedup vs baseline: 1.0010x; 1.0002x over previous
.LBB0_899:
	s_lshr_b32 s16, s94, 4
	s_add_i32 s16, s16, -1
	s_cmp_gt_i32 s94, 31
	s_cselect_b32 s16, s16, 0
	v_lshl_or_b32 v70, s12, 8, v228
	s_mul_i32 s47, s16, 0xc000
	s_mul_hi_i32 s46, s16, 0xc000
	s_add_u32 s16, s91, s47
	v_ashrrev_i32_e32 v71, 31, v70
	s_addc_u32 s17, s92, s46
	v_lshlrev_b64 v[108:109], 2, v[70:71]
	v_lshl_add_u64 v[26:27], s[16:17], 0, v[108:109]
	v_lshl_add_u64 v[28:29], s[24:25], 0, v[108:109]
	s_waitcnt lgkmcnt(0)
	global_load_dwordx4 v[2:5], v[26:27], off offset:16
	global_load_dwordx4 v[6:9], v[26:27], off
	global_load_dwordx4 v[10:13], v[28:29], off offset:16
	global_load_dwordx4 v[14:17], v[28:29], off
	s_add_u32 s16, s88, s47
	v_lshl_add_u64 v[30:31], s[28:29], 0, v[108:109]
	s_addc_u32 s17, s89, s46
	v_lshl_add_u64 v[32:33], s[16:17], 0, v[108:109]
	v_lshl_add_u32 v118, s94, 8, v226
	v_cmp_gt_i32_e32 vcc, s87, v118
	v_ashrrev_i32_e32 v119, 31, v118
	v_or_b32_e32 v34, 16, v118
	v_ashrrev_i32_e32 v35, 31, v34
	s_lshl_b32 s46, s12, 2
	s_ashr_i32 s47, s46, 31
	s_waitcnt vmcnt(0)
	v_pk_mul_f32 v[88:89], v[4:5], v[12:13]
	v_pk_mul_f32 v[76:77], v[8:9], v[16:17]
	v_pk_mul_f32 v[78:79], v[6:7], v[14:15]
	global_load_dwordx4 v[6:9], v[30:31], off offset:16
	global_load_dwordx4 v[14:17], v[30:31], off
	global_load_dwordx4 v[18:21], v[32:33], off offset:16
	global_load_dwordx4 v[22:25], v[32:33], off
	v_pk_mul_f32 v[90:91], v[2:3], v[10:11]
	s_waitcnt vmcnt(0)
	v_pk_add_f32 v[2:3], v[20:21], 1.0 op_sel_hi:[1,0]
	v_pk_add_f32 v[24:25], v[24:25], 1.0 op_sel_hi:[1,0]
	v_pk_add_f32 v[22:23], v[22:23], 1.0 op_sel_hi:[1,0]
	v_pk_add_f32 v[4:5], v[18:19], 1.0 op_sel_hi:[1,0]
	v_pk_mul_f32 v[80:81], v[16:17], v[24:25]
	v_pk_mul_f32 v[82:83], v[14:15], v[22:23]
	v_pk_mul_f32 v[84:85], v[8:9], v[2:3]
	v_pk_mul_f32 v[86:87], v[6:7], v[4:5]
	global_load_dwordx4 v[2:5], v[26:27], off offset:528
	global_load_dwordx4 v[6:9], v[26:27], off offset:512
	global_load_dwordx4 v[10:13], v[28:29], off offset:528
	global_load_dwordx4 v[14:17], v[28:29], off offset:512
	s_waitcnt vmcnt(0)
	v_pk_mul_f32 v[72:73], v[2:3], v[10:11]
	v_pk_mul_f32 v[66:67], v[8:9], v[16:17]
	v_pk_mul_f32 v[68:69], v[6:7], v[14:15]
	global_load_dwordx4 v[6:9], v[30:31], off offset:528
	global_load_dwordx4 v[14:17], v[30:31], off offset:512
	global_load_dwordx4 v[18:21], v[32:33], off offset:528
	global_load_dwordx4 v[22:25], v[32:33], off offset:512
	v_pk_mul_f32 v[74:75], v[4:5], v[12:13]
	s_waitcnt vmcnt(0)
	v_pk_add_f32 v[2:3], v[20:21], 1.0 op_sel_hi:[1,0]
	v_pk_add_f32 v[4:5], v[18:19], 1.0 op_sel_hi:[1,0]
	v_pk_mul_f32 v[62:63], v[8:9], v[2:3]
	v_add_u32_e32 v2, 0xffffe000, v118
	v_pk_mul_f32 v[64:65], v[6:7], v[4:5]
	v_cndmask_b32_e32 v3, 0, v119, vcc
	v_cndmask_b32_e32 v2, v2, v118, vcc
	v_mov_b32_e32 v6, s59
	v_mov_b32_e32 v7, s57
	v_mov_b32_e32 v8, s58
	v_mov_b32_e32 v9, s56
	v_cndmask_b32_e32 v5, v6, v7, vcc
	v_cndmask_b32_e32 v4, v8, v9, vcc
	v_lshlrev_b64 v[2:3], 13, v[2:3]
	v_lshl_add_u64 v[2:3], v[4:5], 0, v[2:3]
	v_pk_add_f32 v[24:25], v[24:25], 1.0 op_sel_hi:[1,0]
	v_pk_add_f32 v[22:23], v[22:23], 1.0 op_sel_hi:[1,0]
	v_lshl_add_u64 v[2:3], v[2:3], 0, v[108:109]
	v_pk_mul_f32 v[58:59], v[16:17], v[24:25]
	v_pk_mul_f32 v[60:61], v[14:15], v[22:23]
	v_lshl_add_u64 v[176:177], v[118:119], 2, s[22:23]
	global_load_dword v240, v[176:177], off
	global_load_dword v241, v[176:177], off offset:64
	global_load_dword v242, v[176:177], off offset:128
	global_load_dword v243, v[176:177], off offset:192
	global_load_dword v244, v[176:177], off offset:512
	global_load_dword v245, v[176:177], off offset:576
	global_load_dword v246, v[176:177], off offset:640
	global_load_dword v247, v[176:177], off offset:704
	global_load_dwordx4 v[26:29], v[2:3], off offset:16 nt
	global_load_dwordx4 v[30:33], v[2:3], off nt
	global_load_dwordx4 v[18:21], v[2:3], off offset:528 nt
	global_load_dwordx4 v[22:25], v[2:3], off offset:512 nt
	v_cmp_gt_i32_e32 vcc, s87, v34
	v_add_u32_e32 v2, 0xffffe010, v118
	s_nop 0
	v_cndmask_b32_e32 v3, 0, v35, vcc
	v_cndmask_b32_e32 v2, v2, v34, vcc
	v_cndmask_b32_e32 v5, v6, v7, vcc
	v_cndmask_b32_e32 v4, v8, v9, vcc
	v_lshlrev_b64 v[2:3], 13, v[2:3]
	v_lshl_add_u64 v[2:3], v[4:5], 0, v[2:3]
	v_lshl_add_u64 v[6:7], v[2:3], 0, v[108:109]
	global_load_dwordx4 v[10:13], v[6:7], off offset:16 nt
	global_load_dwordx4 v[14:17], v[6:7], off nt
	global_load_dwordx4 v[2:5], v[6:7], off offset:528 nt
	s_nop 0
	global_load_dwordx4 v[6:9], v[6:7], off offset:512 nt
	v_lshl_add_u64 v[176:177], v[118:119], 2, s[22:23]
	s_nop 0
	v_lshlrev_b64 v[36:37], 13, v[118:119]
	v_lshl_add_u64 v[36:37], s[20:21], 0, v[36:37]
	v_lshl_add_u64 v[36:37], v[36:37], 0, v[108:109]
	s_waitcnt vmcnt(4)
	v_mov_b32_e32 v38, v240
	v_pk_mul_f32 v[40:41], v[38:39], v[220:221] op_sel_hi:[0,1]
	v_pk_mul_f32 v[218:219], v[38:39], v[218:219] op_sel_hi:[0,1]
	v_pk_fma_f32 v[32:33], v[76:77], v[218:219], v[32:33]
	v_pk_fma_f32 v[30:31], v[78:79], v[40:41], v[30:31]
	v_pk_mul_f32 v[220:221], v[38:39], v[224:225] op_sel_hi:[0,1]
	v_pk_mul_f32 v[222:223], v[38:39], v[222:223] op_sel_hi:[0,1]
	v_mul_f32_e32 v39, v31, v31
	v_mul_f32_e32 v40, v33, v33
	v_pk_fma_f32 v[26:27], v[90:91], v[220:221], v[26:27]
	v_fmac_f32_e32 v39, v30, v30
	v_fmac_f32_e32 v40, v32, v32
	v_add_f32_e32 v39, v39, v40
	v_mul_f32_e32 v40, v27, v27
	v_pk_fma_f32 v[28:29], v[88:89], v[222:223], v[28:29]
	v_fmac_f32_e32 v40, v26, v26
	v_add_f32_e32 v39, v40, v39
	v_mul_f32_e32 v40, v29, v29
	global_store_dwordx4 v[36:37], v[30:33], off nt
	global_store_dwordx4 v[36:37], v[26:29], off offset:16 nt
	v_fmac_f32_e32 v40, v28, v28
	v_pk_mul_f32 v[30:31], v[82:83], v[30:31]
	v_add_f32_e32 v218, v40, v39
	v_pk_mul_f32 v[40:41], v[84:85], v[28:29]
	v_pk_mul_f32 v[28:29], v[86:87], v[26:27]
	v_cvt_pk_bf16_f32 v26, v30, v31
	v_lshlrev_b64 v[30:31], 12, v[118:119]
	v_lshl_add_u64 v[30:31], s[26:27], 0, v[30:31]
	v_pk_mul_f32 v[32:33], v[80:81], v[32:33]
	v_lshl_add_u64 v[30:31], v[70:71], 1, v[30:31]
	v_cvt_pk_bf16_f32 v27, v32, v33
	v_cvt_pk_bf16_f32 v28, v28, v29
	v_cvt_pk_bf16_f32 v29, v40, v41
	global_store_dwordx4 v[30:31], v[26:29], off
	v_lshlrev_b32_e32 v32, 16, v26
	s_nop 0
	v_and_b32_e32 v26, 0xffff0000, v26
	v_max3_f32 v26, |v32|, 0, |v26|
	v_lshlrev_b32_e32 v32, 16, v27
	v_and_b32_e32 v27, 0xffff0000, v27
	v_max3_f32 v26, v26, |v32|, |v27|
	v_lshlrev_b32_e32 v27, 16, v28
	v_and_b32_e32 v28, 0xffff0000, v28
	v_max3_f32 v26, v26, |v27|, |v28|
	v_lshlrev_b32_e32 v27, 16, v29
	v_and_b32_e32 v28, 0xffff0000, v29
	v_max3_f32 v40, v26, |v27|, |v28|
	v_pk_mul_f32 v[26:27], v[38:39], v[212:213] op_sel_hi:[0,1]
	v_pk_mul_f32 v[28:29], v[38:39], v[210:211] op_sel_hi:[0,1]
	v_pk_mul_f32 v[32:33], v[38:39], v[216:217] op_sel_hi:[0,1]
	v_pk_fma_f32 v[24:25], v[66:67], v[28:29], v[24:25]
	v_pk_fma_f32 v[22:23], v[68:69], v[26:27], v[22:23]
	v_pk_fma_f32 v[26:27], v[72:73], v[32:33], v[18:19]
	v_mul_f32_e32 v18, v23, v23
	v_mul_f32_e32 v19, v25, v25
	v_fmac_f32_e32 v18, v22, v22
	v_fmac_f32_e32 v19, v24, v24
	v_pk_mul_f32 v[38:39], v[38:39], v[214:215] op_sel_hi:[0,1]
	v_add_f32_e32 v18, v18, v19
	v_mul_f32_e32 v19, v27, v27
	v_pk_fma_f32 v[28:29], v[74:75], v[38:39], v[20:21]
	v_fmac_f32_e32 v19, v26, v26
	v_add_f32_e32 v18, v19, v18
	v_mul_f32_e32 v19, v29, v29
	v_fmac_f32_e32 v19, v28, v28
	v_pk_mul_f32 v[20:21], v[60:61], v[22:23]
	global_store_dwordx4 v[36:37], v[22:25], off offset:512 nt
	global_store_dwordx4 v[36:37], v[26:29], off offset:528 nt
	v_add_f32_e32 v18, v19, v18
	v_pk_mul_f32 v[22:23], v[64:65], v[26:27]
	v_cvt_pk_bf16_f32 v20, v20, v21
	v_add_f32_e32 v19, v218, v18
	v_pk_mul_f32 v[24:25], v[58:59], v[24:25]
	v_pk_mul_f32 v[28:29], v[62:63], v[28:29]
	v_cvt_pk_bf16_f32 v21, v24, v25
	v_cvt_pk_bf16_f32 v22, v22, v23
	v_lshlrev_b32_e32 v18, 16, v20
	v_cvt_pk_bf16_f32 v23, v28, v29
	global_store_dwordx4 v[30:31], v[20:23], off offset:256
	s_nop 1
	v_and_b32_e32 v20, 0xffff0000, v20
	v_max3_f32 v18, v40, |v18|, |v20|
	v_lshlrev_b32_e32 v20, 16, v21
	v_and_b32_e32 v21, 0xffff0000, v21
	v_max3_f32 v18, v18, |v20|, |v21|
	v_lshlrev_b32_e32 v20, 16, v22
	v_and_b32_e32 v21, 0xffff0000, v22
	v_max3_f32 v18, v18, |v20|, |v21|
	v_lshlrev_b32_e32 v20, 16, v23
	v_and_b32_e32 v21, 0xffff0000, v23
	v_max3_f32 v18, v18, |v20|, |v21|
	v_and_b32_e32 v21, 64, v230
	v_xor_b32_e32 v20, 16, v230
	v_add_u32_e32 v21, 64, v21
	v_cmp_lt_i32_e32 vcc, v20, v21
	s_nop 1
	v_cndmask_b32_e32 v20, v230, v20, vcc
	v_lshlrev_b32_e32 v212, 2, v20
	ds_bpermute_b32 v20, v212, v19
	s_waitcnt lgkmcnt(0)
	v_add_f32_e32 v19, v19, v20
	v_xor_b32_e32 v20, 32, v230
	v_cmp_lt_i32_e32 vcc, v20, v21
	ds_bpermute_b32 v21, v212, v18
	s_waitcnt lgkmcnt(0)
	v_max_f32_e32 v21, v21, v21
	v_cndmask_b32_e32 v20, v230, v20, vcc
	v_lshlrev_b32_e32 v213, 2, v20
	v_max_f32_e32 v18, v18, v21
	ds_bpermute_b32 v20, v213, v19
	ds_bpermute_b32 v21, v213, v18
	s_and_saveexec_b64 s[50:51], s[0:1]
	s_cbranch_execz .LBB0_901
	s_waitcnt lgkmcnt(0)
	v_max_f32_e32 v21, v21, v21
	v_max_f32_e32 v18, v18, v18
	v_max_f32_e32 v22, v18, v21
	v_add_f32_e32 v23, v19, v20
	v_lshlrev_b64 v[18:19], 7, v[118:119]
	v_lshl_add_u64 v[20:21], s[30:31], 0, v[18:19]
	s_lshl_b64 s[16:17], s[46:47], 2
	v_lshl_add_u64 v[18:19], s[34:35], 0, v[18:19]
	v_lshl_add_u64 v[20:21], v[20:21], 0, s[16:17]
	s_lshl_b32 s12, s93, 2
	v_lshl_add_u64 v[18:19], v[18:19], 0, s[16:17]
	v_lshl_add_u64 v[20:21], v[20:21], 0, s[12:13]
	v_lshl_add_u64 v[18:19], v[18:19], 0, s[12:13]
	global_store_dword v[20:21], v23, off
	global_store_dword v[18:19], v22, off
.LBB0_901:
	s_or_b64 exec, exec, s[50:51]
	v_or_b32_e32 v210, 32, v118
	v_ashrrev_i32_e32 v211, 31, v210
	v_add_u32_e32 v18, 0xffffe020, v118
	v_cmp_gt_i32_e32 vcc, s87, v210
	s_waitcnt lgkmcnt(1)
	v_mov_b32_e32 v20, s59
	s_waitcnt lgkmcnt(0)
	v_mov_b32_e32 v21, s57
	v_cndmask_b32_e32 v19, 0, v211, vcc
	v_cndmask_b32_e32 v18, v18, v210, vcc
	v_cndmask_b32_e32 v21, v20, v21, vcc
	v_mov_b32_e32 v20, s58
	v_mov_b32_e32 v22, s56
	v_cndmask_b32_e32 v20, v20, v22, vcc
	v_lshlrev_b64 v[18:19], 13, v[18:19]
	v_lshl_add_u64 v[18:19], v[20:21], 0, v[18:19]
	v_lshl_add_u64 v[22:23], v[18:19], 0, v[108:109]
	global_load_dwordx4 v[26:29], v[22:23], off offset:16 nt
	global_load_dwordx4 v[30:33], v[22:23], off nt
	global_load_dwordx4 v[18:21], v[22:23], off offset:528 nt
	s_nop 0
	global_load_dwordx4 v[22:25], v[22:23], off offset:512 nt
	v_lshlrev_b64 v[36:37], 13, v[34:35]
	v_lshl_add_u64 v[214:215], s[20:21], 0, v[36:37]
	v_lshl_add_u64 v[36:37], v[34:35], 2, s[22:23]
	s_nop 1
	v_mov_b32_e32 v36, v241
	s_waitcnt vmcnt(12)
	v_pk_mul_f32 v[38:39], v[36:37], v[204:205] op_sel_hi:[0,1]
	v_pk_mul_f32 v[40:41], v[36:37], v[202:203] op_sel_hi:[0,1]
	v_pk_mul_f32 v[202:203], v[36:37], v[208:209] op_sel_hi:[0,1]
	v_pk_fma_f32 v[16:17], v[76:77], v[40:41], v[16:17]
	v_pk_fma_f32 v[14:15], v[78:79], v[38:39], v[14:15]
	v_pk_fma_f32 v[38:39], v[90:91], v[202:203], v[10:11]
	v_mul_f32_e32 v10, v15, v15
	v_mul_f32_e32 v11, v17, v17
	v_fmac_f32_e32 v10, v14, v14
	v_fmac_f32_e32 v11, v16, v16
	v_pk_mul_f32 v[204:205], v[36:37], v[206:207] op_sel_hi:[0,1]
	v_add_f32_e32 v10, v10, v11
	v_mul_f32_e32 v11, v39, v39
	v_pk_fma_f32 v[40:41], v[88:89], v[204:205], v[12:13]
	v_fmac_f32_e32 v11, v38, v38
	v_add_f32_e32 v10, v11, v10
	v_mul_f32_e32 v11, v41, v41
	v_lshl_add_u64 v[12:13], v[214:215], 0, v[108:109]
	v_fmac_f32_e32 v11, v40, v40
	global_store_dwordx4 v[12:13], v[14:17], off nt
	global_store_dwordx4 v[12:13], v[38:41], off offset:16 nt
	v_add_f32_e32 v119, v11, v10
	v_pk_mul_f32 v[10:11], v[80:81], v[16:17]
	v_pk_mul_f32 v[14:15], v[82:83], v[14:15]
	v_pk_mul_f32 v[16:17], v[86:87], v[38:39]
	v_cvt_pk_bf16_f32 v14, v14, v15
	v_cvt_pk_bf16_f32 v15, v10, v11
	v_lshlrev_b64 v[10:11], 12, v[34:35]
	v_lshl_add_u64 v[10:11], s[26:27], 0, v[10:11]
	v_lshl_add_u64 v[10:11], v[70:71], 1, v[10:11]
	v_pk_mul_f32 v[40:41], v[84:85], v[40:41]
	v_cvt_pk_bf16_f32 v16, v16, v17
	v_lshlrev_b32_e32 v37, 16, v14
	v_cvt_pk_bf16_f32 v17, v40, v41
	global_store_dwordx4 v[10:11], v[14:17], off
	s_nop 1
	v_and_b32_e32 v14, 0xffff0000, v14
	v_max3_f32 v14, |v37|, 0, |v14|
	v_lshlrev_b32_e32 v37, 16, v15
	v_and_b32_e32 v15, 0xffff0000, v15
	v_max3_f32 v14, v14, |v37|, |v15|
	v_lshlrev_b32_e32 v15, 16, v16
	v_and_b32_e32 v16, 0xffff0000, v16
	v_max3_f32 v14, v14, |v15|, |v16|
	v_lshlrev_b32_e32 v15, 16, v17
	v_and_b32_e32 v16, 0xffff0000, v17
	v_max3_f32 v40, v14, |v15|, |v16|
	v_pk_mul_f32 v[14:15], v[36:37], v[198:199] op_sel_hi:[0,1]
	v_pk_mul_f32 v[16:17], v[36:37], v[194:195] op_sel_hi:[0,1]
	v_pk_mul_f32 v[38:39], v[36:37], v[200:201] op_sel_hi:[0,1]
	v_pk_mul_f32 v[36:37], v[36:37], v[196:197] op_sel_hi:[0,1]
	v_pk_fma_f32 v[8:9], v[66:67], v[16:17], v[8:9]
	v_pk_fma_f32 v[6:7], v[68:69], v[14:15], v[6:7]
	v_pk_fma_f32 v[4:5], v[74:75], v[36:37], v[4:5]
	v_pk_fma_f32 v[2:3], v[72:73], v[38:39], v[2:3]
	global_store_dwordx4 v[12:13], v[6:9], off offset:512 nt
	global_store_dwordx4 v[12:13], v[2:5], off offset:528 nt
	v_mul_f32_e32 v12, v7, v7
	v_mul_f32_e32 v13, v9, v9
	v_fmac_f32_e32 v12, v6, v6
	v_fmac_f32_e32 v13, v8, v8
	v_add_f32_e32 v12, v12, v13
	v_mul_f32_e32 v13, v3, v3
	v_fmac_f32_e32 v13, v2, v2
	v_add_f32_e32 v12, v13, v12
	v_mul_f32_e32 v13, v5, v5
	v_fmac_f32_e32 v13, v4, v4
	v_add_f32_e32 v12, v13, v12
	v_add_f32_e32 v14, v119, v12
	v_pk_mul_f32 v[6:7], v[60:61], v[6:7]
	v_pk_mul_f32 v[12:13], v[62:63], v[4:5]
	v_pk_mul_f32 v[4:5], v[64:65], v[2:3]
	v_cvt_pk_bf16_f32 v2, v6, v7
	v_pk_mul_f32 v[8:9], v[58:59], v[8:9]
	v_lshlrev_b32_e32 v6, 16, v2
	v_cvt_pk_bf16_f32 v3, v8, v9
	v_cvt_pk_bf16_f32 v4, v4, v5
	v_cvt_pk_bf16_f32 v5, v12, v13
	global_store_dwordx4 v[10:11], v[2:5], off offset:256
	s_nop 1
	v_and_b32_e32 v2, 0xffff0000, v2
	v_max3_f32 v2, v40, |v6|, |v2|
	v_lshlrev_b32_e32 v6, 16, v3
	v_and_b32_e32 v3, 0xffff0000, v3
	v_max3_f32 v2, v2, |v6|, |v3|
	v_lshlrev_b32_e32 v3, 16, v4
	v_and_b32_e32 v4, 0xffff0000, v4
	v_max3_f32 v2, v2, |v3|, |v4|
	v_lshlrev_b32_e32 v3, 16, v5
	v_and_b32_e32 v4, 0xffff0000, v5
	v_max3_f32 v4, v2, |v3|, |v4|
	ds_bpermute_b32 v5, v212, v4
	ds_bpermute_b32 v2, v212, v14
	s_waitcnt lgkmcnt(1)
	v_max_f32_e32 v5, v5, v5
	s_waitcnt lgkmcnt(0)
	v_add_f32_e32 v2, v14, v2
	v_max_f32_e32 v4, v4, v5
	ds_bpermute_b32 v3, v213, v2
	ds_bpermute_b32 v5, v213, v4
	s_and_saveexec_b64 s[50:51], s[0:1]
	s_cbranch_execz .LBB0_903
	s_waitcnt lgkmcnt(0)
	v_max_f32_e32 v5, v5, v5
	v_max_f32_e32 v4, v4, v4
	v_add_f32_e32 v7, v2, v3
	v_lshlrev_b64 v[2:3], 7, v[34:35]
	v_max_f32_e32 v6, v4, v5
	v_lshl_add_u64 v[4:5], s[30:31], 0, v[2:3]
	s_lshl_b64 s[16:17], s[46:47], 2
	v_lshl_add_u64 v[2:3], s[34:35], 0, v[2:3]
	v_lshl_add_u64 v[4:5], v[4:5], 0, s[16:17]
	s_lshl_b32 s12, s93, 2
	v_lshl_add_u64 v[2:3], v[2:3], 0, s[16:17]
	v_lshl_add_u64 v[4:5], v[4:5], 0, s[12:13]
	v_lshl_add_u64 v[2:3], v[2:3], 0, s[12:13]
	global_store_dword v[4:5], v7, off
	global_store_dword v[2:3], v6, off
.LBB0_903:
	s_or_b64 exec, exec, s[50:51]
	v_or_b32_e32 v194, 48, v118
	v_ashrrev_i32_e32 v195, 31, v194
	v_add_u32_e32 v2, 0xffffe030, v118
	v_cmp_gt_i32_e32 vcc, s87, v194
	v_mov_b32_e32 v4, s59
	s_waitcnt lgkmcnt(0)
	v_mov_b32_e32 v5, s57
	v_cndmask_b32_e32 v3, 0, v195, vcc
	v_cndmask_b32_e32 v2, v2, v194, vcc
	v_cndmask_b32_e32 v5, v4, v5, vcc
	v_mov_b32_e32 v4, s58
	v_mov_b32_e32 v6, s56
	v_cndmask_b32_e32 v4, v4, v6, vcc
	v_lshlrev_b64 v[2:3], 13, v[2:3]
	v_lshl_add_u64 v[2:3], v[4:5], 0, v[2:3]
	v_lshl_add_u64 v[2:3], v[2:3], 0, v[108:109]
	global_load_dwordx4 v[34:37], v[2:3], off offset:16 nt
	global_load_dwordx4 v[38:41], v[2:3], off nt
	global_load_dwordx4 v[6:9], v[2:3], off offset:528 nt
	global_load_dwordx4 v[14:17], v[2:3], off offset:512 nt
	v_lshl_add_u64 v[4:5], v[210:211], 2, s[22:23]
	s_nop 1
	v_mov_b32_e32 v10, v242
	v_lshlrev_b64 v[2:3], 13, v[210:211]
	v_lshl_add_u64 v[2:3], s[20:21], 0, v[2:3]
	s_waitcnt vmcnt(12)
	v_pk_mul_f32 v[4:5], v[10:11], v[188:189] op_sel_hi:[0,1]
	v_pk_mul_f32 v[12:13], v[10:11], v[186:187] op_sel_hi:[0,1]
	v_pk_fma_f32 v[32:33], v[76:77], v[12:13], v[32:33]
	v_pk_fma_f32 v[30:31], v[78:79], v[4:5], v[30:31]
	v_pk_mul_f32 v[186:187], v[10:11], v[192:193] op_sel_hi:[0,1]
	v_lshl_add_u64 v[4:5], v[2:3], 0, v[108:109]
	v_mul_f32_e32 v2, v31, v31
	v_mul_f32_e32 v3, v33, v33
	v_pk_fma_f32 v[26:27], v[90:91], v[186:187], v[26:27]
	v_fmac_f32_e32 v2, v30, v30
	v_fmac_f32_e32 v3, v32, v32
	v_pk_mul_f32 v[188:189], v[10:11], v[190:191] op_sel_hi:[0,1]
	v_add_f32_e32 v2, v2, v3
	v_mul_f32_e32 v3, v27, v27
	v_pk_fma_f32 v[28:29], v[88:89], v[188:189], v[28:29]
	v_fmac_f32_e32 v3, v26, v26
	v_add_f32_e32 v2, v3, v2
	v_mul_f32_e32 v3, v29, v29
	v_fmac_f32_e32 v3, v28, v28
	v_pk_mul_f32 v[12:13], v[82:83], v[30:31]
	global_store_dwordx4 v[4:5], v[30:33], off nt
	global_store_dwordx4 v[4:5], v[26:29], off offset:16 nt
	v_add_f32_e32 v119, v3, v2
	v_pk_mul_f32 v[2:3], v[80:81], v[32:33]
	v_pk_mul_f32 v[30:31], v[84:85], v[28:29]
	v_pk_mul_f32 v[28:29], v[86:87], v[26:27]
	v_cvt_pk_bf16_f32 v26, v12, v13
	v_cvt_pk_bf16_f32 v27, v2, v3
	v_lshlrev_b64 v[2:3], 12, v[210:211]
	v_lshlrev_b32_e32 v11, 16, v26
	v_and_b32_e32 v12, 0xffff0000, v26
	v_max3_f32 v11, |v11|, 0, |v12|
	v_lshlrev_b32_e32 v12, 16, v27
	v_and_b32_e32 v13, 0xffff0000, v27
	v_cvt_pk_bf16_f32 v28, v28, v29
	v_lshl_add_u64 v[2:3], s[26:27], 0, v[2:3]
	v_max3_f32 v11, v11, |v12|, |v13|
	v_lshlrev_b32_e32 v12, 16, v28
	v_and_b32_e32 v13, 0xffff0000, v28
	v_cvt_pk_bf16_f32 v29, v30, v31
	v_lshl_add_u64 v[2:3], v[70:71], 1, v[2:3]
	v_max3_f32 v11, v11, |v12|, |v13|
	v_lshlrev_b32_e32 v12, 16, v29
	v_and_b32_e32 v13, 0xffff0000, v29
	global_store_dwordx4 v[2:3], v[26:29], off
	v_max3_f32 v32, v11, |v12|, |v13|
	v_pk_mul_f32 v[12:13], v[10:11], v[178:179] op_sel_hi:[0,1]
	v_pk_mul_f32 v[26:27], v[10:11], v[182:183] op_sel_hi:[0,1]
	v_pk_mul_f32 v[28:29], v[10:11], v[184:185] op_sel_hi:[0,1]
	v_pk_mul_f32 v[30:31], v[10:11], v[180:181] op_sel_hi:[0,1]
	v_pk_fma_f32 v[12:13], v[66:67], v[12:13], v[24:25]
	v_pk_fma_f32 v[10:11], v[68:69], v[26:27], v[22:23]
	v_pk_fma_f32 v[20:21], v[74:75], v[30:31], v[20:21]
	v_pk_fma_f32 v[18:19], v[72:73], v[28:29], v[18:19]
	global_store_dwordx4 v[4:5], v[10:13], off offset:512 nt
	global_store_dwordx4 v[4:5], v[18:21], off offset:528 nt
	v_mul_f32_e32 v4, v11, v11
	v_mul_f32_e32 v5, v13, v13
	v_fmac_f32_e32 v4, v10, v10
	v_fmac_f32_e32 v5, v12, v12
	v_add_f32_e32 v4, v4, v5
	v_mul_f32_e32 v5, v19, v19
	v_fmac_f32_e32 v5, v18, v18
	v_add_f32_e32 v4, v5, v4
	v_mul_f32_e32 v5, v21, v21
	v_fmac_f32_e32 v5, v20, v20
	v_add_f32_e32 v4, v5, v4
	v_add_f32_e32 v22, v119, v4
	v_pk_mul_f32 v[4:5], v[58:59], v[12:13]
	v_pk_mul_f32 v[10:11], v[60:61], v[10:11]
	v_pk_mul_f32 v[12:13], v[64:65], v[18:19]
	v_pk_mul_f32 v[20:21], v[62:63], v[20:21]
	v_cvt_pk_bf16_f32 v10, v10, v11
	v_cvt_pk_bf16_f32 v11, v4, v5
	v_cvt_pk_bf16_f32 v12, v12, v13
	s_nop 0
	v_cvt_pk_bf16_f32 v13, v20, v21
	global_store_dwordx4 v[2:3], v[10:13], off offset:256
	v_lshlrev_b32_e32 v2, 16, v10
	v_and_b32_e32 v3, 0xffff0000, v10
	v_max3_f32 v2, v32, |v2|, |v3|
	v_lshlrev_b32_e32 v3, 16, v11
	v_and_b32_e32 v4, 0xffff0000, v11
	v_max3_f32 v2, v2, |v3|, |v4|
	v_lshlrev_b32_e32 v3, 16, v12
	v_and_b32_e32 v4, 0xffff0000, v12
	v_max3_f32 v2, v2, |v3|, |v4|
	v_lshlrev_b32_e32 v3, 16, v13
	v_and_b32_e32 v4, 0xffff0000, v13
	v_max3_f32 v4, v2, |v3|, |v4|
	ds_bpermute_b32 v5, v212, v4
	ds_bpermute_b32 v2, v212, v22
	s_waitcnt lgkmcnt(1)
	v_max_f32_e32 v5, v5, v5
	s_waitcnt lgkmcnt(0)
	v_add_f32_e32 v2, v22, v2
	v_max_f32_e32 v4, v4, v5
	ds_bpermute_b32 v3, v213, v2
	ds_bpermute_b32 v5, v213, v4
	s_and_saveexec_b64 s[50:51], s[0:1]
	s_cbranch_execz .LBB0_905
	s_waitcnt lgkmcnt(0)
	v_max_f32_e32 v5, v5, v5
	v_max_f32_e32 v4, v4, v4
	v_add_f32_e32 v11, v2, v3
	v_lshlrev_b64 v[2:3], 7, v[210:211]
	v_max_f32_e32 v10, v4, v5
	v_lshl_add_u64 v[4:5], s[30:31], 0, v[2:3]
	s_lshl_b64 s[16:17], s[46:47], 2
	v_lshl_add_u64 v[2:3], s[34:35], 0, v[2:3]
	v_lshl_add_u64 v[4:5], v[4:5], 0, s[16:17]
	s_lshl_b32 s12, s93, 2
	v_lshl_add_u64 v[2:3], v[2:3], 0, s[16:17]
	v_lshl_add_u64 v[4:5], v[4:5], 0, s[12:13]
	v_lshl_add_u64 v[2:3], v[2:3], 0, s[12:13]
	global_store_dword v[4:5], v11, off
	global_store_dword v[2:3], v10, off
.LBB0_905:
	s_or_b64 exec, exec, s[50:51]
	v_add_u32_e32 v178, 0x80, v118
	s_movk_i32 s12, 0x1f80
	v_ashrrev_i32_e32 v179, 31, v178
	v_add_u32_e32 v2, 0xffffe080, v118
	v_cmp_gt_i32_e32 vcc, s12, v118
	v_mov_b32_e32 v4, s59
	s_waitcnt lgkmcnt(0)
	v_mov_b32_e32 v5, s57
	v_cndmask_b32_e32 v3, 0, v179, vcc
	v_cndmask_b32_e32 v2, v2, v178, vcc
	v_cndmask_b32_e32 v5, v4, v5, vcc
	v_mov_b32_e32 v4, s58
	v_mov_b32_e32 v10, s56
	v_cndmask_b32_e32 v4, v4, v10, vcc
	v_lshlrev_b64 v[2:3], 13, v[2:3]
	v_lshl_add_u64 v[2:3], v[4:5], 0, v[2:3]
	v_lshl_add_u64 v[10:11], v[2:3], 0, v[108:109]
	global_load_dwordx4 v[18:21], v[10:11], off offset:16 nt
	global_load_dwordx4 v[22:25], v[10:11], off nt
	global_load_dwordx4 v[2:5], v[10:11], off offset:528 nt
	s_nop 0
	global_load_dwordx4 v[10:13], v[10:11], off offset:512 nt
	v_lshl_add_u64 v[28:29], v[194:195], 2, s[22:23]
	s_nop 1
	v_mov_b32_e32 v30, v243
	v_lshlrev_b64 v[26:27], 13, v[194:195]
	v_lshl_add_u64 v[26:27], s[20:21], 0, v[26:27]
	s_waitcnt vmcnt(12)
	v_pk_mul_f32 v[28:29], v[30:31], v[170:171] op_sel_hi:[0,1]
	v_pk_mul_f32 v[32:33], v[30:31], v[168:169] op_sel_hi:[0,1]
	v_pk_fma_f32 v[40:41], v[76:77], v[32:33], v[40:41]
	v_pk_fma_f32 v[38:39], v[78:79], v[28:29], v[38:39]
	v_pk_mul_f32 v[168:169], v[30:31], v[174:175] op_sel_hi:[0,1]
	v_lshl_add_u64 v[28:29], v[26:27], 0, v[108:109]
	v_mul_f32_e32 v26, v39, v39
	v_mul_f32_e32 v27, v41, v41
	v_pk_fma_f32 v[34:35], v[90:91], v[168:169], v[34:35]
	v_fmac_f32_e32 v26, v38, v38
	v_fmac_f32_e32 v27, v40, v40
	v_pk_mul_f32 v[170:171], v[30:31], v[172:173] op_sel_hi:[0,1]
	v_add_f32_e32 v26, v26, v27
	v_mul_f32_e32 v27, v35, v35
	v_pk_fma_f32 v[36:37], v[88:89], v[170:171], v[36:37]
	v_fmac_f32_e32 v27, v34, v34
	v_add_f32_e32 v26, v27, v26
	v_mul_f32_e32 v27, v37, v37
	v_fmac_f32_e32 v27, v36, v36
	v_add_f32_e32 v119, v27, v26
	v_pk_mul_f32 v[26:27], v[80:81], v[40:41]
	v_pk_mul_f32 v[32:33], v[82:83], v[38:39]
	global_store_dwordx4 v[28:29], v[38:41], off nt
	global_store_dwordx4 v[28:29], v[34:37], off offset:16 nt
	v_cvt_pk_bf16_f32 v32, v32, v33
	v_cvt_pk_bf16_f32 v33, v26, v27
	v_lshlrev_b64 v[26:27], 12, v[194:195]
	v_lshl_add_u64 v[26:27], s[26:27], 0, v[26:27]
	v_pk_mul_f32 v[34:35], v[86:87], v[34:35]
	v_lshl_add_u64 v[26:27], v[70:71], 1, v[26:27]
	v_pk_mul_f32 v[36:37], v[84:85], v[36:37]
	v_cvt_pk_bf16_f32 v34, v34, v35
	v_lshlrev_b32_e32 v31, 16, v32
	v_cvt_pk_bf16_f32 v35, v36, v37
	global_store_dwordx4 v[26:27], v[32:35], off
	s_nop 1
	v_and_b32_e32 v32, 0xffff0000, v32
	v_max3_f32 v31, |v31|, 0, |v32|
	v_lshlrev_b32_e32 v32, 16, v33
	v_and_b32_e32 v33, 0xffff0000, v33
	v_max3_f32 v31, v31, |v32|, |v33|
	v_lshlrev_b32_e32 v32, 16, v34
	v_and_b32_e32 v33, 0xffff0000, v34
	v_max3_f32 v31, v31, |v32|, |v33|
	v_lshlrev_b32_e32 v32, 16, v35
	v_and_b32_e32 v33, 0xffff0000, v35
	v_max3_f32 v38, v31, |v32|, |v33|
	v_pk_mul_f32 v[32:33], v[30:31], v[164:165] op_sel_hi:[0,1]
	v_pk_mul_f32 v[34:35], v[30:31], v[160:161] op_sel_hi:[0,1]
	v_pk_mul_f32 v[36:37], v[30:31], v[166:167] op_sel_hi:[0,1]
	v_pk_mul_f32 v[30:31], v[30:31], v[162:163] op_sel_hi:[0,1]
	v_pk_fma_f32 v[16:17], v[66:67], v[34:35], v[16:17]
	v_pk_fma_f32 v[14:15], v[68:69], v[32:33], v[14:15]
	v_pk_fma_f32 v[8:9], v[74:75], v[30:31], v[8:9]
	v_pk_fma_f32 v[6:7], v[72:73], v[36:37], v[6:7]
	global_store_dwordx4 v[28:29], v[14:17], off offset:512 nt
	global_store_dwordx4 v[28:29], v[6:9], off offset:528 nt
	v_mul_f32_e32 v28, v15, v15
	v_mul_f32_e32 v29, v17, v17
	v_fmac_f32_e32 v28, v14, v14
	v_fmac_f32_e32 v29, v16, v16
	v_add_f32_e32 v28, v28, v29
	v_mul_f32_e32 v29, v7, v7
	v_fmac_f32_e32 v29, v6, v6
	v_add_f32_e32 v28, v29, v28
	v_mul_f32_e32 v29, v9, v9
	v_fmac_f32_e32 v29, v8, v8
	v_add_f32_e32 v28, v29, v28
	v_add_f32_e32 v30, v119, v28
	v_pk_mul_f32 v[14:15], v[60:61], v[14:15]
	v_pk_mul_f32 v[28:29], v[62:63], v[8:9]
	v_pk_mul_f32 v[8:9], v[64:65], v[6:7]
	v_cvt_pk_bf16_f32 v6, v14, v15
	v_pk_mul_f32 v[16:17], v[58:59], v[16:17]
	v_lshlrev_b32_e32 v14, 16, v6
	v_cvt_pk_bf16_f32 v7, v16, v17
	v_cvt_pk_bf16_f32 v8, v8, v9
	v_cvt_pk_bf16_f32 v9, v28, v29
	global_store_dwordx4 v[26:27], v[6:9], off offset:256
	s_nop 1
	v_and_b32_e32 v6, 0xffff0000, v6
	v_max3_f32 v6, v38, |v14|, |v6|
	v_lshlrev_b32_e32 v14, 16, v7
	v_and_b32_e32 v7, 0xffff0000, v7
	v_max3_f32 v6, v6, |v14|, |v7|
	v_lshlrev_b32_e32 v7, 16, v8
	v_and_b32_e32 v8, 0xffff0000, v8
	v_max3_f32 v6, v6, |v7|, |v8|
	v_lshlrev_b32_e32 v7, 16, v9
	v_and_b32_e32 v8, 0xffff0000, v9
	v_max3_f32 v8, v6, |v7|, |v8|
	ds_bpermute_b32 v9, v212, v8
	ds_bpermute_b32 v6, v212, v30
	s_waitcnt lgkmcnt(1)
	v_max_f32_e32 v9, v9, v9
	s_waitcnt lgkmcnt(0)
	v_add_f32_e32 v6, v30, v6
	v_max_f32_e32 v8, v8, v9
	ds_bpermute_b32 v7, v213, v6
	ds_bpermute_b32 v9, v213, v8
	s_and_saveexec_b64 s[50:51], s[0:1]
	s_cbranch_execz .LBB0_907
	s_waitcnt lgkmcnt(0)
	v_max_f32_e32 v9, v9, v9
	v_max_f32_e32 v8, v8, v8
	v_add_f32_e32 v15, v6, v7
	v_lshlrev_b64 v[6:7], 7, v[194:195]
	v_max_f32_e32 v14, v8, v9
	v_lshl_add_u64 v[8:9], s[30:31], 0, v[6:7]
	s_lshl_b64 s[16:17], s[46:47], 2
	v_lshl_add_u64 v[6:7], s[34:35], 0, v[6:7]
	v_lshl_add_u64 v[8:9], v[8:9], 0, s[16:17]
	s_lshl_b32 s12, s93, 2
	v_lshl_add_u64 v[6:7], v[6:7], 0, s[16:17]
	v_lshl_add_u64 v[8:9], v[8:9], 0, s[12:13]
	v_lshl_add_u64 v[6:7], v[6:7], 0, s[12:13]
	global_store_dword v[8:9], v15, off
	global_store_dword v[6:7], v14, off
.LBB0_907:
	s_or_b64 exec, exec, s[50:51]
	v_or_b32_e32 v36, 16, v178
	v_ashrrev_i32_e32 v37, 31, v36
	v_add_u32_e32 v6, 0xffffe090, v118
	v_cmp_gt_i32_e32 vcc, s87, v36
	v_mov_b32_e32 v8, s59
	s_waitcnt lgkmcnt(0)
	v_mov_b32_e32 v9, s57
	v_cndmask_b32_e32 v7, 0, v37, vcc
	v_cndmask_b32_e32 v6, v6, v36, vcc
	v_cndmask_b32_e32 v9, v8, v9, vcc
	v_mov_b32_e32 v8, s58
	v_mov_b32_e32 v14, s56
	v_cndmask_b32_e32 v8, v8, v14, vcc
	v_lshlrev_b64 v[6:7], 13, v[6:7]
	v_lshl_add_u64 v[6:7], v[8:9], 0, v[6:7]
	v_lshl_add_u64 v[14:15], v[6:7], 0, v[108:109]
	global_load_dwordx4 v[26:29], v[14:15], off offset:16 nt
	global_load_dwordx4 v[30:33], v[14:15], off nt
	global_load_dwordx4 v[6:9], v[14:15], off offset:528 nt
	s_nop 0
	global_load_dwordx4 v[14:17], v[14:15], off offset:512 nt
	v_lshlrev_b64 v[34:35], 13, v[178:179]
	v_lshl_add_u64 v[160:161], s[20:21], 0, v[34:35]
	s_nop 1
	v_mov_b32_e32 v34, v244
	s_waitcnt vmcnt(12)
	v_pk_mul_f32 v[38:39], v[34:35], v[154:155] op_sel_hi:[0,1]
	v_pk_mul_f32 v[40:41], v[34:35], v[152:153] op_sel_hi:[0,1]
	v_pk_mul_f32 v[152:153], v[34:35], v[158:159] op_sel_hi:[0,1]
	v_pk_fma_f32 v[24:25], v[76:77], v[40:41], v[24:25]
	v_pk_fma_f32 v[22:23], v[78:79], v[38:39], v[22:23]
	v_pk_fma_f32 v[38:39], v[90:91], v[152:153], v[18:19]
	v_mul_f32_e32 v18, v23, v23
	v_mul_f32_e32 v19, v25, v25
	v_fmac_f32_e32 v18, v22, v22
	v_fmac_f32_e32 v19, v24, v24
	v_pk_mul_f32 v[154:155], v[34:35], v[156:157] op_sel_hi:[0,1]
	v_add_f32_e32 v18, v18, v19
	v_mul_f32_e32 v19, v39, v39
	v_pk_fma_f32 v[40:41], v[88:89], v[154:155], v[20:21]
	v_fmac_f32_e32 v19, v38, v38
	v_add_f32_e32 v18, v19, v18
	v_mul_f32_e32 v19, v41, v41
	v_lshl_add_u64 v[20:21], v[160:161], 0, v[108:109]
	v_fmac_f32_e32 v19, v40, v40
	global_store_dwordx4 v[20:21], v[22:25], off nt
	global_store_dwordx4 v[20:21], v[38:41], off offset:16 nt
	v_add_f32_e32 v119, v19, v18
	v_pk_mul_f32 v[18:19], v[80:81], v[24:25]
	v_pk_mul_f32 v[22:23], v[82:83], v[22:23]
	v_pk_mul_f32 v[24:25], v[86:87], v[38:39]
	v_cvt_pk_bf16_f32 v22, v22, v23
	v_cvt_pk_bf16_f32 v23, v18, v19
	v_lshlrev_b64 v[18:19], 12, v[178:179]
	v_lshl_add_u64 v[18:19], s[26:27], 0, v[18:19]
	v_lshl_add_u64 v[18:19], v[70:71], 1, v[18:19]
	v_pk_mul_f32 v[40:41], v[84:85], v[40:41]
	v_cvt_pk_bf16_f32 v24, v24, v25
	v_lshlrev_b32_e32 v35, 16, v22
	v_cvt_pk_bf16_f32 v25, v40, v41
	global_store_dwordx4 v[18:19], v[22:25], off
	s_nop 1
	v_and_b32_e32 v22, 0xffff0000, v22
	v_max3_f32 v22, |v35|, 0, |v22|
	v_lshlrev_b32_e32 v35, 16, v23
	v_and_b32_e32 v23, 0xffff0000, v23
	v_max3_f32 v22, v22, |v35|, |v23|
	v_lshlrev_b32_e32 v23, 16, v24
	v_and_b32_e32 v24, 0xffff0000, v24
	v_max3_f32 v22, v22, |v23|, |v24|
	v_lshlrev_b32_e32 v23, 16, v25
	v_and_b32_e32 v24, 0xffff0000, v25
	v_max3_f32 v40, v22, |v23|, |v24|
	v_pk_mul_f32 v[22:23], v[34:35], v[148:149] op_sel_hi:[0,1]
	v_pk_mul_f32 v[24:25], v[34:35], v[128:129] op_sel_hi:[0,1]
	v_pk_mul_f32 v[38:39], v[34:35], v[150:151] op_sel_hi:[0,1]
	v_pk_mul_f32 v[34:35], v[34:35], v[146:147] op_sel_hi:[0,1]
	v_pk_fma_f32 v[12:13], v[66:67], v[24:25], v[12:13]
	v_pk_fma_f32 v[10:11], v[68:69], v[22:23], v[10:11]
	v_pk_fma_f32 v[4:5], v[74:75], v[34:35], v[4:5]
	v_pk_fma_f32 v[2:3], v[72:73], v[38:39], v[2:3]
	global_store_dwordx4 v[20:21], v[10:13], off offset:512 nt
	global_store_dwordx4 v[20:21], v[2:5], off offset:528 nt
	v_mul_f32_e32 v20, v11, v11
	v_mul_f32_e32 v21, v13, v13
	v_fmac_f32_e32 v20, v10, v10
	v_fmac_f32_e32 v21, v12, v12
	v_add_f32_e32 v20, v20, v21
	v_mul_f32_e32 v21, v3, v3
	v_fmac_f32_e32 v21, v2, v2
	v_add_f32_e32 v20, v21, v20
	v_mul_f32_e32 v21, v5, v5
	v_fmac_f32_e32 v21, v4, v4
	v_add_f32_e32 v20, v21, v20
	v_add_f32_e32 v22, v119, v20
	v_pk_mul_f32 v[10:11], v[60:61], v[10:11]
	v_pk_mul_f32 v[20:21], v[62:63], v[4:5]
	v_pk_mul_f32 v[4:5], v[64:65], v[2:3]
	v_cvt_pk_bf16_f32 v2, v10, v11
	v_pk_mul_f32 v[12:13], v[58:59], v[12:13]
	v_lshlrev_b32_e32 v10, 16, v2
	v_cvt_pk_bf16_f32 v3, v12, v13
	v_cvt_pk_bf16_f32 v4, v4, v5
	v_cvt_pk_bf16_f32 v5, v20, v21
	global_store_dwordx4 v[18:19], v[2:5], off offset:256
	s_nop 1
	v_and_b32_e32 v2, 0xffff0000, v2
	v_max3_f32 v2, v40, |v10|, |v2|
	v_lshlrev_b32_e32 v10, 16, v3
	v_and_b32_e32 v3, 0xffff0000, v3
	v_max3_f32 v2, v2, |v10|, |v3|
	v_lshlrev_b32_e32 v3, 16, v4
	v_and_b32_e32 v4, 0xffff0000, v4
	v_max3_f32 v2, v2, |v3|, |v4|
	v_lshlrev_b32_e32 v3, 16, v5
	v_and_b32_e32 v4, 0xffff0000, v5
	v_max3_f32 v4, v2, |v3|, |v4|
	ds_bpermute_b32 v5, v212, v4
	ds_bpermute_b32 v2, v212, v22
	s_waitcnt lgkmcnt(1)
	v_max_f32_e32 v5, v5, v5
	s_waitcnt lgkmcnt(0)
	v_add_f32_e32 v2, v22, v2
	v_max_f32_e32 v4, v4, v5
	ds_bpermute_b32 v3, v213, v2
	ds_bpermute_b32 v5, v213, v4
	s_and_saveexec_b64 s[50:51], s[0:1]
	s_cbranch_execz .LBB0_909
	s_waitcnt lgkmcnt(0)
	v_max_f32_e32 v5, v5, v5
	v_max_f32_e32 v4, v4, v4
	v_add_f32_e32 v11, v2, v3
	v_lshlrev_b64 v[2:3], 7, v[178:179]
	v_max_f32_e32 v10, v4, v5
	v_lshl_add_u64 v[4:5], s[30:31], 0, v[2:3]
	s_lshl_b64 s[16:17], s[46:47], 2
	v_lshl_add_u64 v[2:3], s[34:35], 0, v[2:3]
	v_lshl_add_u64 v[4:5], v[4:5], 0, s[16:17]
	s_lshl_b32 s12, s93, 2
	v_lshl_add_u64 v[2:3], v[2:3], 0, s[16:17]
	v_lshl_add_u64 v[4:5], v[4:5], 0, s[12:13]
	v_lshl_add_u64 v[2:3], v[2:3], 0, s[12:13]
	global_store_dword v[4:5], v11, off
	global_store_dword v[2:3], v10, off
.LBB0_909:
	s_or_b64 exec, exec, s[50:51]
	v_or_b32_e32 v34, 32, v178
	v_ashrrev_i32_e32 v35, 31, v34
	v_add_u32_e32 v2, 0xffffe0a0, v118
	v_cmp_gt_i32_e32 vcc, s87, v34
	v_mov_b32_e32 v4, s59
	s_waitcnt lgkmcnt(0)
	v_mov_b32_e32 v5, s57
	v_cndmask_b32_e32 v3, 0, v35, vcc
	v_cndmask_b32_e32 v2, v2, v34, vcc
	v_cndmask_b32_e32 v5, v4, v5, vcc
	v_mov_b32_e32 v4, s58
	v_mov_b32_e32 v10, s56
	v_cndmask_b32_e32 v4, v4, v10, vcc
	v_lshlrev_b64 v[2:3], 13, v[2:3]
	v_lshl_add_u64 v[2:3], v[4:5], 0, v[2:3]
	v_lshl_add_u64 v[10:11], v[2:3], 0, v[108:109]
	global_load_dwordx4 v[18:21], v[10:11], off offset:16 nt
	global_load_dwordx4 v[22:25], v[10:11], off nt
	global_load_dwordx4 v[2:5], v[10:11], off offset:528 nt
	s_nop 0
	global_load_dwordx4 v[10:13], v[10:11], off offset:512 nt
	v_lshlrev_b64 v[38:39], 13, v[36:37]
	v_lshl_add_u64 v[40:41], s[20:21], 0, v[38:39]
	v_lshl_add_u64 v[38:39], v[36:37], 2, s[22:23]
	s_nop 1
	v_mov_b32_e32 v38, v245
	s_waitcnt vmcnt(12)
	v_pk_mul_f32 v[122:123], v[38:39], v[122:123] op_sel_hi:[0,1]
	v_pk_mul_f32 v[120:121], v[38:39], v[120:121] op_sel_hi:[0,1]
	v_pk_mul_f32 v[126:127], v[38:39], v[126:127] op_sel_hi:[0,1]
	v_pk_fma_f32 v[32:33], v[76:77], v[120:121], v[32:33]
	v_pk_fma_f32 v[30:31], v[78:79], v[122:123], v[30:31]
	v_pk_fma_f32 v[120:121], v[90:91], v[126:127], v[26:27]
	v_mul_f32_e32 v26, v31, v31
	v_mul_f32_e32 v27, v33, v33
	v_fmac_f32_e32 v26, v30, v30
	v_fmac_f32_e32 v27, v32, v32
	v_pk_mul_f32 v[124:125], v[38:39], v[124:125] op_sel_hi:[0,1]
	v_add_f32_e32 v26, v26, v27
	v_mul_f32_e32 v27, v121, v121
	v_pk_fma_f32 v[122:123], v[88:89], v[124:125], v[28:29]
	v_fmac_f32_e32 v27, v120, v120
	v_add_f32_e32 v26, v27, v26
	v_mul_f32_e32 v27, v123, v123
	v_lshl_add_u64 v[28:29], v[40:41], 0, v[108:109]
	v_fmac_f32_e32 v27, v122, v122
	global_store_dwordx4 v[28:29], v[30:33], off nt
	global_store_dwordx4 v[28:29], v[120:123], off offset:16 nt
	v_add_f32_e32 v119, v27, v26
	v_pk_mul_f32 v[26:27], v[80:81], v[32:33]
	v_pk_mul_f32 v[30:31], v[82:83], v[30:31]
	v_pk_mul_f32 v[32:33], v[86:87], v[120:121]
	v_cvt_pk_bf16_f32 v30, v30, v31
	v_cvt_pk_bf16_f32 v31, v26, v27
	v_lshlrev_b64 v[26:27], 12, v[36:37]
	v_lshl_add_u64 v[26:27], s[26:27], 0, v[26:27]
	v_lshl_add_u64 v[26:27], v[70:71], 1, v[26:27]
	v_pk_mul_f32 v[40:41], v[84:85], v[122:123]
	v_cvt_pk_bf16_f32 v32, v32, v33
	v_lshlrev_b32_e32 v39, 16, v30
	v_cvt_pk_bf16_f32 v33, v40, v41
	global_store_dwordx4 v[26:27], v[30:33], off
	s_nop 1
	v_and_b32_e32 v30, 0xffff0000, v30
	v_max3_f32 v30, |v39|, 0, |v30|
	v_lshlrev_b32_e32 v39, 16, v31
	v_and_b32_e32 v31, 0xffff0000, v31
	v_max3_f32 v30, v30, |v39|, |v31|
	v_lshlrev_b32_e32 v31, 16, v32
	v_and_b32_e32 v32, 0xffff0000, v32
	v_max3_f32 v30, v30, |v31|, |v32|
	v_lshlrev_b32_e32 v31, 16, v33
	v_and_b32_e32 v32, 0xffff0000, v33
	v_max3_f32 v120, v30, |v31|, |v32|
	v_pk_mul_f32 v[30:31], v[38:39], v[114:115] op_sel_hi:[0,1]
	v_pk_mul_f32 v[32:33], v[38:39], v[110:111] op_sel_hi:[0,1]
	v_pk_mul_f32 v[40:41], v[38:39], v[116:117] op_sel_hi:[0,1]
	v_pk_mul_f32 v[38:39], v[38:39], v[112:113] op_sel_hi:[0,1]
	v_pk_fma_f32 v[16:17], v[66:67], v[32:33], v[16:17]
	v_pk_fma_f32 v[14:15], v[68:69], v[30:31], v[14:15]
	v_pk_fma_f32 v[8:9], v[74:75], v[38:39], v[8:9]
	v_pk_fma_f32 v[6:7], v[72:73], v[40:41], v[6:7]
	global_store_dwordx4 v[28:29], v[14:17], off offset:512 nt
	global_store_dwordx4 v[28:29], v[6:9], off offset:528 nt
	v_mul_f32_e32 v28, v15, v15
	v_mul_f32_e32 v29, v17, v17
	v_fmac_f32_e32 v28, v14, v14
	v_fmac_f32_e32 v29, v16, v16
	v_add_f32_e32 v28, v28, v29
	v_mul_f32_e32 v29, v7, v7
	v_fmac_f32_e32 v29, v6, v6
	v_add_f32_e32 v28, v29, v28
	v_mul_f32_e32 v29, v9, v9
	v_fmac_f32_e32 v29, v8, v8
	v_add_f32_e32 v28, v29, v28
	v_add_f32_e32 v30, v119, v28
	v_pk_mul_f32 v[14:15], v[60:61], v[14:15]
	v_pk_mul_f32 v[28:29], v[62:63], v[8:9]
	v_pk_mul_f32 v[8:9], v[64:65], v[6:7]
	v_cvt_pk_bf16_f32 v6, v14, v15
	v_pk_mul_f32 v[16:17], v[58:59], v[16:17]
	v_lshlrev_b32_e32 v14, 16, v6
	v_cvt_pk_bf16_f32 v7, v16, v17
	v_cvt_pk_bf16_f32 v8, v8, v9
	v_cvt_pk_bf16_f32 v9, v28, v29
	global_store_dwordx4 v[26:27], v[6:9], off offset:256
	s_nop 1
	v_and_b32_e32 v6, 0xffff0000, v6
	v_max3_f32 v6, v120, |v14|, |v6|
	v_lshlrev_b32_e32 v14, 16, v7
	v_and_b32_e32 v7, 0xffff0000, v7
	v_max3_f32 v6, v6, |v14|, |v7|
	v_lshlrev_b32_e32 v7, 16, v8
	v_and_b32_e32 v8, 0xffff0000, v8
	v_max3_f32 v6, v6, |v7|, |v8|
	v_lshlrev_b32_e32 v7, 16, v9
	v_and_b32_e32 v8, 0xffff0000, v9
	v_max3_f32 v8, v6, |v7|, |v8|
	ds_bpermute_b32 v9, v212, v8
	ds_bpermute_b32 v6, v212, v30
	s_waitcnt lgkmcnt(1)
	v_max_f32_e32 v9, v9, v9
	s_waitcnt lgkmcnt(0)
	v_add_f32_e32 v6, v30, v6
	v_max_f32_e32 v8, v8, v9
	ds_bpermute_b32 v7, v213, v6
	ds_bpermute_b32 v9, v213, v8
	s_and_saveexec_b64 s[50:51], s[0:1]
	s_cbranch_execz .LBB0_911
	s_waitcnt lgkmcnt(0)
	v_max_f32_e32 v9, v9, v9
	v_max_f32_e32 v8, v8, v8
	v_add_f32_e32 v15, v6, v7
	v_lshlrev_b64 v[6:7], 7, v[36:37]
	v_max_f32_e32 v14, v8, v9
	v_lshl_add_u64 v[8:9], s[30:31], 0, v[6:7]
	s_lshl_b64 s[16:17], s[46:47], 2
	v_lshl_add_u64 v[6:7], s[34:35], 0, v[6:7]
	v_lshl_add_u64 v[8:9], v[8:9], 0, s[16:17]
	s_lshl_b32 s12, s93, 2
	v_lshl_add_u64 v[6:7], v[6:7], 0, s[16:17]
	v_lshl_add_u64 v[8:9], v[8:9], 0, s[12:13]
	v_lshl_add_u64 v[6:7], v[6:7], 0, s[12:13]
	global_store_dword v[8:9], v15, off
	global_store_dword v[6:7], v14, off
.LBB0_911:
	s_or_b64 exec, exec, s[50:51]
	v_or_b32_e32 v36, 48, v178
	v_ashrrev_i32_e32 v37, 31, v36
	v_add_u32_e32 v6, 0xffffe0b0, v118
	v_cmp_gt_i32_e32 vcc, s87, v36
	v_mov_b32_e32 v8, s59
	s_waitcnt lgkmcnt(0)
	v_mov_b32_e32 v9, s57
	v_cndmask_b32_e32 v7, 0, v37, vcc
	v_cndmask_b32_e32 v6, v6, v36, vcc
	v_cndmask_b32_e32 v9, v8, v9, vcc
	v_mov_b32_e32 v8, s58
	v_mov_b32_e32 v14, s56
	v_cndmask_b32_e32 v8, v8, v14, vcc
	v_lshlrev_b64 v[6:7], 13, v[6:7]
	v_lshl_add_u64 v[6:7], v[8:9], 0, v[6:7]
	v_lshl_add_u64 v[14:15], v[6:7], 0, v[108:109]
	global_load_dwordx4 v[26:29], v[14:15], off offset:16 nt
	global_load_dwordx4 v[30:33], v[14:15], off nt
	global_load_dwordx4 v[6:9], v[14:15], off offset:528 nt
	s_nop 0
	global_load_dwordx4 v[14:17], v[14:15], off offset:512 nt
	v_lshlrev_b64 v[38:39], 13, v[34:35]
	v_lshl_add_u64 v[40:41], s[20:21], 0, v[38:39]
	v_lshl_add_u64 v[38:39], v[34:35], 2, s[22:23]
	s_nop 1
	v_mov_b32_e32 v38, v246
	s_waitcnt vmcnt(12)
	v_pk_mul_f32 v[102:103], v[38:39], v[102:103] op_sel_hi:[0,1]
	v_pk_mul_f32 v[100:101], v[38:39], v[100:101] op_sel_hi:[0,1]
	v_pk_mul_f32 v[106:107], v[38:39], v[106:107] op_sel_hi:[0,1]
	v_pk_fma_f32 v[24:25], v[76:77], v[100:101], v[24:25]
	v_pk_fma_f32 v[22:23], v[78:79], v[102:103], v[22:23]
	v_pk_fma_f32 v[100:101], v[90:91], v[106:107], v[18:19]
	v_mul_f32_e32 v18, v23, v23
	v_mul_f32_e32 v19, v25, v25
	v_fmac_f32_e32 v18, v22, v22
	v_fmac_f32_e32 v19, v24, v24
	v_pk_mul_f32 v[104:105], v[38:39], v[104:105] op_sel_hi:[0,1]
	v_add_f32_e32 v18, v18, v19
	v_mul_f32_e32 v19, v101, v101
	v_pk_fma_f32 v[102:103], v[88:89], v[104:105], v[20:21]
	v_fmac_f32_e32 v19, v100, v100
	v_add_f32_e32 v18, v19, v18
	v_mul_f32_e32 v19, v103, v103
	v_lshl_add_u64 v[20:21], v[40:41], 0, v[108:109]
	v_fmac_f32_e32 v19, v102, v102
	global_store_dwordx4 v[20:21], v[22:25], off nt
	global_store_dwordx4 v[20:21], v[100:103], off offset:16 nt
	v_add_f32_e32 v104, v19, v18
	v_pk_mul_f32 v[18:19], v[80:81], v[24:25]
	v_pk_mul_f32 v[22:23], v[82:83], v[22:23]
	v_pk_mul_f32 v[24:25], v[86:87], v[100:101]
	v_cvt_pk_bf16_f32 v22, v22, v23
	v_cvt_pk_bf16_f32 v23, v18, v19
	v_lshlrev_b64 v[18:19], 12, v[34:35]
	v_lshl_add_u64 v[18:19], s[26:27], 0, v[18:19]
	v_lshl_add_u64 v[18:19], v[70:71], 1, v[18:19]
	v_pk_mul_f32 v[40:41], v[84:85], v[102:103]
	v_cvt_pk_bf16_f32 v24, v24, v25
	v_lshlrev_b32_e32 v39, 16, v22
	v_cvt_pk_bf16_f32 v25, v40, v41
	global_store_dwordx4 v[18:19], v[22:25], off
	s_nop 1
	v_and_b32_e32 v22, 0xffff0000, v22
	v_max3_f32 v22, |v39|, 0, |v22|
	v_lshlrev_b32_e32 v39, 16, v23
	v_and_b32_e32 v23, 0xffff0000, v23
	v_max3_f32 v22, v22, |v39|, |v23|
	v_lshlrev_b32_e32 v23, 16, v24
	v_and_b32_e32 v24, 0xffff0000, v24
	v_max3_f32 v22, v22, |v23|, |v24|
	v_lshlrev_b32_e32 v23, 16, v25
	v_and_b32_e32 v24, 0xffff0000, v25
	v_max3_f32 v100, v22, |v23|, |v24|
	v_pk_mul_f32 v[22:23], v[38:39], v[96:97] op_sel_hi:[0,1]
	v_pk_mul_f32 v[24:25], v[38:39], v[92:93] op_sel_hi:[0,1]
	v_pk_mul_f32 v[40:41], v[38:39], v[98:99] op_sel_hi:[0,1]
	v_pk_mul_f32 v[38:39], v[38:39], v[94:95] op_sel_hi:[0,1]
	v_pk_fma_f32 v[12:13], v[66:67], v[24:25], v[12:13]
	v_pk_fma_f32 v[10:11], v[68:69], v[22:23], v[10:11]
	v_pk_fma_f32 v[4:5], v[74:75], v[38:39], v[4:5]
	v_pk_fma_f32 v[2:3], v[72:73], v[40:41], v[2:3]
	global_store_dwordx4 v[20:21], v[10:13], off offset:512 nt
	global_store_dwordx4 v[20:21], v[2:5], off offset:528 nt
	v_mul_f32_e32 v20, v11, v11
	v_mul_f32_e32 v21, v13, v13
	v_fmac_f32_e32 v20, v10, v10
	v_fmac_f32_e32 v21, v12, v12
	v_add_f32_e32 v20, v20, v21
	v_mul_f32_e32 v21, v3, v3
	v_fmac_f32_e32 v21, v2, v2
	v_add_f32_e32 v20, v21, v20
	v_mul_f32_e32 v21, v5, v5
	v_fmac_f32_e32 v21, v4, v4
	v_add_f32_e32 v20, v21, v20
	v_add_f32_e32 v22, v104, v20
	v_pk_mul_f32 v[10:11], v[60:61], v[10:11]
	v_pk_mul_f32 v[20:21], v[62:63], v[4:5]
	v_pk_mul_f32 v[4:5], v[64:65], v[2:3]
	v_cvt_pk_bf16_f32 v2, v10, v11
	v_pk_mul_f32 v[12:13], v[58:59], v[12:13]
	v_lshlrev_b32_e32 v10, 16, v2
	v_cvt_pk_bf16_f32 v3, v12, v13
	v_cvt_pk_bf16_f32 v4, v4, v5
	v_cvt_pk_bf16_f32 v5, v20, v21
	global_store_dwordx4 v[18:19], v[2:5], off offset:256
	s_nop 1
	v_and_b32_e32 v2, 0xffff0000, v2
	v_max3_f32 v2, v100, |v10|, |v2|
	v_lshlrev_b32_e32 v10, 16, v3
	v_and_b32_e32 v3, 0xffff0000, v3
	v_max3_f32 v2, v2, |v10|, |v3|
	v_lshlrev_b32_e32 v3, 16, v4
	v_and_b32_e32 v4, 0xffff0000, v4
	v_max3_f32 v2, v2, |v3|, |v4|
	v_lshlrev_b32_e32 v3, 16, v5
	v_and_b32_e32 v4, 0xffff0000, v5
	v_max3_f32 v4, v2, |v3|, |v4|
	ds_bpermute_b32 v5, v212, v4
	ds_bpermute_b32 v2, v212, v22
	s_waitcnt lgkmcnt(1)
	v_max_f32_e32 v5, v5, v5
	s_waitcnt lgkmcnt(0)
	v_add_f32_e32 v2, v22, v2
	v_max_f32_e32 v4, v4, v5
	ds_bpermute_b32 v3, v213, v2
	ds_bpermute_b32 v5, v213, v4
	s_and_saveexec_b64 s[50:51], s[0:1]
	s_cbranch_execz .LBB0_913
	s_waitcnt lgkmcnt(0)
	v_max_f32_e32 v5, v5, v5
	v_max_f32_e32 v4, v4, v4
	v_add_f32_e32 v11, v2, v3
	v_lshlrev_b64 v[2:3], 7, v[34:35]
	v_max_f32_e32 v10, v4, v5
	v_lshl_add_u64 v[4:5], s[30:31], 0, v[2:3]
	s_lshl_b64 s[16:17], s[46:47], 2
	v_lshl_add_u64 v[2:3], s[34:35], 0, v[2:3]
	v_lshl_add_u64 v[4:5], v[4:5], 0, s[16:17]
	s_lshl_b32 s12, s93, 2
	v_lshl_add_u64 v[2:3], v[2:3], 0, s[16:17]
	v_lshl_add_u64 v[4:5], v[4:5], 0, s[12:13]
	v_lshl_add_u64 v[2:3], v[2:3], 0, s[12:13]
	global_store_dword v[4:5], v11, off
	global_store_dword v[2:3], v10, off
.LBB0_913:
	s_or_b64 exec, exec, s[50:51]
	s_waitcnt lgkmcnt(0)
	v_lshl_add_u64 v[4:5], v[36:37], 2, s[22:23]
	s_nop 1
	v_mov_b32_e32 v10, v247
	v_lshlrev_b64 v[2:3], 13, v[36:37]
	v_lshl_add_u64 v[2:3], s[20:21], 0, v[2:3]
	s_waitcnt vmcnt(8)
	v_pk_mul_f32 v[4:5], v[10:11], v[52:53] op_sel_hi:[0,1]
	v_pk_mul_f32 v[12:13], v[10:11], v[50:51] op_sel_hi:[0,1]
	v_pk_fma_f32 v[20:21], v[76:77], v[12:13], v[32:33]
	v_pk_fma_f32 v[18:19], v[78:79], v[4:5], v[30:31]
	v_pk_mul_f32 v[22:23], v[10:11], v[56:57] op_sel_hi:[0,1]
	v_lshl_add_u64 v[4:5], v[70:71], 2, v[2:3]
	v_mul_f32_e32 v2, v19, v19
	v_mul_f32_e32 v3, v21, v21
	v_pk_fma_f32 v[22:23], v[90:91], v[22:23], v[26:27]
	v_fmac_f32_e32 v2, v18, v18
	v_fmac_f32_e32 v3, v20, v20
	v_pk_mul_f32 v[24:25], v[10:11], v[54:55] op_sel_hi:[0,1]
	v_add_f32_e32 v2, v2, v3
	v_mul_f32_e32 v3, v23, v23
	v_pk_fma_f32 v[24:25], v[88:89], v[24:25], v[28:29]
	v_fmac_f32_e32 v3, v22, v22
	v_add_f32_e32 v2, v3, v2
	v_mul_f32_e32 v3, v25, v25
	v_fmac_f32_e32 v3, v24, v24
	v_pk_mul_f32 v[12:13], v[82:83], v[18:19]
	global_store_dwordx4 v[4:5], v[18:21], off nt
	global_store_dwordx4 v[4:5], v[22:25], off offset:16 nt
	v_add_f32_e32 v26, v3, v2
	v_pk_mul_f32 v[2:3], v[80:81], v[20:21]
	v_cvt_pk_bf16_f32 v18, v12, v13
	v_pk_mul_f32 v[20:21], v[86:87], v[22:23]
	v_lshlrev_b32_e32 v11, 16, v18
	v_and_b32_e32 v12, 0xffff0000, v18
	v_cvt_pk_bf16_f32 v19, v2, v3
	v_lshlrev_b64 v[2:3], 12, v[36:37]
	v_max3_f32 v11, |v11|, 0, |v12|
	v_lshlrev_b32_e32 v12, 16, v19
	v_and_b32_e32 v13, 0xffff0000, v19
	v_cvt_pk_bf16_f32 v20, v20, v21
	v_lshl_add_u64 v[2:3], s[26:27], 0, v[2:3]
	v_max3_f32 v11, v11, |v12|, |v13|
	v_lshlrev_b32_e32 v12, 16, v20
	v_and_b32_e32 v13, 0xffff0000, v20
	v_pk_mul_f32 v[24:25], v[84:85], v[24:25]
	v_lshl_add_u64 v[2:3], v[70:71], 1, v[2:3]
	v_cvt_pk_bf16_f32 v21, v24, v25
	v_max3_f32 v11, v11, |v12|, |v13|
	v_lshlrev_b32_e32 v12, 16, v21
	v_and_b32_e32 v13, 0xffff0000, v21
	global_store_dwordx4 v[2:3], v[18:21], off
	v_max3_f32 v24, v11, |v12|, |v13|
	v_pk_mul_f32 v[12:13], v[10:11], v[42:43] op_sel_hi:[0,1]
	v_pk_mul_f32 v[18:19], v[10:11], v[46:47] op_sel_hi:[0,1]
	v_pk_mul_f32 v[20:21], v[10:11], v[48:49] op_sel_hi:[0,1]
	v_pk_mul_f32 v[22:23], v[10:11], v[44:45] op_sel_hi:[0,1]
	v_pk_fma_f32 v[12:13], v[66:67], v[12:13], v[16:17]
	v_pk_fma_f32 v[10:11], v[68:69], v[18:19], v[14:15]
	v_pk_fma_f32 v[8:9], v[74:75], v[22:23], v[8:9]
	v_pk_fma_f32 v[6:7], v[72:73], v[20:21], v[6:7]
	global_store_dwordx4 v[4:5], v[10:13], off offset:512 nt
	global_store_dwordx4 v[4:5], v[6:9], off offset:528 nt
	v_mul_f32_e32 v4, v11, v11
	v_mul_f32_e32 v5, v13, v13
	v_fmac_f32_e32 v4, v10, v10
	v_fmac_f32_e32 v5, v12, v12
	v_add_f32_e32 v4, v4, v5
	v_mul_f32_e32 v5, v7, v7
	v_fmac_f32_e32 v5, v6, v6
	v_add_f32_e32 v4, v5, v4
	v_mul_f32_e32 v5, v9, v9
	v_fmac_f32_e32 v5, v8, v8
	v_add_f32_e32 v4, v5, v4
	v_add_f32_e32 v14, v26, v4
	v_pk_mul_f32 v[4:5], v[60:61], v[10:11]
	v_pk_mul_f32 v[6:7], v[64:65], v[6:7]
	v_pk_mul_f32 v[12:13], v[58:59], v[12:13]
	v_pk_mul_f32 v[8:9], v[62:63], v[8:9]
	v_cvt_pk_bf16_f32 v4, v4, v5
	v_cvt_pk_bf16_f32 v5, v12, v13
	v_cvt_pk_bf16_f32 v6, v6, v7
	s_nop 0
	v_cvt_pk_bf16_f32 v7, v8, v9
	global_store_dwordx4 v[2:3], v[4:7], off offset:256
	v_lshlrev_b32_e32 v2, 16, v4
	v_and_b32_e32 v3, 0xffff0000, v4
	v_max3_f32 v2, v24, |v2|, |v3|
	v_lshlrev_b32_e32 v3, 16, v5
	v_and_b32_e32 v4, 0xffff0000, v5
	v_max3_f32 v2, v2, |v3|, |v4|
	v_lshlrev_b32_e32 v3, 16, v6
	v_and_b32_e32 v4, 0xffff0000, v6
	v_max3_f32 v2, v2, |v3|, |v4|
	v_lshlrev_b32_e32 v3, 16, v7
	v_and_b32_e32 v4, 0xffff0000, v7
	v_max3_f32 v4, v2, |v3|, |v4|
	ds_bpermute_b32 v5, v212, v4
	ds_bpermute_b32 v2, v212, v14
	s_waitcnt lgkmcnt(1)
	v_max_f32_e32 v5, v5, v5
	s_waitcnt lgkmcnt(0)
	v_add_f32_e32 v2, v14, v2
	v_max_f32_e32 v4, v4, v5
	ds_bpermute_b32 v3, v213, v2
	ds_bpermute_b32 v5, v213, v4
	s_and_saveexec_b64 s[50:51], s[0:1]
	s_cbranch_execz .LBB0_915
	s_waitcnt lgkmcnt(0)
	v_max_f32_e32 v5, v5, v5
	v_max_f32_e32 v4, v4, v4
	v_add_f32_e32 v7, v2, v3
	v_lshlrev_b64 v[2:3], 7, v[36:37]
	v_max_f32_e32 v6, v4, v5
	v_lshl_add_u64 v[4:5], s[30:31], 0, v[2:3]
	s_lshl_b64 s[16:17], s[46:47], 2
	v_lshl_add_u64 v[2:3], s[34:35], 0, v[2:3]
	v_lshl_add_u64 v[4:5], v[4:5], 0, s[16:17]
	s_lshl_b32 s12, s93, 2
	v_lshl_add_u64 v[2:3], v[2:3], 0, s[16:17]
	v_lshl_add_u64 v[4:5], v[4:5], 0, s[12:13]
	v_lshl_add_u64 v[2:3], v[2:3], 0, s[12:13]
	global_store_dword v[4:5], v7, off
	global_store_dword v[2:3], v6, off

.LBB0_1758:
	s_lshr_b32 s42, s85, 4
	s_add_i32 s42, s42, -1
	s_cmp_gt_i32 s85, 31
	s_cselect_b32 s42, s42, 0
	v_lshl_or_b32 v90, s12, 8, v230
	s_mul_i32 s45, s42, 0xc000
	s_mul_hi_i32 s44, s42, 0xc000
	s_add_u32 s42, s59, s45
	v_ashrrev_i32_e32 v91, 31, v90
	s_addc_u32 s43, s60, s44
	v_lshlrev_b64 v[36:37], 2, v[90:91]
	v_lshl_add_u64 v[26:27], s[42:43], 0, v[36:37]
	v_lshl_add_u64 v[28:29], s[20:21], 0, v[36:37]
	s_waitcnt lgkmcnt(0)
	global_load_dwordx4 v[2:5], v[26:27], off offset:16
	global_load_dwordx4 v[6:9], v[26:27], off
	global_load_dwordx4 v[10:13], v[28:29], off offset:16
	global_load_dwordx4 v[14:17], v[28:29], off
	s_add_u32 s42, s61, s45
	v_lshl_add_u64 v[30:31], s[24:25], 0, v[36:37]
	s_addc_u32 s43, s62, s44
	v_lshl_add_u64 v[32:33], s[42:43], 0, v[36:37]
	v_lshl_add_u32 v210, s85, 8, v228
	v_ashrrev_i32_e32 v211, 31, v210
	v_or_b32_e32 v34, 16, v210
	v_ashrrev_i32_e32 v35, 31, v34
	s_lshl_b32 s42, s12, 2
	s_ashr_i32 s43, s42, 31
	s_waitcnt vmcnt(0)
	v_pk_mul_f32 v[92:93], v[4:5], v[12:13]
	v_pk_mul_f32 v[86:87], v[8:9], v[16:17]
	v_pk_mul_f32 v[88:89], v[6:7], v[14:15]
	global_load_dwordx4 v[6:9], v[30:31], off offset:16
	global_load_dwordx4 v[14:17], v[30:31], off
	global_load_dwordx4 v[18:21], v[32:33], off offset:16
	global_load_dwordx4 v[22:25], v[32:33], off
	v_pk_mul_f32 v[94:95], v[2:3], v[10:11]
	s_waitcnt vmcnt(0)
	v_pk_add_f32 v[2:3], v[20:21], 1.0 op_sel_hi:[1,0]
	v_pk_add_f32 v[24:25], v[24:25], 1.0 op_sel_hi:[1,0]
	v_pk_add_f32 v[22:23], v[22:23], 1.0 op_sel_hi:[1,0]
	v_pk_add_f32 v[4:5], v[18:19], 1.0 op_sel_hi:[1,0]
	v_pk_mul_f32 v[78:79], v[16:17], v[24:25]
	v_pk_mul_f32 v[80:81], v[14:15], v[22:23]
	v_pk_mul_f32 v[82:83], v[8:9], v[2:3]
	v_pk_mul_f32 v[84:85], v[6:7], v[4:5]
	global_load_dwordx4 v[2:5], v[26:27], off offset:528
	global_load_dwordx4 v[6:9], v[26:27], off offset:512
	global_load_dwordx4 v[10:13], v[28:29], off offset:528
	global_load_dwordx4 v[14:17], v[28:29], off offset:512
	s_waitcnt vmcnt(0)
	v_pk_mul_f32 v[108:109], v[2:3], v[10:11]
	v_pk_mul_f32 v[104:105], v[8:9], v[16:17]
	v_pk_mul_f32 v[106:107], v[6:7], v[14:15]
	global_load_dwordx4 v[6:9], v[30:31], off offset:528
	global_load_dwordx4 v[14:17], v[30:31], off offset:512
	global_load_dwordx4 v[18:21], v[32:33], off offset:528
	global_load_dwordx4 v[22:25], v[32:33], off offset:512
	v_pk_mul_f32 v[110:111], v[4:5], v[12:13]
	s_waitcnt vmcnt(0)
	v_pk_add_f32 v[2:3], v[20:21], 1.0 op_sel_hi:[1,0]
	s_nop 0
	v_pk_mul_f32 v[100:101], v[8:9], v[2:3]
	v_lshlrev_b64 v[2:3], 13, v[210:211]
	v_lshl_add_u64 v[2:3], s[16:17], 0, v[2:3]
	v_lshl_add_u64 v[38:39], v[2:3], 0, v[36:37]
	v_lshlrev_b64 v[2:3], 13, v[34:35]
	v_lshl_add_u64 v[2:3], s[16:17], 0, v[2:3]
	v_pk_add_f32 v[24:25], v[24:25], 1.0 op_sel_hi:[1,0]
	v_pk_add_f32 v[22:23], v[22:23], 1.0 op_sel_hi:[1,0]
	v_pk_add_f32 v[4:5], v[18:19], 1.0 op_sel_hi:[1,0]
	v_lshl_add_u64 v[36:37], v[2:3], 0, v[36:37]
	v_pk_mul_f32 v[96:97], v[16:17], v[24:25]
	v_pk_mul_f32 v[98:99], v[14:15], v[22:23]
	v_pk_mul_f32 v[102:103], v[6:7], v[4:5]
	v_lshl_add_u64 v[196:197], v[210:211], 2, s[18:19]
	global_load_dword v240, v[196:197], off
	global_load_dword v241, v[196:197], off offset:64
	global_load_dword v242, v[196:197], off offset:128
	global_load_dword v243, v[196:197], off offset:192
	global_load_dword v244, v[196:197], off offset:512
	global_load_dword v245, v[196:197], off offset:576
	global_load_dword v246, v[196:197], off offset:640
	global_load_dword v247, v[196:197], off offset:704
	global_load_dwordx4 v[22:25], v[38:39], off offset:16 nt
	global_load_dwordx4 v[30:33], v[38:39], off nt
	global_load_dwordx4 v[18:21], v[38:39], off offset:528 nt
	global_load_dwordx4 v[26:29], v[38:39], off offset:512 nt
	global_load_dwordx4 v[10:13], v[36:37], off offset:16 nt
	global_load_dwordx4 v[14:17], v[36:37], off nt
	global_load_dwordx4 v[2:5], v[36:37], off offset:528 nt
	global_load_dwordx4 v[6:9], v[36:37], off offset:512 nt
	v_lshl_add_u64 v[196:197], v[210:211], 2, s[18:19]
	s_nop 0
	v_and_b32_e32 v44, 64, v232
	v_xor_b32_e32 v41, 16, v232
	v_add_u32_e32 v234, 64, v44
	v_cmp_lt_i32_e32 vcc, v41, v234
	v_lshlrev_b64 v[42:43], 12, v[210:211]
	v_lshl_add_u64 v[42:43], s[22:23], 0, v[42:43]
	v_cndmask_b32_e32 v41, v232, v41, vcc
	v_lshlrev_b32_e32 v233, 2, v41
	v_lshl_add_u64 v[42:43], v[90:91], 1, v[42:43]
	s_waitcnt vmcnt(4)
	v_mov_b32_e32 v40, v240
	v_pk_mul_f32 v[44:45], v[40:41], v[214:215] op_sel_hi:[0,1]
	v_pk_mul_f32 v[212:213], v[40:41], v[212:213] op_sel_hi:[0,1]
	v_pk_mul_f32 v[214:215], v[40:41], v[218:219] op_sel_hi:[0,1]
	v_pk_mul_f32 v[218:219], v[40:41], v[222:223] op_sel_hi:[0,1]
	v_pk_mul_f32 v[220:221], v[40:41], v[220:221] op_sel_hi:[0,1]
	v_pk_mul_f32 v[216:217], v[40:41], v[216:217] op_sel_hi:[0,1]
	v_pk_mul_f32 v[222:223], v[40:41], v[226:227] op_sel_hi:[0,1]
	v_pk_mul_f32 v[40:41], v[40:41], v[224:225] op_sel_hi:[0,1]
	v_pk_fma_f32 v[32:33], v[86:87], v[212:213], v[32:33]
	v_pk_fma_f32 v[30:31], v[88:89], v[44:45], v[30:31]
	v_pk_fma_f32 v[28:29], v[104:105], v[220:221], v[28:29]
	v_pk_fma_f32 v[26:27], v[106:107], v[218:219], v[26:27]
	v_pk_fma_f32 v[24:25], v[92:93], v[216:217], v[24:25]
	v_pk_fma_f32 v[22:23], v[94:95], v[214:215], v[22:23]
	v_pk_fma_f32 v[20:21], v[110:111], v[40:41], v[20:21]
	v_pk_fma_f32 v[18:19], v[108:109], v[222:223], v[18:19]
	global_store_dwordx4 v[38:39], v[30:33], off nt
	global_store_dwordx4 v[38:39], v[22:25], off offset:16 nt
	v_mul_f32_e32 v224, v31, v31
	v_mul_f32_e32 v225, v33, v33
	v_pk_mul_f32 v[40:41], v[78:79], v[32:33]
	v_pk_mul_f32 v[44:45], v[80:81], v[30:31]
	v_mul_f32_e32 v31, v27, v27
	v_mul_f32_e32 v33, v29, v29
	v_mul_f32_e32 v226, v23, v23
	v_mul_f32_e32 v227, v25, v25
	v_mul_f32_e32 v235, v19, v19
	v_fmac_f32_e32 v224, v30, v30
	v_fmac_f32_e32 v225, v32, v32
	v_fmac_f32_e32 v31, v26, v26
	v_fmac_f32_e32 v33, v28, v28
	v_pk_mul_f32 v[212:213], v[82:83], v[24:25]
	v_pk_mul_f32 v[214:215], v[84:85], v[22:23]
	v_mul_f32_e32 v236, v21, v21
	v_pk_mul_f32 v[222:223], v[102:103], v[18:19]
	v_fmac_f32_e32 v226, v22, v22
	v_fmac_f32_e32 v227, v24, v24
	v_cvt_pk_bf16_f32 v22, v44, v45
	v_cvt_pk_bf16_f32 v23, v40, v41
	v_cvt_pk_bf16_f32 v24, v214, v215
	v_cvt_pk_bf16_f32 v25, v212, v213
	v_fmac_f32_e32 v235, v18, v18
	v_add_f32_e32 v30, v224, v225
	global_store_dwordx4 v[42:43], v[22:25], off
	v_lshlrev_b32_e32 v32, 16, v22
	v_and_b32_e32 v40, 0xffff0000, v22
	global_store_dwordx4 v[38:39], v[26:29], off offset:512 nt
	global_store_dwordx4 v[38:39], v[18:21], off offset:528 nt
	v_pk_mul_f32 v[220:221], v[100:101], v[20:21]
	v_fmac_f32_e32 v236, v20, v20
	v_add_f32_e32 v18, v31, v33
	v_lshlrev_b32_e32 v41, 16, v23
	v_and_b32_e32 v44, 0xffff0000, v23
	v_add_f32_e32 v19, v226, v30
	v_max3_f32 v20, |v32|, 0, |v40|
	v_add_f32_e32 v18, v235, v18
	v_lshlrev_b32_e32 v45, 16, v24
	v_and_b32_e32 v212, 0xffff0000, v24
	v_add_f32_e32 v19, v227, v19
	v_max3_f32 v20, v20, |v41|, |v44|
	v_add_f32_e32 v18, v236, v18
	v_lshlrev_b32_e32 v213, 16, v25
	v_and_b32_e32 v214, 0xffff0000, v25
	v_max3_f32 v20, v20, |v45|, |v212|
	v_add_f32_e32 v18, v19, v18
	v_pk_mul_f32 v[218:219], v[98:99], v[26:27]
	v_max3_f32 v19, v20, |v213|, |v214|
	v_cvt_pk_bf16_f32 v22, v218, v219
	ds_bpermute_b32 v20, v233, v18
	v_lshlrev_b32_e32 v21, 16, v22
	v_and_b32_e32 v26, 0xffff0000, v22
	v_pk_mul_f32 v[216:217], v[96:97], v[28:29]
	v_max3_f32 v19, v19, |v21|, |v26|
	v_cvt_pk_bf16_f32 v23, v216, v217
	v_cvt_pk_bf16_f32 v24, v222, v223
	v_cvt_pk_bf16_f32 v25, v220, v221
	s_waitcnt lgkmcnt(0)
	v_add_f32_e32 v18, v18, v20
	v_lshlrev_b32_e32 v27, 16, v23
	v_and_b32_e32 v28, 0xffff0000, v23
	v_lshlrev_b32_e32 v29, 16, v24
	v_and_b32_e32 v30, 0xffff0000, v24
	v_max3_f32 v19, v19, |v27|, |v28|
	v_max3_f32 v19, v19, |v29|, |v30|
	v_lshlrev_b32_e32 v21, 16, v25
	v_and_b32_e32 v26, 0xffff0000, v25
	v_max3_f32 v21, v19, |v21|, |v26|
	ds_bpermute_b32 v20, v233, v21
	v_xor_b32_e32 v19, 32, v232
	v_cmp_lt_i32_e32 vcc, v19, v234
	global_store_dwordx4 v[42:43], v[22:25], off offset:256
	s_waitcnt lgkmcnt(0)
	v_max_f32_e32 v20, v20, v20
	v_cndmask_b32_e32 v19, v232, v19, vcc
	v_lshlrev_b32_e32 v216, 2, v19
	v_max_f32_e32 v20, v21, v20
	ds_bpermute_b32 v19, v216, v18
	ds_bpermute_b32 v21, v216, v20
	s_and_saveexec_b64 s[44:45], s[0:1]
	s_cbranch_execz .LBB0_1760
	s_waitcnt lgkmcnt(0)
	v_max_f32_e32 v21, v21, v21
	v_max_f32_e32 v20, v20, v20
	v_add_f32_e32 v23, v18, v19
	v_lshlrev_b64 v[18:19], 7, v[210:211]
	v_max_f32_e32 v22, v20, v21
	v_lshl_add_u64 v[20:21], s[26:27], 0, v[18:19]
	s_lshl_b64 s[86:87], s[42:43], 2
	v_lshl_add_u64 v[18:19], s[28:29], 0, v[18:19]
	v_lshl_add_u64 v[20:21], v[20:21], 0, s[86:87]
	s_lshl_b32 s12, s65, 2
	v_lshl_add_u64 v[18:19], v[18:19], 0, s[86:87]
	v_lshl_add_u64 v[20:21], v[20:21], 0, s[12:13]
	v_lshl_add_u64 v[18:19], v[18:19], 0, s[12:13]
	global_store_dword v[20:21], v23, off
	global_store_dword v[18:19], v22, off
.LBB0_1760:
	s_or_b64 exec, exec, s[44:45]
	v_or_b32_e32 v212, 32, v210
	v_ashrrev_i32_e32 v213, 31, v212
	s_waitcnt lgkmcnt(1)
	v_lshlrev_b64 v[18:19], 13, v[212:213]
	v_lshl_add_u64 v[18:19], s[16:17], 0, v[18:19]
	v_lshl_add_u64 v[214:215], v[90:91], 2, v[18:19]
	global_load_dwordx4 v[26:29], v[214:215], off offset:16 nt
	global_load_dwordx4 v[30:33], v[214:215], off nt
	s_waitcnt lgkmcnt(0)
	global_load_dwordx4 v[18:21], v[214:215], off offset:528 nt
	global_load_dwordx4 v[22:25], v[214:215], off offset:512 nt
	v_lshl_add_u64 v[38:39], v[34:35], 2, s[18:19]
	s_nop 1
	v_mov_b32_e32 v38, v241
	v_lshlrev_b64 v[40:41], 12, v[34:35]
	v_lshl_add_u64 v[40:41], s[22:23], 0, v[40:41]
	v_lshl_add_u64 v[40:41], v[90:91], 1, v[40:41]
	s_waitcnt vmcnt(12)
	v_pk_mul_f32 v[44:45], v[38:39], v[192:193] op_sel_hi:[0,1]
	v_pk_mul_f32 v[192:193], v[38:39], v[200:201] op_sel_hi:[0,1]
	v_pk_mul_f32 v[42:43], v[38:39], v[194:195] op_sel_hi:[0,1]
	v_pk_mul_f32 v[194:195], v[38:39], v[198:199] op_sel_hi:[0,1]
	v_pk_mul_f32 v[198:199], v[38:39], v[206:207] op_sel_hi:[0,1]
	v_pk_mul_f32 v[200:201], v[38:39], v[202:203] op_sel_hi:[0,1]
	v_pk_fma_f32 v[10:11], v[94:95], v[192:193], v[10:11]
	v_pk_mul_f32 v[202:203], v[38:39], v[208:209] op_sel_hi:[0,1]
	v_pk_mul_f32 v[38:39], v[38:39], v[204:205] op_sel_hi:[0,1]
	v_pk_fma_f32 v[16:17], v[86:87], v[44:45], v[16:17]
	v_pk_fma_f32 v[14:15], v[88:89], v[42:43], v[14:15]
	v_pk_fma_f32 v[12:13], v[92:93], v[194:195], v[12:13]
	v_pk_fma_f32 v[8:9], v[104:105], v[200:201], v[8:9]
	v_pk_fma_f32 v[6:7], v[106:107], v[198:199], v[6:7]
	v_mul_f32_e32 v206, v11, v11
	v_pk_fma_f32 v[4:5], v[110:111], v[38:39], v[4:5]
	v_pk_fma_f32 v[2:3], v[108:109], v[202:203], v[2:3]
	global_store_dwordx4 v[36:37], v[14:17], off nt
	global_store_dwordx4 v[36:37], v[10:13], off offset:16 nt
	v_mul_f32_e32 v204, v15, v15
	v_mul_f32_e32 v205, v17, v17
	v_mul_f32_e32 v207, v13, v13
	v_pk_mul_f32 v[38:39], v[78:79], v[16:17]
	v_pk_mul_f32 v[42:43], v[80:81], v[14:15]
	v_pk_mul_f32 v[192:193], v[84:85], v[10:11]
	v_mul_f32_e32 v15, v7, v7
	v_mul_f32_e32 v17, v9, v9
	v_fmac_f32_e32 v206, v10, v10
	v_cvt_pk_bf16_f32 v10, v42, v43
	v_pk_mul_f32 v[44:45], v[82:83], v[12:13]
	v_mul_f32_e32 v208, v3, v3
	v_mul_f32_e32 v209, v5, v5
	v_fmac_f32_e32 v204, v14, v14
	v_fmac_f32_e32 v205, v16, v16
	v_fmac_f32_e32 v207, v12, v12
	v_cvt_pk_bf16_f32 v11, v38, v39
	v_cvt_pk_bf16_f32 v12, v192, v193
	v_cvt_pk_bf16_f32 v13, v44, v45
	v_fmac_f32_e32 v15, v6, v6
	v_fmac_f32_e32 v17, v8, v8
	global_store_dwordx4 v[40:41], v[10:13], off
	v_lshlrev_b32_e32 v16, 16, v10
	v_pk_mul_f32 v[200:201], v[100:101], v[4:5]
	v_and_b32_e32 v10, 0xffff0000, v10
	v_pk_mul_f32 v[202:203], v[102:103], v[2:3]
	v_fmac_f32_e32 v208, v2, v2
	v_fmac_f32_e32 v209, v4, v4
	v_add_f32_e32 v14, v204, v205
	v_lshlrev_b32_e32 v38, 16, v11
	v_and_b32_e32 v11, 0xffff0000, v11
	global_store_dwordx4 v[36:37], v[6:9], off offset:512 nt
	global_store_dwordx4 v[36:37], v[2:5], off offset:528 nt
	v_lshlrev_b32_e32 v39, 16, v12
	v_and_b32_e32 v12, 0xffff0000, v12
	v_add_f32_e32 v2, v15, v17
	v_max3_f32 v4, |v16|, 0, |v10|
	v_add_f32_e32 v3, v206, v14
	v_add_f32_e32 v2, v208, v2
	v_max3_f32 v4, v4, |v38|, |v11|
	v_lshlrev_b32_e32 v42, 16, v13
	v_and_b32_e32 v13, 0xffff0000, v13
	v_add_f32_e32 v3, v207, v3
	v_add_f32_e32 v2, v209, v2
	v_max3_f32 v4, v4, |v39|, |v12|
	v_pk_mul_f32 v[198:199], v[98:99], v[6:7]
	v_add_f32_e32 v2, v3, v2
	v_cvt_pk_bf16_f32 v6, v198, v199
	v_max3_f32 v3, v4, |v42|, |v13|
	v_lshlrev_b32_e32 v5, 16, v6
	v_and_b32_e32 v10, 0xffff0000, v6
	v_pk_mul_f32 v[194:195], v[96:97], v[8:9]
	v_max3_f32 v3, v3, |v5|, |v10|
	v_cvt_pk_bf16_f32 v7, v194, v195
	v_cvt_pk_bf16_f32 v8, v202, v203
	v_cvt_pk_bf16_f32 v9, v200, v201
	ds_bpermute_b32 v4, v233, v2
	v_lshlrev_b32_e32 v14, 16, v7
	v_and_b32_e32 v15, 0xffff0000, v7
	v_lshlrev_b32_e32 v16, 16, v8
	v_and_b32_e32 v17, 0xffff0000, v8
	v_max3_f32 v3, v3, |v14|, |v15|
	v_lshlrev_b32_e32 v36, 16, v9
	v_and_b32_e32 v37, 0xffff0000, v9
	v_max3_f32 v3, v3, |v16|, |v17|
	v_max3_f32 v5, v3, |v36|, |v37|
	ds_bpermute_b32 v10, v233, v5
	s_waitcnt lgkmcnt(1)
	v_add_f32_e32 v2, v2, v4
	ds_bpermute_b32 v3, v216, v2
	global_store_dwordx4 v[40:41], v[6:9], off offset:256
	s_waitcnt lgkmcnt(1)
	v_max_f32_e32 v4, v10, v10
	v_max_f32_e32 v4, v5, v4
	ds_bpermute_b32 v5, v216, v4
	s_and_saveexec_b64 s[44:45], s[0:1]
	s_cbranch_execz .LBB0_1762
	s_waitcnt lgkmcnt(0)
	v_max_f32_e32 v5, v5, v5
	v_max_f32_e32 v4, v4, v4
	v_add_f32_e32 v7, v2, v3
	v_lshlrev_b64 v[2:3], 7, v[34:35]
	v_max_f32_e32 v6, v4, v5
	v_lshl_add_u64 v[4:5], s[26:27], 0, v[2:3]
	s_lshl_b64 s[86:87], s[42:43], 2
	v_lshl_add_u64 v[2:3], s[28:29], 0, v[2:3]
	v_lshl_add_u64 v[4:5], v[4:5], 0, s[86:87]
	s_lshl_b32 s12, s65, 2
	v_lshl_add_u64 v[2:3], v[2:3], 0, s[86:87]
	v_lshl_add_u64 v[4:5], v[4:5], 0, s[12:13]
	v_lshl_add_u64 v[2:3], v[2:3], 0, s[12:13]
	global_store_dword v[4:5], v7, off
	global_store_dword v[2:3], v6, off
.LBB0_1762:
	s_or_b64 exec, exec, s[44:45]
	v_or_b32_e32 v192, 48, v210
	v_ashrrev_i32_e32 v193, 31, v192
	s_waitcnt lgkmcnt(1)
	v_lshlrev_b64 v[2:3], 13, v[192:193]
	v_lshl_add_u64 v[2:3], s[16:17], 0, v[2:3]
	v_lshl_add_u64 v[194:195], v[90:91], 2, v[2:3]
	global_load_dwordx4 v[38:41], v[194:195], off offset:16 nt
	global_load_dwordx4 v[42:45], v[194:195], off nt
	global_load_dwordx4 v[6:9], v[194:195], off offset:528 nt
	global_load_dwordx4 v[34:37], v[194:195], off offset:512 nt
	v_lshl_add_u64 v[2:3], v[212:213], 2, s[18:19]
	s_nop 1
	v_mov_b32_e32 v2, v242
	s_waitcnt lgkmcnt(0)
	v_lshlrev_b64 v[4:5], 12, v[212:213]
	v_lshl_add_u64 v[4:5], s[22:23], 0, v[4:5]
	v_lshl_add_u64 v[198:199], v[90:91], 1, v[4:5]
	s_waitcnt vmcnt(12)
	v_pk_mul_f32 v[10:11], v[2:3], v[178:179] op_sel_hi:[0,1]
	v_pk_mul_f32 v[4:5], v[2:3], v[176:177] op_sel_hi:[0,1]
	v_pk_mul_f32 v[14:15], v[2:3], v[182:183] op_sel_hi:[0,1]
	v_pk_mul_f32 v[12:13], v[2:3], v[180:181] op_sel_hi:[0,1]
	v_pk_mul_f32 v[176:177], v[2:3], v[188:189] op_sel_hi:[0,1]
	v_pk_mul_f32 v[16:17], v[2:3], v[184:185] op_sel_hi:[0,1]
	v_pk_mul_f32 v[178:179], v[2:3], v[190:191] op_sel_hi:[0,1]
	v_pk_mul_f32 v[180:181], v[2:3], v[186:187] op_sel_hi:[0,1]
	v_pk_fma_f32 v[2:3], v[88:89], v[10:11], v[30:31]
	v_pk_fma_f32 v[4:5], v[86:87], v[4:5], v[32:33]
	v_pk_fma_f32 v[20:21], v[110:111], v[180:181], v[20:21]
	v_mul_f32_e32 v180, v3, v3
	v_pk_fma_f32 v[12:13], v[92:93], v[12:13], v[28:29]
	v_pk_fma_f32 v[10:11], v[94:95], v[14:15], v[26:27]
	v_pk_fma_f32 v[16:17], v[104:105], v[16:17], v[24:25]
	v_pk_fma_f32 v[14:15], v[106:107], v[176:177], v[22:23]
	global_store_dwordx4 v[214:215], v[2:5], off nt
	global_store_dwordx4 v[214:215], v[10:13], off offset:16 nt
	v_mul_f32_e32 v181, v5, v5
	v_pk_mul_f32 v[22:23], v[78:79], v[4:5]
	v_pk_mul_f32 v[24:25], v[80:81], v[2:3]
	v_fmac_f32_e32 v180, v2, v2
	v_cvt_pk_bf16_f32 v2, v24, v25
	v_pk_mul_f32 v[26:27], v[82:83], v[12:13]
	v_pk_mul_f32 v[28:29], v[84:85], v[10:11]
	v_fmac_f32_e32 v181, v4, v4
	v_cvt_pk_bf16_f32 v3, v22, v23
	v_cvt_pk_bf16_f32 v4, v28, v29
	v_cvt_pk_bf16_f32 v5, v26, v27
	global_store_dwordx4 v[198:199], v[2:5], off
	v_lshlrev_b32_e32 v23, 16, v2
	v_lshlrev_b32_e32 v24, 16, v3
	v_and_b32_e32 v2, 0xffff0000, v2
	v_and_b32_e32 v3, 0xffff0000, v3
	v_max3_f32 v2, |v23|, 0, |v2|
	v_lshlrev_b32_e32 v25, 16, v4
	v_and_b32_e32 v4, 0xffff0000, v4
	v_max3_f32 v2, v2, |v24|, |v3|
	v_pk_fma_f32 v[18:19], v[108:109], v[178:179], v[18:19]
	v_mul_f32_e32 v182, v11, v11
	v_mul_f32_e32 v183, v13, v13
	v_mul_f32_e32 v11, v15, v15
	v_mul_f32_e32 v13, v17, v17
	v_lshlrev_b32_e32 v26, 16, v5
	v_and_b32_e32 v5, 0xffff0000, v5
	v_max3_f32 v2, v2, |v25|, |v4|
	v_mul_f32_e32 v184, v19, v19
	v_pk_mul_f32 v[30:31], v[96:97], v[16:17]
	v_pk_mul_f32 v[32:33], v[98:99], v[14:15]
	v_fmac_f32_e32 v182, v10, v10
	v_fmac_f32_e32 v11, v14, v14
	v_fmac_f32_e32 v13, v16, v16
	global_store_dwordx4 v[214:215], v[14:17], off offset:512 nt
	global_store_dwordx4 v[214:215], v[18:21], off offset:528 nt
	v_cvt_pk_bf16_f32 v10, v32, v33
	v_max3_f32 v2, v2, |v26|, |v5|
	v_lshlrev_b32_e32 v16, 16, v10
	v_and_b32_e32 v17, 0xffff0000, v10
	v_mul_f32_e32 v185, v21, v21
	v_pk_mul_f32 v[178:179], v[102:103], v[18:19]
	v_fmac_f32_e32 v184, v18, v18
	v_add_f32_e32 v22, v180, v181
	v_add_f32_e32 v14, v11, v13
	v_cvt_pk_bf16_f32 v11, v30, v31
	v_max3_f32 v2, v2, |v16|, |v17|
	v_lshlrev_b32_e32 v18, 16, v11
	v_and_b32_e32 v19, 0xffff0000, v11
	v_pk_mul_f32 v[176:177], v[100:101], v[20:21]
	v_fmac_f32_e32 v183, v12, v12
	v_fmac_f32_e32 v185, v20, v20
	v_cvt_pk_bf16_f32 v12, v178, v179
	v_add_f32_e32 v15, v182, v22
	v_add_f32_e32 v14, v184, v14
	v_lshlrev_b32_e32 v20, 16, v12
	v_and_b32_e32 v21, 0xffff0000, v12
	v_max3_f32 v2, v2, |v18|, |v19|
	v_cvt_pk_bf16_f32 v13, v176, v177
	v_add_f32_e32 v15, v183, v15
	v_lshlrev_b32_e32 v22, 16, v13
	v_and_b32_e32 v23, 0xffff0000, v13
	v_add_f32_e32 v3, v185, v14
	v_max3_f32 v2, v2, |v20|, |v21|
	v_add_f32_e32 v3, v15, v3
	v_max3_f32 v5, v2, |v22|, |v23|
	ds_bpermute_b32 v4, v233, v3
	ds_bpermute_b32 v14, v233, v5
	global_store_dwordx4 v[198:199], v[10:13], off offset:256
	s_waitcnt lgkmcnt(1)
	v_add_f32_e32 v2, v3, v4
	s_waitcnt lgkmcnt(0)
	v_max_f32_e32 v4, v14, v14
	v_max_f32_e32 v4, v5, v4
	ds_bpermute_b32 v3, v216, v2
	ds_bpermute_b32 v5, v216, v4
	s_and_saveexec_b64 s[44:45], s[0:1]
	s_cbranch_execz .LBB0_1764
	s_waitcnt lgkmcnt(0)
	v_max_f32_e32 v5, v5, v5
	v_max_f32_e32 v4, v4, v4
	v_add_f32_e32 v11, v2, v3
	v_lshlrev_b64 v[2:3], 7, v[212:213]
	v_max_f32_e32 v10, v4, v5
	v_lshl_add_u64 v[4:5], s[26:27], 0, v[2:3]
	s_lshl_b64 s[86:87], s[42:43], 2
	v_lshl_add_u64 v[2:3], s[28:29], 0, v[2:3]
	v_lshl_add_u64 v[4:5], v[4:5], 0, s[86:87]
	s_lshl_b32 s12, s65, 2
	v_lshl_add_u64 v[2:3], v[2:3], 0, s[86:87]
	v_lshl_add_u64 v[4:5], v[4:5], 0, s[12:13]
	v_lshl_add_u64 v[2:3], v[2:3], 0, s[12:13]
	global_store_dword v[4:5], v11, off
	global_store_dword v[2:3], v10, off
.LBB0_1764:
	s_or_b64 exec, exec, s[44:45]
	v_add_u32_e32 v176, 0x80, v210
	v_ashrrev_i32_e32 v177, 31, v176
	s_waitcnt lgkmcnt(1)
	v_lshlrev_b64 v[2:3], 13, v[176:177]
	v_lshl_add_u64 v[2:3], s[16:17], 0, v[2:3]
	v_lshl_add_u64 v[178:179], v[90:91], 2, v[2:3]
	global_load_dwordx4 v[14:17], v[178:179], off offset:16 nt
	global_load_dwordx4 v[18:21], v[178:179], off nt
	s_waitcnt lgkmcnt(0)
	global_load_dwordx4 v[2:5], v[178:179], off offset:528 nt
	global_load_dwordx4 v[10:13], v[178:179], off offset:512 nt
	v_lshl_add_u64 v[22:23], v[192:193], 2, s[18:19]
	s_nop 1
	v_mov_b32_e32 v22, v243
	v_lshlrev_b64 v[24:25], 12, v[192:193]
	v_lshl_add_u64 v[24:25], s[22:23], 0, v[24:25]
	v_lshl_add_u64 v[180:181], v[90:91], 1, v[24:25]
	s_waitcnt vmcnt(12)
	v_pk_mul_f32 v[26:27], v[22:23], v[162:163] op_sel_hi:[0,1]
	v_pk_mul_f32 v[24:25], v[22:23], v[160:161] op_sel_hi:[0,1]
	v_pk_mul_f32 v[30:31], v[22:23], v[166:167] op_sel_hi:[0,1]
	v_pk_mul_f32 v[28:29], v[22:23], v[164:165] op_sel_hi:[0,1]
	v_pk_mul_f32 v[160:161], v[22:23], v[172:173] op_sel_hi:[0,1]
	v_pk_mul_f32 v[32:33], v[22:23], v[168:169] op_sel_hi:[0,1]
	v_pk_mul_f32 v[162:163], v[22:23], v[174:175] op_sel_hi:[0,1]
	v_pk_mul_f32 v[164:165], v[22:23], v[170:171] op_sel_hi:[0,1]
	v_pk_fma_f32 v[24:25], v[86:87], v[24:25], v[44:45]
	v_pk_fma_f32 v[22:23], v[88:89], v[26:27], v[42:43]
	v_pk_fma_f32 v[28:29], v[92:93], v[28:29], v[40:41]
	v_pk_fma_f32 v[26:27], v[94:95], v[30:31], v[38:39]
	v_pk_fma_f32 v[32:33], v[104:105], v[32:33], v[36:37]
	v_pk_fma_f32 v[30:31], v[106:107], v[160:161], v[34:35]
	v_pk_fma_f32 v[8:9], v[110:111], v[164:165], v[8:9]
	v_pk_fma_f32 v[6:7], v[108:109], v[162:163], v[6:7]
	global_store_dwordx4 v[194:195], v[22:25], off nt
	global_store_dwordx4 v[194:195], v[26:29], off offset:16 nt
	v_mul_f32_e32 v164, v23, v23
	v_mul_f32_e32 v165, v25, v25
	v_mul_f32_e32 v166, v27, v27
	v_mul_f32_e32 v167, v29, v29
	v_pk_mul_f32 v[34:35], v[78:79], v[24:25]
	v_pk_mul_f32 v[38:39], v[82:83], v[28:29]
	v_pk_mul_f32 v[40:41], v[84:85], v[26:27]
	v_mul_f32_e32 v27, v31, v31
	v_mul_f32_e32 v29, v33, v33
	v_pk_mul_f32 v[36:37], v[80:81], v[22:23]
	v_mul_f32_e32 v168, v7, v7
	v_mul_f32_e32 v169, v9, v9
	v_fmac_f32_e32 v164, v22, v22
	v_fmac_f32_e32 v165, v24, v24
	v_fmac_f32_e32 v167, v28, v28
	v_cvt_pk_bf16_f32 v22, v36, v37
	v_cvt_pk_bf16_f32 v23, v34, v35
	v_fmac_f32_e32 v27, v30, v30
	v_fmac_f32_e32 v29, v32, v32
	v_lshlrev_b32_e32 v28, 16, v22
	v_and_b32_e32 v34, 0xffff0000, v22
	v_pk_mul_f32 v[160:161], v[100:101], v[8:9]
	v_pk_mul_f32 v[162:163], v[102:103], v[6:7]
	v_fmac_f32_e32 v166, v26, v26
	v_cvt_pk_bf16_f32 v24, v40, v41
	v_cvt_pk_bf16_f32 v25, v38, v39
	v_fmac_f32_e32 v168, v6, v6
	v_fmac_f32_e32 v169, v8, v8
	v_add_f32_e32 v26, v164, v165
	global_store_dwordx4 v[180:181], v[22:25], off
	v_lshlrev_b32_e32 v35, 16, v23
	v_and_b32_e32 v36, 0xffff0000, v23
	global_store_dwordx4 v[194:195], v[30:33], off offset:512 nt
	global_store_dwordx4 v[194:195], v[6:9], off offset:528 nt
	v_lshlrev_b32_e32 v37, 16, v24
	v_and_b32_e32 v38, 0xffff0000, v24
	v_add_f32_e32 v6, v27, v29
	v_max3_f32 v8, |v28|, 0, |v34|
	v_add_f32_e32 v7, v166, v26
	v_add_f32_e32 v6, v168, v6
	v_max3_f32 v8, v8, |v35|, |v36|
	v_lshlrev_b32_e32 v39, 16, v25
	v_and_b32_e32 v40, 0xffff0000, v25
	v_add_f32_e32 v7, v167, v7
	v_add_f32_e32 v6, v169, v6
	v_max3_f32 v8, v8, |v37|, |v38|
	v_pk_mul_f32 v[44:45], v[98:99], v[30:31]
	v_add_f32_e32 v6, v7, v6
	v_cvt_pk_bf16_f32 v22, v44, v45
	v_max3_f32 v7, v8, |v39|, |v40|
	v_lshlrev_b32_e32 v9, 16, v22
	v_and_b32_e32 v26, 0xffff0000, v22
	v_pk_mul_f32 v[42:43], v[96:97], v[32:33]
	v_max3_f32 v7, v7, |v9|, |v26|
	v_cvt_pk_bf16_f32 v23, v42, v43
	v_cvt_pk_bf16_f32 v24, v162, v163
	v_cvt_pk_bf16_f32 v25, v160, v161
	ds_bpermute_b32 v8, v233, v6
	v_lshlrev_b32_e32 v27, 16, v23
	v_and_b32_e32 v28, 0xffff0000, v23
	v_lshlrev_b32_e32 v29, 16, v24
	v_and_b32_e32 v30, 0xffff0000, v24
	v_max3_f32 v7, v7, |v27|, |v28|
	v_lshlrev_b32_e32 v31, 16, v25
	v_and_b32_e32 v32, 0xffff0000, v25
	v_max3_f32 v7, v7, |v29|, |v30|
	v_max3_f32 v9, v7, |v31|, |v32|
	ds_bpermute_b32 v26, v233, v9
	s_waitcnt lgkmcnt(1)
	v_add_f32_e32 v6, v6, v8
	ds_bpermute_b32 v7, v216, v6
	global_store_dwordx4 v[180:181], v[22:25], off offset:256
	s_waitcnt lgkmcnt(1)
	v_max_f32_e32 v8, v26, v26
	v_max_f32_e32 v8, v9, v8
	ds_bpermute_b32 v9, v216, v8
	s_and_saveexec_b64 s[44:45], s[0:1]
	s_cbranch_execz .LBB0_1766
	s_waitcnt lgkmcnt(0)
	v_max_f32_e32 v9, v9, v9
	v_max_f32_e32 v8, v8, v8
	v_add_f32_e32 v23, v6, v7
	v_lshlrev_b64 v[6:7], 7, v[192:193]
	v_max_f32_e32 v22, v8, v9
	v_lshl_add_u64 v[8:9], s[26:27], 0, v[6:7]
	s_lshl_b64 s[86:87], s[42:43], 2
	v_lshl_add_u64 v[6:7], s[28:29], 0, v[6:7]
	v_lshl_add_u64 v[8:9], v[8:9], 0, s[86:87]
	s_lshl_b32 s12, s65, 2
	v_lshl_add_u64 v[6:7], v[6:7], 0, s[86:87]
	v_lshl_add_u64 v[8:9], v[8:9], 0, s[12:13]
	v_lshl_add_u64 v[6:7], v[6:7], 0, s[12:13]
	global_store_dword v[8:9], v23, off
	global_store_dword v[6:7], v22, off
.LBB0_1766:
	s_or_b64 exec, exec, s[44:45]
	v_or_b32_e32 v36, 16, v176
	v_ashrrev_i32_e32 v37, 31, v36
	s_waitcnt lgkmcnt(1)
	v_lshlrev_b64 v[6:7], 13, v[36:37]
	v_lshl_add_u64 v[6:7], s[16:17], 0, v[6:7]
	v_lshl_add_u64 v[40:41], v[90:91], 2, v[6:7]
	global_load_dwordx4 v[26:29], v[40:41], off offset:16 nt
	global_load_dwordx4 v[30:33], v[40:41], off nt
	s_waitcnt lgkmcnt(0)
	global_load_dwordx4 v[6:9], v[40:41], off offset:528 nt
	global_load_dwordx4 v[22:25], v[40:41], off offset:512 nt
	s_nop 1
	v_mov_b32_e32 v34, v244
	v_lshlrev_b64 v[38:39], 12, v[176:177]
	v_lshl_add_u64 v[38:39], s[22:23], 0, v[38:39]
	v_lshl_add_u64 v[38:39], v[90:91], 1, v[38:39]
	s_waitcnt vmcnt(12)
	v_pk_mul_f32 v[44:45], v[34:35], v[128:129] op_sel_hi:[0,1]
	v_pk_mul_f32 v[128:129], v[34:35], v[150:151] op_sel_hi:[0,1]
	v_pk_mul_f32 v[42:43], v[34:35], v[146:147] op_sel_hi:[0,1]
	v_pk_mul_f32 v[146:147], v[34:35], v[148:149] op_sel_hi:[0,1]
	v_pk_mul_f32 v[148:149], v[34:35], v[156:157] op_sel_hi:[0,1]
	v_pk_mul_f32 v[150:151], v[34:35], v[152:153] op_sel_hi:[0,1]
	v_pk_fma_f32 v[14:15], v[94:95], v[128:129], v[14:15]
	v_pk_mul_f32 v[152:153], v[34:35], v[158:159] op_sel_hi:[0,1]
	v_pk_mul_f32 v[34:35], v[34:35], v[154:155] op_sel_hi:[0,1]
	v_pk_fma_f32 v[20:21], v[86:87], v[44:45], v[20:21]
	v_pk_fma_f32 v[18:19], v[88:89], v[42:43], v[18:19]
	v_pk_fma_f32 v[16:17], v[92:93], v[146:147], v[16:17]
	v_pk_fma_f32 v[12:13], v[104:105], v[150:151], v[12:13]
	v_pk_fma_f32 v[10:11], v[106:107], v[148:149], v[10:11]
	v_mul_f32_e32 v156, v15, v15
	v_pk_fma_f32 v[4:5], v[110:111], v[34:35], v[4:5]
	v_pk_fma_f32 v[2:3], v[108:109], v[152:153], v[2:3]
	global_store_dwordx4 v[178:179], v[18:21], off nt
	global_store_dwordx4 v[178:179], v[14:17], off offset:16 nt
	v_mul_f32_e32 v154, v19, v19
	v_mul_f32_e32 v155, v21, v21
	v_mul_f32_e32 v157, v17, v17
	v_pk_mul_f32 v[34:35], v[78:79], v[20:21]
	v_pk_mul_f32 v[42:43], v[80:81], v[18:19]
	v_pk_mul_f32 v[128:129], v[84:85], v[14:15]
	v_mul_f32_e32 v19, v11, v11
	v_mul_f32_e32 v21, v13, v13
	v_fmac_f32_e32 v156, v14, v14
	v_cvt_pk_bf16_f32 v14, v42, v43
	v_pk_mul_f32 v[44:45], v[82:83], v[16:17]
	v_mul_f32_e32 v158, v3, v3
	v_mul_f32_e32 v159, v5, v5
	v_fmac_f32_e32 v154, v18, v18
	v_fmac_f32_e32 v155, v20, v20
	v_fmac_f32_e32 v157, v16, v16
	v_cvt_pk_bf16_f32 v15, v34, v35
	v_cvt_pk_bf16_f32 v16, v128, v129
	v_cvt_pk_bf16_f32 v17, v44, v45
	v_fmac_f32_e32 v19, v10, v10
	v_fmac_f32_e32 v21, v12, v12
	global_store_dwordx4 v[38:39], v[14:17], off
	v_lshlrev_b32_e32 v20, 16, v14
	v_pk_mul_f32 v[150:151], v[100:101], v[4:5]
	v_and_b32_e32 v14, 0xffff0000, v14
	v_pk_mul_f32 v[152:153], v[102:103], v[2:3]
	v_fmac_f32_e32 v158, v2, v2
	v_fmac_f32_e32 v159, v4, v4
	v_add_f32_e32 v18, v154, v155
	v_lshlrev_b32_e32 v34, 16, v15
	v_and_b32_e32 v15, 0xffff0000, v15
	global_store_dwordx4 v[178:179], v[10:13], off offset:512 nt
	global_store_dwordx4 v[178:179], v[2:5], off offset:528 nt
	v_lshlrev_b32_e32 v35, 16, v16
	v_and_b32_e32 v16, 0xffff0000, v16
	v_add_f32_e32 v2, v19, v21
	v_max3_f32 v4, |v20|, 0, |v14|
	v_add_f32_e32 v3, v156, v18
	v_add_f32_e32 v2, v158, v2
	v_max3_f32 v4, v4, |v34|, |v15|
	v_lshlrev_b32_e32 v42, 16, v17
	v_and_b32_e32 v17, 0xffff0000, v17
	v_add_f32_e32 v3, v157, v3
	v_add_f32_e32 v2, v159, v2
	v_max3_f32 v4, v4, |v35|, |v16|
	v_pk_mul_f32 v[148:149], v[98:99], v[10:11]
	v_add_f32_e32 v2, v3, v2
	v_cvt_pk_bf16_f32 v10, v148, v149
	v_max3_f32 v3, v4, |v42|, |v17|
	v_lshlrev_b32_e32 v5, 16, v10
	v_and_b32_e32 v14, 0xffff0000, v10
	v_pk_mul_f32 v[146:147], v[96:97], v[12:13]
	v_max3_f32 v3, v3, |v5|, |v14|
	v_cvt_pk_bf16_f32 v11, v146, v147
	v_cvt_pk_bf16_f32 v12, v152, v153
	v_cvt_pk_bf16_f32 v13, v150, v151
	ds_bpermute_b32 v4, v233, v2
	v_lshlrev_b32_e32 v18, 16, v11
	v_and_b32_e32 v19, 0xffff0000, v11
	v_lshlrev_b32_e32 v20, 16, v12
	v_and_b32_e32 v21, 0xffff0000, v12
	v_max3_f32 v3, v3, |v18|, |v19|
	v_lshlrev_b32_e32 v43, 16, v13
	v_and_b32_e32 v44, 0xffff0000, v13
	v_max3_f32 v3, v3, |v20|, |v21|
	v_max3_f32 v5, v3, |v43|, |v44|
	ds_bpermute_b32 v14, v233, v5
	s_waitcnt lgkmcnt(1)
	v_add_f32_e32 v2, v2, v4
	ds_bpermute_b32 v3, v216, v2
	global_store_dwordx4 v[38:39], v[10:13], off offset:256
	s_waitcnt lgkmcnt(1)
	v_max_f32_e32 v4, v14, v14
	v_max_f32_e32 v4, v5, v4
	ds_bpermute_b32 v5, v216, v4
	s_and_saveexec_b64 s[44:45], s[0:1]
	s_cbranch_execz .LBB0_1768
	s_waitcnt lgkmcnt(0)
	v_max_f32_e32 v5, v5, v5
	v_max_f32_e32 v4, v4, v4
	v_add_f32_e32 v11, v2, v3
	v_lshlrev_b64 v[2:3], 7, v[176:177]
	v_max_f32_e32 v10, v4, v5
	v_lshl_add_u64 v[4:5], s[26:27], 0, v[2:3]
	s_lshl_b64 s[86:87], s[42:43], 2
	v_lshl_add_u64 v[2:3], s[28:29], 0, v[2:3]
	v_lshl_add_u64 v[4:5], v[4:5], 0, s[86:87]
	s_lshl_b32 s12, s65, 2
	v_lshl_add_u64 v[2:3], v[2:3], 0, s[86:87]
	v_lshl_add_u64 v[4:5], v[4:5], 0, s[12:13]
	v_lshl_add_u64 v[2:3], v[2:3], 0, s[12:13]
	global_store_dword v[4:5], v11, off
	global_store_dword v[2:3], v10, off
.LBB0_1768:
	s_or_b64 exec, exec, s[44:45]
	v_or_b32_e32 v34, 32, v176
	v_ashrrev_i32_e32 v35, 31, v34
	s_waitcnt lgkmcnt(1)
	v_lshlrev_b64 v[2:3], 13, v[34:35]
	v_lshl_add_u64 v[2:3], s[16:17], 0, v[2:3]
	v_lshl_add_u64 v[38:39], v[90:91], 2, v[2:3]
	global_load_dwordx4 v[14:17], v[38:39], off offset:16 nt
	global_load_dwordx4 v[18:21], v[38:39], off nt
	s_waitcnt lgkmcnt(0)
	global_load_dwordx4 v[2:5], v[38:39], off offset:528 nt
	global_load_dwordx4 v[10:13], v[38:39], off offset:512 nt
	v_lshl_add_u64 v[42:43], v[36:37], 2, s[18:19]
	s_nop 1
	v_mov_b32_e32 v42, v245
	v_lshlrev_b64 v[44:45], 12, v[36:37]
	v_lshl_add_u64 v[44:45], s[22:23], 0, v[44:45]
	v_lshl_add_u64 v[44:45], v[90:91], 1, v[44:45]
	s_waitcnt vmcnt(12)
	v_pk_mul_f32 v[118:119], v[42:43], v[118:119] op_sel_hi:[0,1]
	v_pk_mul_f32 v[114:115], v[42:43], v[114:115] op_sel_hi:[0,1]
	v_pk_mul_f32 v[112:113], v[42:43], v[112:113] op_sel_hi:[0,1]
	v_pk_mul_f32 v[116:117], v[42:43], v[116:117] op_sel_hi:[0,1]
	v_pk_mul_f32 v[124:125], v[42:43], v[124:125] op_sel_hi:[0,1]
	v_pk_mul_f32 v[120:121], v[42:43], v[120:121] op_sel_hi:[0,1]
	v_pk_fma_f32 v[26:27], v[94:95], v[118:119], v[26:27]
	v_pk_mul_f32 v[126:127], v[42:43], v[126:127] op_sel_hi:[0,1]
	v_pk_mul_f32 v[42:43], v[42:43], v[122:123] op_sel_hi:[0,1]
	v_pk_fma_f32 v[32:33], v[86:87], v[112:113], v[32:33]
	v_pk_fma_f32 v[30:31], v[88:89], v[114:115], v[30:31]
	v_pk_fma_f32 v[28:29], v[92:93], v[116:117], v[28:29]
	v_pk_fma_f32 v[24:25], v[104:105], v[120:121], v[24:25]
	v_pk_fma_f32 v[22:23], v[106:107], v[124:125], v[22:23]
	v_mul_f32_e32 v128, v27, v27
	v_pk_fma_f32 v[8:9], v[110:111], v[42:43], v[8:9]
	v_pk_fma_f32 v[6:7], v[108:109], v[126:127], v[6:7]
	global_store_dwordx4 v[40:41], v[30:33], off nt
	global_store_dwordx4 v[40:41], v[26:29], off offset:16 nt
	v_mul_f32_e32 v126, v31, v31
	v_mul_f32_e32 v127, v33, v33
	v_mul_f32_e32 v129, v29, v29
	v_pk_mul_f32 v[42:43], v[78:79], v[32:33]
	v_pk_mul_f32 v[112:113], v[80:81], v[30:31]
	v_pk_mul_f32 v[116:117], v[84:85], v[26:27]
	v_mul_f32_e32 v31, v23, v23
	v_mul_f32_e32 v33, v25, v25
	v_fmac_f32_e32 v128, v26, v26
	v_cvt_pk_bf16_f32 v26, v112, v113
	v_pk_mul_f32 v[114:115], v[82:83], v[28:29]
	v_mul_f32_e32 v146, v7, v7
	v_mul_f32_e32 v147, v9, v9
	v_fmac_f32_e32 v126, v30, v30
	v_fmac_f32_e32 v127, v32, v32
	v_fmac_f32_e32 v129, v28, v28
	v_cvt_pk_bf16_f32 v27, v42, v43
	v_cvt_pk_bf16_f32 v28, v116, v117
	v_cvt_pk_bf16_f32 v29, v114, v115
	v_fmac_f32_e32 v31, v22, v22
	v_fmac_f32_e32 v33, v24, v24
	global_store_dwordx4 v[44:45], v[26:29], off
	v_lshlrev_b32_e32 v32, 16, v26
	v_pk_mul_f32 v[122:123], v[100:101], v[8:9]
	v_and_b32_e32 v26, 0xffff0000, v26
	v_pk_mul_f32 v[124:125], v[102:103], v[6:7]
	v_fmac_f32_e32 v146, v6, v6
	v_fmac_f32_e32 v147, v8, v8
	v_add_f32_e32 v30, v126, v127
	v_lshlrev_b32_e32 v42, 16, v27
	v_and_b32_e32 v27, 0xffff0000, v27
	global_store_dwordx4 v[40:41], v[22:25], off offset:512 nt
	global_store_dwordx4 v[40:41], v[6:9], off offset:528 nt
	v_lshlrev_b32_e32 v43, 16, v28
	v_and_b32_e32 v28, 0xffff0000, v28
	v_add_f32_e32 v6, v31, v33
	v_max3_f32 v8, |v32|, 0, |v26|
	v_add_f32_e32 v7, v128, v30
	v_add_f32_e32 v6, v146, v6
	v_max3_f32 v8, v8, |v42|, |v27|
	v_lshlrev_b32_e32 v112, 16, v29
	v_and_b32_e32 v29, 0xffff0000, v29
	v_add_f32_e32 v7, v129, v7
	v_add_f32_e32 v6, v147, v6
	v_max3_f32 v8, v8, |v43|, |v28|
	v_pk_mul_f32 v[120:121], v[98:99], v[22:23]
	v_add_f32_e32 v6, v7, v6
	v_cvt_pk_bf16_f32 v22, v120, v121
	v_max3_f32 v7, v8, |v112|, |v29|
	v_lshlrev_b32_e32 v9, 16, v22
	v_and_b32_e32 v26, 0xffff0000, v22
	v_pk_mul_f32 v[118:119], v[96:97], v[24:25]
	v_max3_f32 v7, v7, |v9|, |v26|
	v_cvt_pk_bf16_f32 v23, v118, v119
	v_cvt_pk_bf16_f32 v24, v124, v125
	v_cvt_pk_bf16_f32 v25, v122, v123
	ds_bpermute_b32 v8, v233, v6
	v_lshlrev_b32_e32 v30, 16, v23
	v_and_b32_e32 v31, 0xffff0000, v23
	v_lshlrev_b32_e32 v32, 16, v24
	v_and_b32_e32 v33, 0xffff0000, v24
	v_max3_f32 v7, v7, |v30|, |v31|
	v_lshlrev_b32_e32 v40, 16, v25
	v_and_b32_e32 v41, 0xffff0000, v25
	v_max3_f32 v7, v7, |v32|, |v33|
	v_max3_f32 v9, v7, |v40|, |v41|
	ds_bpermute_b32 v26, v233, v9
	s_waitcnt lgkmcnt(1)
	v_add_f32_e32 v6, v6, v8
	ds_bpermute_b32 v7, v216, v6
	global_store_dwordx4 v[44:45], v[22:25], off offset:256
	s_waitcnt lgkmcnt(1)
	v_max_f32_e32 v8, v26, v26
	v_max_f32_e32 v8, v9, v8
	ds_bpermute_b32 v9, v216, v8
	s_and_saveexec_b64 s[44:45], s[0:1]
	s_cbranch_execz .LBB0_1770
	s_waitcnt lgkmcnt(0)
	v_max_f32_e32 v9, v9, v9
	v_max_f32_e32 v8, v8, v8
	v_add_f32_e32 v23, v6, v7
	v_lshlrev_b64 v[6:7], 7, v[36:37]
	v_max_f32_e32 v22, v8, v9
	v_lshl_add_u64 v[8:9], s[26:27], 0, v[6:7]
	s_lshl_b64 s[86:87], s[42:43], 2
	v_lshl_add_u64 v[6:7], s[28:29], 0, v[6:7]
	v_lshl_add_u64 v[8:9], v[8:9], 0, s[86:87]
	s_lshl_b32 s12, s65, 2
	v_lshl_add_u64 v[6:7], v[6:7], 0, s[86:87]
	v_lshl_add_u64 v[8:9], v[8:9], 0, s[12:13]
	v_lshl_add_u64 v[6:7], v[6:7], 0, s[12:13]
	global_store_dword v[8:9], v23, off
	global_store_dword v[6:7], v22, off
.LBB0_1770:
	s_or_b64 exec, exec, s[44:45]
	v_or_b32_e32 v36, 48, v176
	v_ashrrev_i32_e32 v37, 31, v36
	s_waitcnt lgkmcnt(1)
	v_lshlrev_b64 v[6:7], 13, v[36:37]
	v_lshl_add_u64 v[6:7], s[16:17], 0, v[6:7]
	v_lshl_add_u64 v[40:41], v[90:91], 2, v[6:7]
	global_load_dwordx4 v[26:29], v[40:41], off offset:16 nt
	global_load_dwordx4 v[30:33], v[40:41], off nt
	s_waitcnt lgkmcnt(0)
	global_load_dwordx4 v[6:9], v[40:41], off offset:528 nt
	global_load_dwordx4 v[22:25], v[40:41], off offset:512 nt
	v_lshl_add_u64 v[42:43], v[34:35], 2, s[18:19]
	s_nop 1
	v_mov_b32_e32 v42, v246
	v_lshlrev_b64 v[44:45], 12, v[34:35]
	v_lshl_add_u64 v[44:45], s[22:23], 0, v[44:45]
	v_lshl_add_u64 v[44:45], v[90:91], 1, v[44:45]
	s_waitcnt vmcnt(12)
	v_pk_mul_f32 v[68:69], v[42:43], v[68:69] op_sel_hi:[0,1]
	v_pk_mul_f32 v[64:65], v[42:43], v[64:65] op_sel_hi:[0,1]
	v_pk_mul_f32 v[62:63], v[42:43], v[62:63] op_sel_hi:[0,1]
	v_pk_mul_f32 v[66:67], v[42:43], v[66:67] op_sel_hi:[0,1]
	v_pk_mul_f32 v[74:75], v[42:43], v[74:75] op_sel_hi:[0,1]
	v_pk_mul_f32 v[70:71], v[42:43], v[70:71] op_sel_hi:[0,1]
	v_pk_fma_f32 v[14:15], v[94:95], v[68:69], v[14:15]
	v_pk_mul_f32 v[76:77], v[42:43], v[76:77] op_sel_hi:[0,1]
	v_pk_mul_f32 v[42:43], v[42:43], v[72:73] op_sel_hi:[0,1]
	v_pk_fma_f32 v[20:21], v[86:87], v[62:63], v[20:21]
	v_pk_fma_f32 v[18:19], v[88:89], v[64:65], v[18:19]
	v_pk_fma_f32 v[16:17], v[92:93], v[66:67], v[16:17]
	v_pk_fma_f32 v[12:13], v[104:105], v[70:71], v[12:13]
	v_pk_fma_f32 v[10:11], v[106:107], v[74:75], v[10:11]
	v_mul_f32_e32 v112, v15, v15
	v_pk_fma_f32 v[4:5], v[110:111], v[42:43], v[4:5]
	v_pk_fma_f32 v[2:3], v[108:109], v[76:77], v[2:3]
	global_store_dwordx4 v[38:39], v[18:21], off nt
	global_store_dwordx4 v[38:39], v[14:17], off offset:16 nt
	v_mul_f32_e32 v76, v19, v19
	v_mul_f32_e32 v77, v21, v21
	v_mul_f32_e32 v113, v17, v17
	v_pk_mul_f32 v[42:43], v[78:79], v[20:21]
	v_pk_mul_f32 v[62:63], v[80:81], v[18:19]
	v_pk_mul_f32 v[66:67], v[84:85], v[14:15]
	v_mul_f32_e32 v19, v11, v11
	v_mul_f32_e32 v21, v13, v13
	v_fmac_f32_e32 v112, v14, v14
	v_cvt_pk_bf16_f32 v14, v62, v63
	v_pk_mul_f32 v[64:65], v[82:83], v[16:17]
	v_mul_f32_e32 v114, v3, v3
	v_mul_f32_e32 v115, v5, v5
	v_fmac_f32_e32 v76, v18, v18
	v_fmac_f32_e32 v77, v20, v20
	v_fmac_f32_e32 v113, v16, v16
	v_cvt_pk_bf16_f32 v15, v42, v43
	v_cvt_pk_bf16_f32 v16, v66, v67
	v_cvt_pk_bf16_f32 v17, v64, v65
	v_fmac_f32_e32 v19, v10, v10
	v_fmac_f32_e32 v21, v12, v12
	global_store_dwordx4 v[44:45], v[14:17], off
	v_lshlrev_b32_e32 v20, 16, v14
	v_pk_mul_f32 v[72:73], v[100:101], v[4:5]
	v_and_b32_e32 v14, 0xffff0000, v14
	v_pk_mul_f32 v[74:75], v[102:103], v[2:3]
	v_fmac_f32_e32 v114, v2, v2
	v_fmac_f32_e32 v115, v4, v4
	v_add_f32_e32 v18, v76, v77
	v_lshlrev_b32_e32 v42, 16, v15
	v_and_b32_e32 v15, 0xffff0000, v15
	global_store_dwordx4 v[38:39], v[10:13], off offset:512 nt
	global_store_dwordx4 v[38:39], v[2:5], off offset:528 nt
	v_lshlrev_b32_e32 v43, 16, v16
	v_and_b32_e32 v16, 0xffff0000, v16
	v_add_f32_e32 v2, v19, v21
	v_max3_f32 v4, |v20|, 0, |v14|
	v_add_f32_e32 v3, v112, v18
	v_add_f32_e32 v2, v114, v2
	v_max3_f32 v4, v4, |v42|, |v15|
	v_lshlrev_b32_e32 v62, 16, v17
	v_and_b32_e32 v17, 0xffff0000, v17
	v_add_f32_e32 v3, v113, v3
	v_add_f32_e32 v2, v115, v2
	v_max3_f32 v4, v4, |v43|, |v16|
	v_pk_mul_f32 v[70:71], v[98:99], v[10:11]
	v_add_f32_e32 v2, v3, v2
	v_cvt_pk_bf16_f32 v10, v70, v71
	v_max3_f32 v3, v4, |v62|, |v17|
	v_lshlrev_b32_e32 v5, 16, v10
	v_and_b32_e32 v14, 0xffff0000, v10
	v_pk_mul_f32 v[68:69], v[96:97], v[12:13]
	v_max3_f32 v3, v3, |v5|, |v14|
	v_cvt_pk_bf16_f32 v11, v68, v69
	v_cvt_pk_bf16_f32 v12, v74, v75
	v_cvt_pk_bf16_f32 v13, v72, v73
	ds_bpermute_b32 v4, v233, v2
	v_lshlrev_b32_e32 v18, 16, v11
	v_and_b32_e32 v19, 0xffff0000, v11
	v_lshlrev_b32_e32 v20, 16, v12
	v_and_b32_e32 v21, 0xffff0000, v12
	v_max3_f32 v3, v3, |v18|, |v19|
	v_lshlrev_b32_e32 v38, 16, v13
	v_and_b32_e32 v39, 0xffff0000, v13
	v_max3_f32 v3, v3, |v20|, |v21|
	v_max3_f32 v5, v3, |v38|, |v39|
	ds_bpermute_b32 v14, v233, v5
	s_waitcnt lgkmcnt(1)
	v_add_f32_e32 v2, v2, v4
	ds_bpermute_b32 v3, v216, v2
	global_store_dwordx4 v[44:45], v[10:13], off offset:256
	s_waitcnt lgkmcnt(1)
	v_max_f32_e32 v4, v14, v14
	v_max_f32_e32 v4, v5, v4
	ds_bpermute_b32 v5, v216, v4
	s_and_saveexec_b64 s[44:45], s[0:1]
	s_cbranch_execz .LBB0_1772
	s_waitcnt lgkmcnt(0)
	v_max_f32_e32 v5, v5, v5
	v_max_f32_e32 v4, v4, v4
	v_add_f32_e32 v11, v2, v3
	v_lshlrev_b64 v[2:3], 7, v[34:35]
	v_max_f32_e32 v10, v4, v5
	v_lshl_add_u64 v[4:5], s[26:27], 0, v[2:3]
	s_lshl_b64 s[86:87], s[42:43], 2
	v_lshl_add_u64 v[2:3], s[28:29], 0, v[2:3]
	v_lshl_add_u64 v[4:5], v[4:5], 0, s[86:87]
	s_lshl_b32 s12, s65, 2
	v_lshl_add_u64 v[2:3], v[2:3], 0, s[86:87]
	v_lshl_add_u64 v[4:5], v[4:5], 0, s[12:13]
	v_lshl_add_u64 v[2:3], v[2:3], 0, s[12:13]
	global_store_dword v[4:5], v11, off
	global_store_dword v[2:3], v10, off
.LBB0_1772:
	s_or_b64 exec, exec, s[44:45]
	s_waitcnt lgkmcnt(1)
	v_lshl_add_u64 v[2:3], v[36:37], 2, s[18:19]
	s_nop 1
	v_mov_b32_e32 v2, v247
	s_waitcnt lgkmcnt(0)
	v_lshlrev_b64 v[4:5], 12, v[36:37]
	v_lshl_add_u64 v[4:5], s[22:23], 0, v[4:5]
	v_lshl_add_u64 v[18:19], v[90:91], 1, v[4:5]
	s_waitcnt vmcnt(8)
	v_pk_mul_f32 v[10:11], v[2:3], v[48:49] op_sel_hi:[0,1]
	v_pk_mul_f32 v[4:5], v[2:3], v[46:47] op_sel_hi:[0,1]
	v_pk_mul_f32 v[14:15], v[2:3], v[52:53] op_sel_hi:[0,1]
	v_pk_mul_f32 v[12:13], v[2:3], v[50:51] op_sel_hi:[0,1]
	v_pk_mul_f32 v[20:21], v[2:3], v[58:59] op_sel_hi:[0,1]
	v_pk_mul_f32 v[16:17], v[2:3], v[54:55] op_sel_hi:[0,1]
	v_pk_mul_f32 v[34:35], v[2:3], v[60:61] op_sel_hi:[0,1]
	v_pk_mul_f32 v[38:39], v[2:3], v[56:57] op_sel_hi:[0,1]
	v_pk_fma_f32 v[2:3], v[88:89], v[10:11], v[30:31]
	v_pk_fma_f32 v[4:5], v[86:87], v[4:5], v[32:33]
	v_pk_fma_f32 v[12:13], v[92:93], v[12:13], v[28:29]
	v_pk_fma_f32 v[8:9], v[110:111], v[38:39], v[8:9]
	v_mul_f32_e32 v38, v3, v3
	v_pk_fma_f32 v[10:11], v[94:95], v[14:15], v[26:27]
	v_pk_fma_f32 v[14:15], v[106:107], v[20:21], v[22:23]
	global_store_dwordx4 v[40:41], v[2:5], off nt
	global_store_dwordx4 v[40:41], v[10:13], off offset:16 nt
	v_mul_f32_e32 v39, v5, v5
	v_mul_f32_e32 v43, v13, v13
	v_pk_mul_f32 v[22:23], v[80:81], v[2:3]
	v_fmac_f32_e32 v38, v2, v2
	v_cvt_pk_bf16_f32 v2, v22, v23
	v_pk_fma_f32 v[16:17], v[104:105], v[16:17], v[24:25]
	v_pk_mul_f32 v[20:21], v[78:79], v[4:5]
	v_pk_mul_f32 v[24:25], v[82:83], v[12:13]
	v_pk_mul_f32 v[26:27], v[84:85], v[10:11]
	v_fmac_f32_e32 v39, v4, v4
	v_fmac_f32_e32 v43, v12, v12
	v_cvt_pk_bf16_f32 v3, v20, v21
	v_cvt_pk_bf16_f32 v4, v26, v27
	v_cvt_pk_bf16_f32 v5, v24, v25
	global_store_dwordx4 v[18:19], v[2:5], off
	v_lshlrev_b32_e32 v12, 16, v2
	v_lshlrev_b32_e32 v20, 16, v3
	v_and_b32_e32 v2, 0xffff0000, v2
	v_and_b32_e32 v3, 0xffff0000, v3
	v_max3_f32 v2, |v12|, 0, |v2|
	v_pk_fma_f32 v[6:7], v[108:109], v[34:35], v[6:7]
	v_mul_f32_e32 v42, v11, v11
	v_mul_f32_e32 v11, v15, v15
	v_mul_f32_e32 v13, v17, v17
	v_lshlrev_b32_e32 v21, 16, v4
	v_and_b32_e32 v4, 0xffff0000, v4
	v_max3_f32 v2, v2, |v20|, |v3|
	v_mul_f32_e32 v44, v7, v7
	v_fmac_f32_e32 v11, v14, v14
	v_fmac_f32_e32 v13, v16, v16
	v_lshlrev_b32_e32 v22, 16, v5
	v_and_b32_e32 v5, 0xffff0000, v5
	v_max3_f32 v2, v2, |v21|, |v4|
	v_pk_mul_f32 v[30:31], v[98:99], v[14:15]
	v_pk_mul_f32 v[34:35], v[102:103], v[6:7]
	v_fmac_f32_e32 v44, v6, v6
	global_store_dwordx4 v[40:41], v[14:17], off offset:512 nt
	global_store_dwordx4 v[40:41], v[6:9], off offset:528 nt
	v_add_f32_e32 v11, v11, v13
	v_max3_f32 v2, v2, |v22|, |v5|
	v_cvt_pk_bf16_f32 v6, v30, v31
	v_mul_f32_e32 v45, v9, v9
	v_lshlrev_b32_e32 v12, 16, v6
	v_and_b32_e32 v13, 0xffff0000, v6
	v_pk_mul_f32 v[28:29], v[96:97], v[16:17]
	v_fmac_f32_e32 v42, v10, v10
	v_add_f32_e32 v10, v38, v39
	v_cvt_pk_bf16_f32 v7, v28, v29
	v_max3_f32 v2, v2, |v12|, |v13|
	v_lshlrev_b32_e32 v14, 16, v7
	v_and_b32_e32 v15, 0xffff0000, v7
	v_pk_mul_f32 v[32:33], v[100:101], v[8:9]
	v_fmac_f32_e32 v45, v8, v8
	v_cvt_pk_bf16_f32 v8, v34, v35
	v_add_f32_e32 v10, v42, v10
	v_add_f32_e32 v11, v44, v11
	v_lshlrev_b32_e32 v16, 16, v8
	v_and_b32_e32 v17, 0xffff0000, v8
	v_max3_f32 v2, v2, |v14|, |v15|
	v_cvt_pk_bf16_f32 v9, v32, v33
	v_add_f32_e32 v10, v43, v10
	v_lshlrev_b32_e32 v23, 16, v9
	v_and_b32_e32 v24, 0xffff0000, v9
	v_add_f32_e32 v3, v45, v11
	v_max3_f32 v2, v2, |v16|, |v17|
	v_add_f32_e32 v3, v10, v3
	v_max3_f32 v5, v2, |v23|, |v24|
	ds_bpermute_b32 v4, v233, v3
	ds_bpermute_b32 v10, v233, v5
	global_store_dwordx4 v[18:19], v[6:9], off offset:256
	s_waitcnt lgkmcnt(1)
	v_add_f32_e32 v2, v3, v4
	s_waitcnt lgkmcnt(0)
	v_max_f32_e32 v4, v10, v10
	v_max_f32_e32 v4, v5, v4
	ds_bpermute_b32 v3, v216, v2
	ds_bpermute_b32 v5, v216, v4
	s_and_saveexec_b64 s[44:45], s[0:1]
	s_cbranch_execz .LBB0_1774
	s_waitcnt lgkmcnt(0)
	v_max_f32_e32 v5, v5, v5
	v_max_f32_e32 v4, v4, v4
	v_add_f32_e32 v7, v2, v3
	v_lshlrev_b64 v[2:3], 7, v[36:37]
	v_max_f32_e32 v6, v4, v5
	v_lshl_add_u64 v[4:5], s[26:27], 0, v[2:3]
	s_lshl_b64 s[42:43], s[42:43], 2
	v_lshl_add_u64 v[2:3], s[28:29], 0, v[2:3]
	v_lshl_add_u64 v[4:5], v[4:5], 0, s[42:43]
	s_lshl_b32 s12, s65, 2
	v_lshl_add_u64 v[2:3], v[2:3], 0, s[42:43]
	v_lshl_add_u64 v[4:5], v[4:5], 0, s[12:13]
	v_lshl_add_u64 v[2:3], v[2:3], 0, s[12:13]
	global_store_dword v[4:5], v7, off
	global_store_dword v[2:3], v6, off

.LBB0_2768:
	s_lshr_b32 s40, s81, 4
	s_add_i32 s40, s40, -1
	s_cmp_gt_i32 s81, 31
	s_cselect_b32 s40, s40, 0
	v_lshl_or_b32 v90, s12, 8, v230
	s_mul_i32 s43, s40, 0xc000
	s_mul_hi_i32 s42, s40, 0xc000
	s_add_u32 s40, s57, s43
	v_ashrrev_i32_e32 v91, 31, v90
	s_addc_u32 s41, s58, s42
	v_lshlrev_b64 v[36:37], 2, v[90:91]
	v_lshl_add_u64 v[26:27], s[40:41], 0, v[36:37]
	v_lshl_add_u64 v[28:29], s[20:21], 0, v[36:37]
	s_waitcnt lgkmcnt(0)
	global_load_dwordx4 v[2:5], v[26:27], off offset:16
	global_load_dwordx4 v[6:9], v[26:27], off
	global_load_dwordx4 v[10:13], v[28:29], off offset:16
	global_load_dwordx4 v[14:17], v[28:29], off
	s_add_u32 s40, s59, s43
	v_lshl_add_u64 v[30:31], s[24:25], 0, v[36:37]
	s_addc_u32 s41, s60, s42
	v_lshl_add_u64 v[32:33], s[40:41], 0, v[36:37]
	v_lshl_add_u32 v210, s81, 8, v228
	v_ashrrev_i32_e32 v211, 31, v210
	v_or_b32_e32 v34, 16, v210
	v_ashrrev_i32_e32 v35, 31, v34
	s_lshl_b32 s40, s12, 2
	s_ashr_i32 s41, s40, 31
	s_waitcnt vmcnt(0)
	v_pk_mul_f32 v[92:93], v[4:5], v[12:13]
	v_pk_mul_f32 v[86:87], v[8:9], v[16:17]
	v_pk_mul_f32 v[88:89], v[6:7], v[14:15]
	global_load_dwordx4 v[6:9], v[30:31], off offset:16
	global_load_dwordx4 v[14:17], v[30:31], off
	global_load_dwordx4 v[18:21], v[32:33], off offset:16
	global_load_dwordx4 v[22:25], v[32:33], off
	v_pk_mul_f32 v[94:95], v[2:3], v[10:11]
	s_waitcnt vmcnt(0)
	v_pk_add_f32 v[2:3], v[20:21], 1.0 op_sel_hi:[1,0]
	v_pk_add_f32 v[24:25], v[24:25], 1.0 op_sel_hi:[1,0]
	v_pk_add_f32 v[22:23], v[22:23], 1.0 op_sel_hi:[1,0]
	v_pk_add_f32 v[4:5], v[18:19], 1.0 op_sel_hi:[1,0]
	v_pk_mul_f32 v[78:79], v[16:17], v[24:25]
	v_pk_mul_f32 v[80:81], v[14:15], v[22:23]
	v_pk_mul_f32 v[82:83], v[8:9], v[2:3]
	v_pk_mul_f32 v[84:85], v[6:7], v[4:5]
	global_load_dwordx4 v[2:5], v[26:27], off offset:528
	global_load_dwordx4 v[6:9], v[26:27], off offset:512
	global_load_dwordx4 v[10:13], v[28:29], off offset:528
	global_load_dwordx4 v[14:17], v[28:29], off offset:512
	s_waitcnt vmcnt(0)
	v_pk_mul_f32 v[108:109], v[2:3], v[10:11]
	v_pk_mul_f32 v[104:105], v[8:9], v[16:17]
	v_pk_mul_f32 v[106:107], v[6:7], v[14:15]
	global_load_dwordx4 v[6:9], v[30:31], off offset:528
	global_load_dwordx4 v[14:17], v[30:31], off offset:512
	global_load_dwordx4 v[18:21], v[32:33], off offset:528
	global_load_dwordx4 v[22:25], v[32:33], off offset:512
	v_pk_mul_f32 v[110:111], v[4:5], v[12:13]
	s_waitcnt vmcnt(0)
	v_pk_add_f32 v[2:3], v[20:21], 1.0 op_sel_hi:[1,0]
	s_nop 0
	v_pk_mul_f32 v[100:101], v[8:9], v[2:3]
	v_lshlrev_b64 v[2:3], 13, v[210:211]
	v_lshl_add_u64 v[2:3], s[16:17], 0, v[2:3]
	v_lshl_add_u64 v[38:39], v[2:3], 0, v[36:37]
	v_lshlrev_b64 v[2:3], 13, v[34:35]
	v_lshl_add_u64 v[2:3], s[16:17], 0, v[2:3]
	v_pk_add_f32 v[24:25], v[24:25], 1.0 op_sel_hi:[1,0]
	v_pk_add_f32 v[22:23], v[22:23], 1.0 op_sel_hi:[1,0]
	v_pk_add_f32 v[4:5], v[18:19], 1.0 op_sel_hi:[1,0]
	v_lshl_add_u64 v[36:37], v[2:3], 0, v[36:37]
	v_pk_mul_f32 v[96:97], v[16:17], v[24:25]
	v_pk_mul_f32 v[98:99], v[14:15], v[22:23]
	v_pk_mul_f32 v[102:103], v[6:7], v[4:5]
	v_lshl_add_u64 v[196:197], v[210:211], 2, s[18:19]
	global_load_dword v240, v[196:197], off
	global_load_dword v241, v[196:197], off offset:64
	global_load_dword v242, v[196:197], off offset:128
	global_load_dword v243, v[196:197], off offset:192
	global_load_dword v244, v[196:197], off offset:512
	global_load_dword v245, v[196:197], off offset:576
	global_load_dword v246, v[196:197], off offset:640
	global_load_dword v247, v[196:197], off offset:704
	global_load_dwordx4 v[22:25], v[38:39], off offset:16 nt
	global_load_dwordx4 v[30:33], v[38:39], off nt
	global_load_dwordx4 v[18:21], v[38:39], off offset:528 nt
	global_load_dwordx4 v[26:29], v[38:39], off offset:512 nt
	global_load_dwordx4 v[10:13], v[36:37], off offset:16 nt
	global_load_dwordx4 v[14:17], v[36:37], off nt
	global_load_dwordx4 v[2:5], v[36:37], off offset:528 nt
	global_load_dwordx4 v[6:9], v[36:37], off offset:512 nt
	v_lshl_add_u64 v[196:197], v[210:211], 2, s[18:19]
	s_nop 0
	v_and_b32_e32 v44, 64, v232
	v_xor_b32_e32 v41, 16, v232
	v_add_u32_e32 v234, 64, v44
	v_cmp_lt_i32_e32 vcc, v41, v234
	v_lshlrev_b64 v[42:43], 12, v[210:211]
	v_lshl_add_u64 v[42:43], s[22:23], 0, v[42:43]
	v_cndmask_b32_e32 v41, v232, v41, vcc
	v_lshlrev_b32_e32 v233, 2, v41
	v_lshl_add_u64 v[42:43], v[90:91], 1, v[42:43]
	s_waitcnt vmcnt(4)
	v_mov_b32_e32 v40, v240
	v_pk_mul_f32 v[44:45], v[40:41], v[214:215] op_sel_hi:[0,1]
	v_pk_mul_f32 v[212:213], v[40:41], v[212:213] op_sel_hi:[0,1]
	v_pk_mul_f32 v[214:215], v[40:41], v[218:219] op_sel_hi:[0,1]
	v_pk_mul_f32 v[218:219], v[40:41], v[222:223] op_sel_hi:[0,1]
	v_pk_mul_f32 v[220:221], v[40:41], v[220:221] op_sel_hi:[0,1]
	v_pk_mul_f32 v[216:217], v[40:41], v[216:217] op_sel_hi:[0,1]
	v_pk_mul_f32 v[222:223], v[40:41], v[226:227] op_sel_hi:[0,1]
	v_pk_mul_f32 v[40:41], v[40:41], v[224:225] op_sel_hi:[0,1]
	v_pk_fma_f32 v[32:33], v[86:87], v[212:213], v[32:33]
	v_pk_fma_f32 v[30:31], v[88:89], v[44:45], v[30:31]
	v_pk_fma_f32 v[28:29], v[104:105], v[220:221], v[28:29]
	v_pk_fma_f32 v[26:27], v[106:107], v[218:219], v[26:27]
	v_pk_fma_f32 v[24:25], v[92:93], v[216:217], v[24:25]
	v_pk_fma_f32 v[22:23], v[94:95], v[214:215], v[22:23]
	v_pk_fma_f32 v[20:21], v[110:111], v[40:41], v[20:21]
	v_pk_fma_f32 v[18:19], v[108:109], v[222:223], v[18:19]
	global_store_dwordx4 v[38:39], v[30:33], off nt
	global_store_dwordx4 v[38:39], v[22:25], off offset:16 nt
	v_mul_f32_e32 v224, v31, v31
	v_mul_f32_e32 v225, v33, v33
	v_pk_mul_f32 v[40:41], v[78:79], v[32:33]
	v_pk_mul_f32 v[44:45], v[80:81], v[30:31]
	v_mul_f32_e32 v31, v27, v27
	v_mul_f32_e32 v33, v29, v29
	v_mul_f32_e32 v226, v23, v23
	v_mul_f32_e32 v227, v25, v25
	v_mul_f32_e32 v235, v19, v19
	v_fmac_f32_e32 v224, v30, v30
	v_fmac_f32_e32 v225, v32, v32
	v_fmac_f32_e32 v31, v26, v26
	v_fmac_f32_e32 v33, v28, v28
	v_pk_mul_f32 v[212:213], v[82:83], v[24:25]
	v_pk_mul_f32 v[214:215], v[84:85], v[22:23]
	v_mul_f32_e32 v236, v21, v21
	v_pk_mul_f32 v[222:223], v[102:103], v[18:19]
	v_fmac_f32_e32 v226, v22, v22
	v_fmac_f32_e32 v227, v24, v24
	v_cvt_pk_bf16_f32 v22, v44, v45
	v_cvt_pk_bf16_f32 v23, v40, v41
	v_cvt_pk_bf16_f32 v24, v214, v215
	v_cvt_pk_bf16_f32 v25, v212, v213
	v_fmac_f32_e32 v235, v18, v18
	v_add_f32_e32 v30, v224, v225
	global_store_dwordx4 v[42:43], v[22:25], off
	v_lshlrev_b32_e32 v32, 16, v22
	v_and_b32_e32 v40, 0xffff0000, v22
	global_store_dwordx4 v[38:39], v[26:29], off offset:512 nt
	global_store_dwordx4 v[38:39], v[18:21], off offset:528 nt
	v_pk_mul_f32 v[220:221], v[100:101], v[20:21]
	v_fmac_f32_e32 v236, v20, v20
	v_add_f32_e32 v18, v31, v33
	v_lshlrev_b32_e32 v41, 16, v23
	v_and_b32_e32 v44, 0xffff0000, v23
	v_add_f32_e32 v19, v226, v30
	v_max3_f32 v20, |v32|, 0, |v40|
	v_add_f32_e32 v18, v235, v18
	v_lshlrev_b32_e32 v45, 16, v24
	v_and_b32_e32 v212, 0xffff0000, v24
	v_add_f32_e32 v19, v227, v19
	v_max3_f32 v20, v20, |v41|, |v44|
	v_add_f32_e32 v18, v236, v18
	v_lshlrev_b32_e32 v213, 16, v25
	v_and_b32_e32 v214, 0xffff0000, v25
	v_max3_f32 v20, v20, |v45|, |v212|
	v_add_f32_e32 v18, v19, v18
	v_pk_mul_f32 v[218:219], v[98:99], v[26:27]
	v_max3_f32 v19, v20, |v213|, |v214|
	v_cvt_pk_bf16_f32 v22, v218, v219
	ds_bpermute_b32 v20, v233, v18
	v_lshlrev_b32_e32 v21, 16, v22
	v_and_b32_e32 v26, 0xffff0000, v22
	v_pk_mul_f32 v[216:217], v[96:97], v[28:29]
	v_max3_f32 v19, v19, |v21|, |v26|
	v_cvt_pk_bf16_f32 v23, v216, v217
	v_cvt_pk_bf16_f32 v24, v222, v223
	v_cvt_pk_bf16_f32 v25, v220, v221
	s_waitcnt lgkmcnt(0)
	v_add_f32_e32 v18, v18, v20
	v_lshlrev_b32_e32 v27, 16, v23
	v_and_b32_e32 v28, 0xffff0000, v23
	v_lshlrev_b32_e32 v29, 16, v24
	v_and_b32_e32 v30, 0xffff0000, v24
	v_max3_f32 v19, v19, |v27|, |v28|
	v_max3_f32 v19, v19, |v29|, |v30|
	v_lshlrev_b32_e32 v21, 16, v25
	v_and_b32_e32 v26, 0xffff0000, v25
	v_max3_f32 v21, v19, |v21|, |v26|
	ds_bpermute_b32 v20, v233, v21
	v_xor_b32_e32 v19, 32, v232
	v_cmp_lt_i32_e32 vcc, v19, v234
	global_store_dwordx4 v[42:43], v[22:25], off offset:256
	s_waitcnt lgkmcnt(0)
	v_max_f32_e32 v20, v20, v20
	v_cndmask_b32_e32 v19, v232, v19, vcc
	v_lshlrev_b32_e32 v216, 2, v19
	v_max_f32_e32 v20, v21, v20
	ds_bpermute_b32 v19, v216, v18
	ds_bpermute_b32 v21, v216, v20
	s_and_saveexec_b64 s[42:43], s[0:1]
	s_cbranch_execz .LBB0_2770
	s_waitcnt lgkmcnt(0)
	v_max_f32_e32 v21, v21, v21
	v_max_f32_e32 v20, v20, v20
	v_add_f32_e32 v23, v18, v19
	v_lshlrev_b64 v[18:19], 7, v[210:211]
	v_max_f32_e32 v22, v20, v21
	v_lshl_add_u64 v[20:21], s[26:27], 0, v[18:19]
	s_lshl_b64 s[82:83], s[40:41], 2
	v_lshl_add_u64 v[18:19], s[28:29], 0, v[18:19]
	v_lshl_add_u64 v[20:21], v[20:21], 0, s[82:83]
	s_lshl_b32 s12, s63, 2
	v_lshl_add_u64 v[18:19], v[18:19], 0, s[82:83]
	v_lshl_add_u64 v[20:21], v[20:21], 0, s[12:13]
	v_lshl_add_u64 v[18:19], v[18:19], 0, s[12:13]
	global_store_dword v[20:21], v23, off
	global_store_dword v[18:19], v22, off
.LBB0_2770:
	s_or_b64 exec, exec, s[42:43]
	v_or_b32_e32 v212, 32, v210
	v_ashrrev_i32_e32 v213, 31, v212
	s_waitcnt lgkmcnt(1)
	v_lshlrev_b64 v[18:19], 13, v[212:213]
	v_lshl_add_u64 v[18:19], s[16:17], 0, v[18:19]
	v_lshl_add_u64 v[214:215], v[90:91], 2, v[18:19]
	global_load_dwordx4 v[26:29], v[214:215], off offset:16 nt
	global_load_dwordx4 v[30:33], v[214:215], off nt
	s_waitcnt lgkmcnt(0)
	global_load_dwordx4 v[18:21], v[214:215], off offset:528 nt
	global_load_dwordx4 v[22:25], v[214:215], off offset:512 nt
	v_lshl_add_u64 v[38:39], v[34:35], 2, s[18:19]
	s_nop 1
	v_mov_b32_e32 v38, v241
	v_lshlrev_b64 v[40:41], 12, v[34:35]
	v_lshl_add_u64 v[40:41], s[22:23], 0, v[40:41]
	v_lshl_add_u64 v[40:41], v[90:91], 1, v[40:41]
	s_waitcnt vmcnt(12)
	v_pk_mul_f32 v[44:45], v[38:39], v[192:193] op_sel_hi:[0,1]
	v_pk_mul_f32 v[192:193], v[38:39], v[200:201] op_sel_hi:[0,1]
	v_pk_mul_f32 v[42:43], v[38:39], v[194:195] op_sel_hi:[0,1]
	v_pk_mul_f32 v[194:195], v[38:39], v[198:199] op_sel_hi:[0,1]
	v_pk_mul_f32 v[198:199], v[38:39], v[206:207] op_sel_hi:[0,1]
	v_pk_mul_f32 v[200:201], v[38:39], v[202:203] op_sel_hi:[0,1]
	v_pk_fma_f32 v[10:11], v[94:95], v[192:193], v[10:11]
	v_pk_mul_f32 v[202:203], v[38:39], v[208:209] op_sel_hi:[0,1]
	v_pk_mul_f32 v[38:39], v[38:39], v[204:205] op_sel_hi:[0,1]
	v_pk_fma_f32 v[16:17], v[86:87], v[44:45], v[16:17]
	v_pk_fma_f32 v[14:15], v[88:89], v[42:43], v[14:15]
	v_pk_fma_f32 v[12:13], v[92:93], v[194:195], v[12:13]
	v_pk_fma_f32 v[8:9], v[104:105], v[200:201], v[8:9]
	v_pk_fma_f32 v[6:7], v[106:107], v[198:199], v[6:7]
	v_mul_f32_e32 v206, v11, v11
	v_pk_fma_f32 v[4:5], v[110:111], v[38:39], v[4:5]
	v_pk_fma_f32 v[2:3], v[108:109], v[202:203], v[2:3]
	global_store_dwordx4 v[36:37], v[14:17], off nt
	global_store_dwordx4 v[36:37], v[10:13], off offset:16 nt
	v_mul_f32_e32 v204, v15, v15
	v_mul_f32_e32 v205, v17, v17
	v_mul_f32_e32 v207, v13, v13
	v_pk_mul_f32 v[38:39], v[78:79], v[16:17]
	v_pk_mul_f32 v[42:43], v[80:81], v[14:15]
	v_pk_mul_f32 v[192:193], v[84:85], v[10:11]
	v_mul_f32_e32 v15, v7, v7
	v_mul_f32_e32 v17, v9, v9
	v_fmac_f32_e32 v206, v10, v10
	v_cvt_pk_bf16_f32 v10, v42, v43
	v_pk_mul_f32 v[44:45], v[82:83], v[12:13]
	v_mul_f32_e32 v208, v3, v3
	v_mul_f32_e32 v209, v5, v5
	v_fmac_f32_e32 v204, v14, v14
	v_fmac_f32_e32 v205, v16, v16
	v_fmac_f32_e32 v207, v12, v12
	v_cvt_pk_bf16_f32 v11, v38, v39
	v_cvt_pk_bf16_f32 v12, v192, v193
	v_cvt_pk_bf16_f32 v13, v44, v45
	v_fmac_f32_e32 v15, v6, v6
	v_fmac_f32_e32 v17, v8, v8
	global_store_dwordx4 v[40:41], v[10:13], off
	v_lshlrev_b32_e32 v16, 16, v10
	v_pk_mul_f32 v[200:201], v[100:101], v[4:5]
	v_and_b32_e32 v10, 0xffff0000, v10
	v_pk_mul_f32 v[202:203], v[102:103], v[2:3]
	v_fmac_f32_e32 v208, v2, v2
	v_fmac_f32_e32 v209, v4, v4
	v_add_f32_e32 v14, v204, v205
	v_lshlrev_b32_e32 v38, 16, v11
	v_and_b32_e32 v11, 0xffff0000, v11
	global_store_dwordx4 v[36:37], v[6:9], off offset:512 nt
	global_store_dwordx4 v[36:37], v[2:5], off offset:528 nt
	v_lshlrev_b32_e32 v39, 16, v12
	v_and_b32_e32 v12, 0xffff0000, v12
	v_add_f32_e32 v2, v15, v17
	v_max3_f32 v4, |v16|, 0, |v10|
	v_add_f32_e32 v3, v206, v14
	v_add_f32_e32 v2, v208, v2
	v_max3_f32 v4, v4, |v38|, |v11|
	v_lshlrev_b32_e32 v42, 16, v13
	v_and_b32_e32 v13, 0xffff0000, v13
	v_add_f32_e32 v3, v207, v3
	v_add_f32_e32 v2, v209, v2
	v_max3_f32 v4, v4, |v39|, |v12|
	v_pk_mul_f32 v[198:199], v[98:99], v[6:7]
	v_add_f32_e32 v2, v3, v2
	v_cvt_pk_bf16_f32 v6, v198, v199
	v_max3_f32 v3, v4, |v42|, |v13|
	v_lshlrev_b32_e32 v5, 16, v6
	v_and_b32_e32 v10, 0xffff0000, v6
	v_pk_mul_f32 v[194:195], v[96:97], v[8:9]
	v_max3_f32 v3, v3, |v5|, |v10|
	v_cvt_pk_bf16_f32 v7, v194, v195
	v_cvt_pk_bf16_f32 v8, v202, v203
	v_cvt_pk_bf16_f32 v9, v200, v201
	ds_bpermute_b32 v4, v233, v2
	v_lshlrev_b32_e32 v14, 16, v7
	v_and_b32_e32 v15, 0xffff0000, v7
	v_lshlrev_b32_e32 v16, 16, v8
	v_and_b32_e32 v17, 0xffff0000, v8
	v_max3_f32 v3, v3, |v14|, |v15|
	v_lshlrev_b32_e32 v36, 16, v9
	v_and_b32_e32 v37, 0xffff0000, v9
	v_max3_f32 v3, v3, |v16|, |v17|
	v_max3_f32 v5, v3, |v36|, |v37|
	ds_bpermute_b32 v10, v233, v5
	s_waitcnt lgkmcnt(1)
	v_add_f32_e32 v2, v2, v4
	ds_bpermute_b32 v3, v216, v2
	global_store_dwordx4 v[40:41], v[6:9], off offset:256
	s_waitcnt lgkmcnt(1)
	v_max_f32_e32 v4, v10, v10
	v_max_f32_e32 v4, v5, v4
	ds_bpermute_b32 v5, v216, v4
	s_and_saveexec_b64 s[42:43], s[0:1]
	s_cbranch_execz .LBB0_2772
	s_waitcnt lgkmcnt(0)
	v_max_f32_e32 v5, v5, v5
	v_max_f32_e32 v4, v4, v4
	v_add_f32_e32 v7, v2, v3
	v_lshlrev_b64 v[2:3], 7, v[34:35]
	v_max_f32_e32 v6, v4, v5
	v_lshl_add_u64 v[4:5], s[26:27], 0, v[2:3]
	s_lshl_b64 s[82:83], s[40:41], 2
	v_lshl_add_u64 v[2:3], s[28:29], 0, v[2:3]
	v_lshl_add_u64 v[4:5], v[4:5], 0, s[82:83]
	s_lshl_b32 s12, s63, 2
	v_lshl_add_u64 v[2:3], v[2:3], 0, s[82:83]
	v_lshl_add_u64 v[4:5], v[4:5], 0, s[12:13]
	v_lshl_add_u64 v[2:3], v[2:3], 0, s[12:13]
	global_store_dword v[4:5], v7, off
	global_store_dword v[2:3], v6, off
.LBB0_2772:
	s_or_b64 exec, exec, s[42:43]
	v_or_b32_e32 v192, 48, v210
	v_ashrrev_i32_e32 v193, 31, v192
	s_waitcnt lgkmcnt(1)
	v_lshlrev_b64 v[2:3], 13, v[192:193]
	v_lshl_add_u64 v[2:3], s[16:17], 0, v[2:3]
	v_lshl_add_u64 v[194:195], v[90:91], 2, v[2:3]
	global_load_dwordx4 v[38:41], v[194:195], off offset:16 nt
	global_load_dwordx4 v[42:45], v[194:195], off nt
	global_load_dwordx4 v[6:9], v[194:195], off offset:528 nt
	global_load_dwordx4 v[34:37], v[194:195], off offset:512 nt
	v_lshl_add_u64 v[2:3], v[212:213], 2, s[18:19]
	s_nop 1
	v_mov_b32_e32 v2, v242
	s_waitcnt lgkmcnt(0)
	v_lshlrev_b64 v[4:5], 12, v[212:213]
	v_lshl_add_u64 v[4:5], s[22:23], 0, v[4:5]
	v_lshl_add_u64 v[198:199], v[90:91], 1, v[4:5]
	s_waitcnt vmcnt(12)
	v_pk_mul_f32 v[10:11], v[2:3], v[178:179] op_sel_hi:[0,1]
	v_pk_mul_f32 v[4:5], v[2:3], v[176:177] op_sel_hi:[0,1]
	v_pk_mul_f32 v[14:15], v[2:3], v[182:183] op_sel_hi:[0,1]
	v_pk_mul_f32 v[12:13], v[2:3], v[180:181] op_sel_hi:[0,1]
	v_pk_mul_f32 v[176:177], v[2:3], v[188:189] op_sel_hi:[0,1]
	v_pk_mul_f32 v[16:17], v[2:3], v[184:185] op_sel_hi:[0,1]
	v_pk_mul_f32 v[178:179], v[2:3], v[190:191] op_sel_hi:[0,1]
	v_pk_mul_f32 v[180:181], v[2:3], v[186:187] op_sel_hi:[0,1]
	v_pk_fma_f32 v[2:3], v[88:89], v[10:11], v[30:31]
	v_pk_fma_f32 v[4:5], v[86:87], v[4:5], v[32:33]
	v_pk_fma_f32 v[20:21], v[110:111], v[180:181], v[20:21]
	v_mul_f32_e32 v180, v3, v3
	v_pk_fma_f32 v[12:13], v[92:93], v[12:13], v[28:29]
	v_pk_fma_f32 v[10:11], v[94:95], v[14:15], v[26:27]
	v_pk_fma_f32 v[16:17], v[104:105], v[16:17], v[24:25]
	v_pk_fma_f32 v[14:15], v[106:107], v[176:177], v[22:23]
	global_store_dwordx4 v[214:215], v[2:5], off nt
	global_store_dwordx4 v[214:215], v[10:13], off offset:16 nt
	v_mul_f32_e32 v181, v5, v5
	v_pk_mul_f32 v[22:23], v[78:79], v[4:5]
	v_pk_mul_f32 v[24:25], v[80:81], v[2:3]
	v_fmac_f32_e32 v180, v2, v2
	v_cvt_pk_bf16_f32 v2, v24, v25
	v_pk_mul_f32 v[26:27], v[82:83], v[12:13]
	v_pk_mul_f32 v[28:29], v[84:85], v[10:11]
	v_fmac_f32_e32 v181, v4, v4
	v_cvt_pk_bf16_f32 v3, v22, v23
	v_cvt_pk_bf16_f32 v4, v28, v29
	v_cvt_pk_bf16_f32 v5, v26, v27
	global_store_dwordx4 v[198:199], v[2:5], off
	v_lshlrev_b32_e32 v23, 16, v2
	v_lshlrev_b32_e32 v24, 16, v3
	v_and_b32_e32 v2, 0xffff0000, v2
	v_and_b32_e32 v3, 0xffff0000, v3
	v_max3_f32 v2, |v23|, 0, |v2|
	v_lshlrev_b32_e32 v25, 16, v4
	v_and_b32_e32 v4, 0xffff0000, v4
	v_max3_f32 v2, v2, |v24|, |v3|
	v_pk_fma_f32 v[18:19], v[108:109], v[178:179], v[18:19]
	v_mul_f32_e32 v182, v11, v11
	v_mul_f32_e32 v183, v13, v13
	v_mul_f32_e32 v11, v15, v15
	v_mul_f32_e32 v13, v17, v17
	v_lshlrev_b32_e32 v26, 16, v5
	v_and_b32_e32 v5, 0xffff0000, v5
	v_max3_f32 v2, v2, |v25|, |v4|
	v_mul_f32_e32 v184, v19, v19
	v_pk_mul_f32 v[30:31], v[96:97], v[16:17]
	v_pk_mul_f32 v[32:33], v[98:99], v[14:15]
	v_fmac_f32_e32 v182, v10, v10
	v_fmac_f32_e32 v11, v14, v14
	v_fmac_f32_e32 v13, v16, v16
	global_store_dwordx4 v[214:215], v[14:17], off offset:512 nt
	global_store_dwordx4 v[214:215], v[18:21], off offset:528 nt
	v_cvt_pk_bf16_f32 v10, v32, v33
	v_max3_f32 v2, v2, |v26|, |v5|
	v_lshlrev_b32_e32 v16, 16, v10
	v_and_b32_e32 v17, 0xffff0000, v10
	v_mul_f32_e32 v185, v21, v21
	v_pk_mul_f32 v[178:179], v[102:103], v[18:19]
	v_fmac_f32_e32 v184, v18, v18
	v_add_f32_e32 v22, v180, v181
	v_add_f32_e32 v14, v11, v13
	v_cvt_pk_bf16_f32 v11, v30, v31
	v_max3_f32 v2, v2, |v16|, |v17|
	v_lshlrev_b32_e32 v18, 16, v11
	v_and_b32_e32 v19, 0xffff0000, v11
	v_pk_mul_f32 v[176:177], v[100:101], v[20:21]
	v_fmac_f32_e32 v183, v12, v12
	v_fmac_f32_e32 v185, v20, v20
	v_cvt_pk_bf16_f32 v12, v178, v179
	v_add_f32_e32 v15, v182, v22
	v_add_f32_e32 v14, v184, v14
	v_lshlrev_b32_e32 v20, 16, v12
	v_and_b32_e32 v21, 0xffff0000, v12
	v_max3_f32 v2, v2, |v18|, |v19|
	v_cvt_pk_bf16_f32 v13, v176, v177
	v_add_f32_e32 v15, v183, v15
	v_lshlrev_b32_e32 v22, 16, v13
	v_and_b32_e32 v23, 0xffff0000, v13
	v_add_f32_e32 v3, v185, v14
	v_max3_f32 v2, v2, |v20|, |v21|
	v_add_f32_e32 v3, v15, v3
	v_max3_f32 v5, v2, |v22|, |v23|
	ds_bpermute_b32 v4, v233, v3
	ds_bpermute_b32 v14, v233, v5
	global_store_dwordx4 v[198:199], v[10:13], off offset:256
	s_waitcnt lgkmcnt(1)
	v_add_f32_e32 v2, v3, v4
	s_waitcnt lgkmcnt(0)
	v_max_f32_e32 v4, v14, v14
	v_max_f32_e32 v4, v5, v4
	ds_bpermute_b32 v3, v216, v2
	ds_bpermute_b32 v5, v216, v4
	s_and_saveexec_b64 s[42:43], s[0:1]
	s_cbranch_execz .LBB0_2774
	s_waitcnt lgkmcnt(0)
	v_max_f32_e32 v5, v5, v5
	v_max_f32_e32 v4, v4, v4
	v_add_f32_e32 v11, v2, v3
	v_lshlrev_b64 v[2:3], 7, v[212:213]
	v_max_f32_e32 v10, v4, v5
	v_lshl_add_u64 v[4:5], s[26:27], 0, v[2:3]
	s_lshl_b64 s[82:83], s[40:41], 2
	v_lshl_add_u64 v[2:3], s[28:29], 0, v[2:3]
	v_lshl_add_u64 v[4:5], v[4:5], 0, s[82:83]
	s_lshl_b32 s12, s63, 2
	v_lshl_add_u64 v[2:3], v[2:3], 0, s[82:83]
	v_lshl_add_u64 v[4:5], v[4:5], 0, s[12:13]
	v_lshl_add_u64 v[2:3], v[2:3], 0, s[12:13]
	global_store_dword v[4:5], v11, off
	global_store_dword v[2:3], v10, off
.LBB0_2774:
	s_or_b64 exec, exec, s[42:43]
	v_add_u32_e32 v176, 0x80, v210
	v_ashrrev_i32_e32 v177, 31, v176
	s_waitcnt lgkmcnt(1)
	v_lshlrev_b64 v[2:3], 13, v[176:177]
	v_lshl_add_u64 v[2:3], s[16:17], 0, v[2:3]
	v_lshl_add_u64 v[178:179], v[90:91], 2, v[2:3]
	global_load_dwordx4 v[14:17], v[178:179], off offset:16 nt
	global_load_dwordx4 v[18:21], v[178:179], off nt
	s_waitcnt lgkmcnt(0)
	global_load_dwordx4 v[2:5], v[178:179], off offset:528 nt
	global_load_dwordx4 v[10:13], v[178:179], off offset:512 nt
	v_lshl_add_u64 v[22:23], v[192:193], 2, s[18:19]
	s_nop 1
	v_mov_b32_e32 v22, v243
	v_lshlrev_b64 v[24:25], 12, v[192:193]
	v_lshl_add_u64 v[24:25], s[22:23], 0, v[24:25]
	v_lshl_add_u64 v[180:181], v[90:91], 1, v[24:25]
	s_waitcnt vmcnt(12)
	v_pk_mul_f32 v[26:27], v[22:23], v[162:163] op_sel_hi:[0,1]
	v_pk_mul_f32 v[24:25], v[22:23], v[160:161] op_sel_hi:[0,1]
	v_pk_mul_f32 v[30:31], v[22:23], v[166:167] op_sel_hi:[0,1]
	v_pk_mul_f32 v[28:29], v[22:23], v[164:165] op_sel_hi:[0,1]
	v_pk_mul_f32 v[160:161], v[22:23], v[172:173] op_sel_hi:[0,1]
	v_pk_mul_f32 v[32:33], v[22:23], v[168:169] op_sel_hi:[0,1]
	v_pk_mul_f32 v[162:163], v[22:23], v[174:175] op_sel_hi:[0,1]
	v_pk_mul_f32 v[164:165], v[22:23], v[170:171] op_sel_hi:[0,1]
	v_pk_fma_f32 v[24:25], v[86:87], v[24:25], v[44:45]
	v_pk_fma_f32 v[22:23], v[88:89], v[26:27], v[42:43]
	v_pk_fma_f32 v[28:29], v[92:93], v[28:29], v[40:41]
	v_pk_fma_f32 v[26:27], v[94:95], v[30:31], v[38:39]
	v_pk_fma_f32 v[32:33], v[104:105], v[32:33], v[36:37]
	v_pk_fma_f32 v[30:31], v[106:107], v[160:161], v[34:35]
	v_pk_fma_f32 v[8:9], v[110:111], v[164:165], v[8:9]
	v_pk_fma_f32 v[6:7], v[108:109], v[162:163], v[6:7]
	global_store_dwordx4 v[194:195], v[22:25], off nt
	global_store_dwordx4 v[194:195], v[26:29], off offset:16 nt
	v_mul_f32_e32 v164, v23, v23
	v_mul_f32_e32 v165, v25, v25
	v_mul_f32_e32 v166, v27, v27
	v_mul_f32_e32 v167, v29, v29
	v_pk_mul_f32 v[34:35], v[78:79], v[24:25]
	v_pk_mul_f32 v[38:39], v[82:83], v[28:29]
	v_pk_mul_f32 v[40:41], v[84:85], v[26:27]
	v_mul_f32_e32 v27, v31, v31
	v_mul_f32_e32 v29, v33, v33
	v_pk_mul_f32 v[36:37], v[80:81], v[22:23]
	v_mul_f32_e32 v168, v7, v7
	v_mul_f32_e32 v169, v9, v9
	v_fmac_f32_e32 v164, v22, v22
	v_fmac_f32_e32 v165, v24, v24
	v_fmac_f32_e32 v167, v28, v28
	v_cvt_pk_bf16_f32 v22, v36, v37
	v_cvt_pk_bf16_f32 v23, v34, v35
	v_fmac_f32_e32 v27, v30, v30
	v_fmac_f32_e32 v29, v32, v32
	v_lshlrev_b32_e32 v28, 16, v22
	v_and_b32_e32 v34, 0xffff0000, v22
	v_pk_mul_f32 v[160:161], v[100:101], v[8:9]
	v_pk_mul_f32 v[162:163], v[102:103], v[6:7]
	v_fmac_f32_e32 v166, v26, v26
	v_cvt_pk_bf16_f32 v24, v40, v41
	v_cvt_pk_bf16_f32 v25, v38, v39
	v_fmac_f32_e32 v168, v6, v6
	v_fmac_f32_e32 v169, v8, v8
	v_add_f32_e32 v26, v164, v165
	global_store_dwordx4 v[180:181], v[22:25], off
	v_lshlrev_b32_e32 v35, 16, v23
	v_and_b32_e32 v36, 0xffff0000, v23
	global_store_dwordx4 v[194:195], v[30:33], off offset:512 nt
	global_store_dwordx4 v[194:195], v[6:9], off offset:528 nt
	v_lshlrev_b32_e32 v37, 16, v24
	v_and_b32_e32 v38, 0xffff0000, v24
	v_add_f32_e32 v6, v27, v29
	v_max3_f32 v8, |v28|, 0, |v34|
	v_add_f32_e32 v7, v166, v26
	v_add_f32_e32 v6, v168, v6
	v_max3_f32 v8, v8, |v35|, |v36|
	v_lshlrev_b32_e32 v39, 16, v25
	v_and_b32_e32 v40, 0xffff0000, v25
	v_add_f32_e32 v7, v167, v7
	v_add_f32_e32 v6, v169, v6
	v_max3_f32 v8, v8, |v37|, |v38|
	v_pk_mul_f32 v[44:45], v[98:99], v[30:31]
	v_add_f32_e32 v6, v7, v6
	v_cvt_pk_bf16_f32 v22, v44, v45
	v_max3_f32 v7, v8, |v39|, |v40|
	v_lshlrev_b32_e32 v9, 16, v22
	v_and_b32_e32 v26, 0xffff0000, v22
	v_pk_mul_f32 v[42:43], v[96:97], v[32:33]
	v_max3_f32 v7, v7, |v9|, |v26|
	v_cvt_pk_bf16_f32 v23, v42, v43
	v_cvt_pk_bf16_f32 v24, v162, v163
	v_cvt_pk_bf16_f32 v25, v160, v161
	ds_bpermute_b32 v8, v233, v6
	v_lshlrev_b32_e32 v27, 16, v23
	v_and_b32_e32 v28, 0xffff0000, v23
	v_lshlrev_b32_e32 v29, 16, v24
	v_and_b32_e32 v30, 0xffff0000, v24
	v_max3_f32 v7, v7, |v27|, |v28|
	v_lshlrev_b32_e32 v31, 16, v25
	v_and_b32_e32 v32, 0xffff0000, v25
	v_max3_f32 v7, v7, |v29|, |v30|
	v_max3_f32 v9, v7, |v31|, |v32|
	ds_bpermute_b32 v26, v233, v9
	s_waitcnt lgkmcnt(1)
	v_add_f32_e32 v6, v6, v8
	ds_bpermute_b32 v7, v216, v6
	global_store_dwordx4 v[180:181], v[22:25], off offset:256
	s_waitcnt lgkmcnt(1)
	v_max_f32_e32 v8, v26, v26
	v_max_f32_e32 v8, v9, v8
	ds_bpermute_b32 v9, v216, v8
	s_and_saveexec_b64 s[42:43], s[0:1]
	s_cbranch_execz .LBB0_2776
	s_waitcnt lgkmcnt(0)
	v_max_f32_e32 v9, v9, v9
	v_max_f32_e32 v8, v8, v8
	v_add_f32_e32 v23, v6, v7
	v_lshlrev_b64 v[6:7], 7, v[192:193]
	v_max_f32_e32 v22, v8, v9
	v_lshl_add_u64 v[8:9], s[26:27], 0, v[6:7]
	s_lshl_b64 s[82:83], s[40:41], 2
	v_lshl_add_u64 v[6:7], s[28:29], 0, v[6:7]
	v_lshl_add_u64 v[8:9], v[8:9], 0, s[82:83]
	s_lshl_b32 s12, s63, 2
	v_lshl_add_u64 v[6:7], v[6:7], 0, s[82:83]
	v_lshl_add_u64 v[8:9], v[8:9], 0, s[12:13]
	v_lshl_add_u64 v[6:7], v[6:7], 0, s[12:13]
	global_store_dword v[8:9], v23, off
	global_store_dword v[6:7], v22, off
.LBB0_2776:
	s_or_b64 exec, exec, s[42:43]
	v_or_b32_e32 v36, 16, v176
	v_ashrrev_i32_e32 v37, 31, v36
	s_waitcnt lgkmcnt(1)
	v_lshlrev_b64 v[6:7], 13, v[36:37]
	v_lshl_add_u64 v[6:7], s[16:17], 0, v[6:7]
	v_lshl_add_u64 v[40:41], v[90:91], 2, v[6:7]
	global_load_dwordx4 v[26:29], v[40:41], off offset:16 nt
	global_load_dwordx4 v[30:33], v[40:41], off nt
	s_waitcnt lgkmcnt(0)
	global_load_dwordx4 v[6:9], v[40:41], off offset:528 nt
	global_load_dwordx4 v[22:25], v[40:41], off offset:512 nt
	s_nop 1
	v_mov_b32_e32 v34, v244
	v_lshlrev_b64 v[38:39], 12, v[176:177]
	v_lshl_add_u64 v[38:39], s[22:23], 0, v[38:39]
	v_lshl_add_u64 v[38:39], v[90:91], 1, v[38:39]
	s_waitcnt vmcnt(12)
	v_pk_mul_f32 v[44:45], v[34:35], v[128:129] op_sel_hi:[0,1]
	v_pk_mul_f32 v[128:129], v[34:35], v[150:151] op_sel_hi:[0,1]
	v_pk_mul_f32 v[42:43], v[34:35], v[146:147] op_sel_hi:[0,1]
	v_pk_mul_f32 v[146:147], v[34:35], v[148:149] op_sel_hi:[0,1]
	v_pk_mul_f32 v[148:149], v[34:35], v[156:157] op_sel_hi:[0,1]
	v_pk_mul_f32 v[150:151], v[34:35], v[152:153] op_sel_hi:[0,1]
	v_pk_fma_f32 v[14:15], v[94:95], v[128:129], v[14:15]
	v_pk_mul_f32 v[152:153], v[34:35], v[158:159] op_sel_hi:[0,1]
	v_pk_mul_f32 v[34:35], v[34:35], v[154:155] op_sel_hi:[0,1]
	v_pk_fma_f32 v[20:21], v[86:87], v[44:45], v[20:21]
	v_pk_fma_f32 v[18:19], v[88:89], v[42:43], v[18:19]
	v_pk_fma_f32 v[16:17], v[92:93], v[146:147], v[16:17]
	v_pk_fma_f32 v[12:13], v[104:105], v[150:151], v[12:13]
	v_pk_fma_f32 v[10:11], v[106:107], v[148:149], v[10:11]
	v_mul_f32_e32 v156, v15, v15
	v_pk_fma_f32 v[4:5], v[110:111], v[34:35], v[4:5]
	v_pk_fma_f32 v[2:3], v[108:109], v[152:153], v[2:3]
	global_store_dwordx4 v[178:179], v[18:21], off nt
	global_store_dwordx4 v[178:179], v[14:17], off offset:16 nt
	v_mul_f32_e32 v154, v19, v19
	v_mul_f32_e32 v155, v21, v21
	v_mul_f32_e32 v157, v17, v17
	v_pk_mul_f32 v[34:35], v[78:79], v[20:21]
	v_pk_mul_f32 v[42:43], v[80:81], v[18:19]
	v_pk_mul_f32 v[128:129], v[84:85], v[14:15]
	v_mul_f32_e32 v19, v11, v11
	v_mul_f32_e32 v21, v13, v13
	v_fmac_f32_e32 v156, v14, v14
	v_cvt_pk_bf16_f32 v14, v42, v43
	v_pk_mul_f32 v[44:45], v[82:83], v[16:17]
	v_mul_f32_e32 v158, v3, v3
	v_mul_f32_e32 v159, v5, v5
	v_fmac_f32_e32 v154, v18, v18
	v_fmac_f32_e32 v155, v20, v20
	v_fmac_f32_e32 v157, v16, v16
	v_cvt_pk_bf16_f32 v15, v34, v35
	v_cvt_pk_bf16_f32 v16, v128, v129
	v_cvt_pk_bf16_f32 v17, v44, v45
	v_fmac_f32_e32 v19, v10, v10
	v_fmac_f32_e32 v21, v12, v12
	global_store_dwordx4 v[38:39], v[14:17], off
	v_lshlrev_b32_e32 v20, 16, v14
	v_pk_mul_f32 v[150:151], v[100:101], v[4:5]
	v_and_b32_e32 v14, 0xffff0000, v14
	v_pk_mul_f32 v[152:153], v[102:103], v[2:3]
	v_fmac_f32_e32 v158, v2, v2
	v_fmac_f32_e32 v159, v4, v4
	v_add_f32_e32 v18, v154, v155
	v_lshlrev_b32_e32 v34, 16, v15
	v_and_b32_e32 v15, 0xffff0000, v15
	global_store_dwordx4 v[178:179], v[10:13], off offset:512 nt
	global_store_dwordx4 v[178:179], v[2:5], off offset:528 nt
	v_lshlrev_b32_e32 v35, 16, v16
	v_and_b32_e32 v16, 0xffff0000, v16
	v_add_f32_e32 v2, v19, v21
	v_max3_f32 v4, |v20|, 0, |v14|
	v_add_f32_e32 v3, v156, v18
	v_add_f32_e32 v2, v158, v2
	v_max3_f32 v4, v4, |v34|, |v15|
	v_lshlrev_b32_e32 v42, 16, v17
	v_and_b32_e32 v17, 0xffff0000, v17
	v_add_f32_e32 v3, v157, v3
	v_add_f32_e32 v2, v159, v2
	v_max3_f32 v4, v4, |v35|, |v16|
	v_pk_mul_f32 v[148:149], v[98:99], v[10:11]
	v_add_f32_e32 v2, v3, v2
	v_cvt_pk_bf16_f32 v10, v148, v149
	v_max3_f32 v3, v4, |v42|, |v17|
	v_lshlrev_b32_e32 v5, 16, v10
	v_and_b32_e32 v14, 0xffff0000, v10
	v_pk_mul_f32 v[146:147], v[96:97], v[12:13]
	v_max3_f32 v3, v3, |v5|, |v14|
	v_cvt_pk_bf16_f32 v11, v146, v147
	v_cvt_pk_bf16_f32 v12, v152, v153
	v_cvt_pk_bf16_f32 v13, v150, v151
	ds_bpermute_b32 v4, v233, v2
	v_lshlrev_b32_e32 v18, 16, v11
	v_and_b32_e32 v19, 0xffff0000, v11
	v_lshlrev_b32_e32 v20, 16, v12
	v_and_b32_e32 v21, 0xffff0000, v12
	v_max3_f32 v3, v3, |v18|, |v19|
	v_lshlrev_b32_e32 v43, 16, v13
	v_and_b32_e32 v44, 0xffff0000, v13
	v_max3_f32 v3, v3, |v20|, |v21|
	v_max3_f32 v5, v3, |v43|, |v44|
	ds_bpermute_b32 v14, v233, v5
	s_waitcnt lgkmcnt(1)
	v_add_f32_e32 v2, v2, v4
	ds_bpermute_b32 v3, v216, v2
	global_store_dwordx4 v[38:39], v[10:13], off offset:256
	s_waitcnt lgkmcnt(1)
	v_max_f32_e32 v4, v14, v14
	v_max_f32_e32 v4, v5, v4
	ds_bpermute_b32 v5, v216, v4
	s_and_saveexec_b64 s[42:43], s[0:1]
	s_cbranch_execz .LBB0_2778
	s_waitcnt lgkmcnt(0)
	v_max_f32_e32 v5, v5, v5
	v_max_f32_e32 v4, v4, v4
	v_add_f32_e32 v11, v2, v3
	v_lshlrev_b64 v[2:3], 7, v[176:177]
	v_max_f32_e32 v10, v4, v5
	v_lshl_add_u64 v[4:5], s[26:27], 0, v[2:3]
	s_lshl_b64 s[82:83], s[40:41], 2
	v_lshl_add_u64 v[2:3], s[28:29], 0, v[2:3]
	v_lshl_add_u64 v[4:5], v[4:5], 0, s[82:83]
	s_lshl_b32 s12, s63, 2
	v_lshl_add_u64 v[2:3], v[2:3], 0, s[82:83]
	v_lshl_add_u64 v[4:5], v[4:5], 0, s[12:13]
	v_lshl_add_u64 v[2:3], v[2:3], 0, s[12:13]
	global_store_dword v[4:5], v11, off
	global_store_dword v[2:3], v10, off
.LBB0_2778:
	s_or_b64 exec, exec, s[42:43]
	v_or_b32_e32 v34, 32, v176
	v_ashrrev_i32_e32 v35, 31, v34
	s_waitcnt lgkmcnt(1)
	v_lshlrev_b64 v[2:3], 13, v[34:35]
	v_lshl_add_u64 v[2:3], s[16:17], 0, v[2:3]
	v_lshl_add_u64 v[38:39], v[90:91], 2, v[2:3]
	global_load_dwordx4 v[14:17], v[38:39], off offset:16 nt
	global_load_dwordx4 v[18:21], v[38:39], off nt
	s_waitcnt lgkmcnt(0)
	global_load_dwordx4 v[2:5], v[38:39], off offset:528 nt
	global_load_dwordx4 v[10:13], v[38:39], off offset:512 nt
	v_lshl_add_u64 v[42:43], v[36:37], 2, s[18:19]
	s_nop 1
	v_mov_b32_e32 v42, v245
	v_lshlrev_b64 v[44:45], 12, v[36:37]
	v_lshl_add_u64 v[44:45], s[22:23], 0, v[44:45]
	v_lshl_add_u64 v[44:45], v[90:91], 1, v[44:45]
	s_waitcnt vmcnt(12)
	v_pk_mul_f32 v[118:119], v[42:43], v[118:119] op_sel_hi:[0,1]
	v_pk_mul_f32 v[114:115], v[42:43], v[114:115] op_sel_hi:[0,1]
	v_pk_mul_f32 v[112:113], v[42:43], v[112:113] op_sel_hi:[0,1]
	v_pk_mul_f32 v[116:117], v[42:43], v[116:117] op_sel_hi:[0,1]
	v_pk_mul_f32 v[124:125], v[42:43], v[124:125] op_sel_hi:[0,1]
	v_pk_mul_f32 v[120:121], v[42:43], v[120:121] op_sel_hi:[0,1]
	v_pk_fma_f32 v[26:27], v[94:95], v[118:119], v[26:27]
	v_pk_mul_f32 v[126:127], v[42:43], v[126:127] op_sel_hi:[0,1]
	v_pk_mul_f32 v[42:43], v[42:43], v[122:123] op_sel_hi:[0,1]
	v_pk_fma_f32 v[32:33], v[86:87], v[112:113], v[32:33]
	v_pk_fma_f32 v[30:31], v[88:89], v[114:115], v[30:31]
	v_pk_fma_f32 v[28:29], v[92:93], v[116:117], v[28:29]
	v_pk_fma_f32 v[24:25], v[104:105], v[120:121], v[24:25]
	v_pk_fma_f32 v[22:23], v[106:107], v[124:125], v[22:23]
	v_mul_f32_e32 v128, v27, v27
	v_pk_fma_f32 v[8:9], v[110:111], v[42:43], v[8:9]
	v_pk_fma_f32 v[6:7], v[108:109], v[126:127], v[6:7]
	global_store_dwordx4 v[40:41], v[30:33], off nt
	global_store_dwordx4 v[40:41], v[26:29], off offset:16 nt
	v_mul_f32_e32 v126, v31, v31
	v_mul_f32_e32 v127, v33, v33
	v_mul_f32_e32 v129, v29, v29
	v_pk_mul_f32 v[42:43], v[78:79], v[32:33]
	v_pk_mul_f32 v[112:113], v[80:81], v[30:31]
	v_pk_mul_f32 v[116:117], v[84:85], v[26:27]
	v_mul_f32_e32 v31, v23, v23
	v_mul_f32_e32 v33, v25, v25
	v_fmac_f32_e32 v128, v26, v26
	v_cvt_pk_bf16_f32 v26, v112, v113
	v_pk_mul_f32 v[114:115], v[82:83], v[28:29]
	v_mul_f32_e32 v146, v7, v7
	v_mul_f32_e32 v147, v9, v9
	v_fmac_f32_e32 v126, v30, v30
	v_fmac_f32_e32 v127, v32, v32
	v_fmac_f32_e32 v129, v28, v28
	v_cvt_pk_bf16_f32 v27, v42, v43
	v_cvt_pk_bf16_f32 v28, v116, v117
	v_cvt_pk_bf16_f32 v29, v114, v115
	v_fmac_f32_e32 v31, v22, v22
	v_fmac_f32_e32 v33, v24, v24
	global_store_dwordx4 v[44:45], v[26:29], off
	v_lshlrev_b32_e32 v32, 16, v26
	v_pk_mul_f32 v[122:123], v[100:101], v[8:9]
	v_and_b32_e32 v26, 0xffff0000, v26
	v_pk_mul_f32 v[124:125], v[102:103], v[6:7]
	v_fmac_f32_e32 v146, v6, v6
	v_fmac_f32_e32 v147, v8, v8
	v_add_f32_e32 v30, v126, v127
	v_lshlrev_b32_e32 v42, 16, v27
	v_and_b32_e32 v27, 0xffff0000, v27
	global_store_dwordx4 v[40:41], v[22:25], off offset:512 nt
	global_store_dwordx4 v[40:41], v[6:9], off offset:528 nt
	v_lshlrev_b32_e32 v43, 16, v28
	v_and_b32_e32 v28, 0xffff0000, v28
	v_add_f32_e32 v6, v31, v33
	v_max3_f32 v8, |v32|, 0, |v26|
	v_add_f32_e32 v7, v128, v30
	v_add_f32_e32 v6, v146, v6
	v_max3_f32 v8, v8, |v42|, |v27|
	v_lshlrev_b32_e32 v112, 16, v29
	v_and_b32_e32 v29, 0xffff0000, v29
	v_add_f32_e32 v7, v129, v7
	v_add_f32_e32 v6, v147, v6
	v_max3_f32 v8, v8, |v43|, |v28|
	v_pk_mul_f32 v[120:121], v[98:99], v[22:23]
	v_add_f32_e32 v6, v7, v6
	v_cvt_pk_bf16_f32 v22, v120, v121
	v_max3_f32 v7, v8, |v112|, |v29|
	v_lshlrev_b32_e32 v9, 16, v22
	v_and_b32_e32 v26, 0xffff0000, v22
	v_pk_mul_f32 v[118:119], v[96:97], v[24:25]
	v_max3_f32 v7, v7, |v9|, |v26|
	v_cvt_pk_bf16_f32 v23, v118, v119
	v_cvt_pk_bf16_f32 v24, v124, v125
	v_cvt_pk_bf16_f32 v25, v122, v123
	ds_bpermute_b32 v8, v233, v6
	v_lshlrev_b32_e32 v30, 16, v23
	v_and_b32_e32 v31, 0xffff0000, v23
	v_lshlrev_b32_e32 v32, 16, v24
	v_and_b32_e32 v33, 0xffff0000, v24
	v_max3_f32 v7, v7, |v30|, |v31|
	v_lshlrev_b32_e32 v40, 16, v25
	v_and_b32_e32 v41, 0xffff0000, v25
	v_max3_f32 v7, v7, |v32|, |v33|
	v_max3_f32 v9, v7, |v40|, |v41|
	ds_bpermute_b32 v26, v233, v9
	s_waitcnt lgkmcnt(1)
	v_add_f32_e32 v6, v6, v8
	ds_bpermute_b32 v7, v216, v6
	global_store_dwordx4 v[44:45], v[22:25], off offset:256
	s_waitcnt lgkmcnt(1)
	v_max_f32_e32 v8, v26, v26
	v_max_f32_e32 v8, v9, v8
	ds_bpermute_b32 v9, v216, v8
	s_and_saveexec_b64 s[42:43], s[0:1]
	s_cbranch_execz .LBB0_2780
	s_waitcnt lgkmcnt(0)
	v_max_f32_e32 v9, v9, v9
	v_max_f32_e32 v8, v8, v8
	v_add_f32_e32 v23, v6, v7
	v_lshlrev_b64 v[6:7], 7, v[36:37]
	v_max_f32_e32 v22, v8, v9
	v_lshl_add_u64 v[8:9], s[26:27], 0, v[6:7]
	s_lshl_b64 s[82:83], s[40:41], 2
	v_lshl_add_u64 v[6:7], s[28:29], 0, v[6:7]
	v_lshl_add_u64 v[8:9], v[8:9], 0, s[82:83]
	s_lshl_b32 s12, s63, 2
	v_lshl_add_u64 v[6:7], v[6:7], 0, s[82:83]
	v_lshl_add_u64 v[8:9], v[8:9], 0, s[12:13]
	v_lshl_add_u64 v[6:7], v[6:7], 0, s[12:13]
	global_store_dword v[8:9], v23, off
	global_store_dword v[6:7], v22, off
.LBB0_2780:
	s_or_b64 exec, exec, s[42:43]
	v_or_b32_e32 v36, 48, v176
	v_ashrrev_i32_e32 v37, 31, v36
	s_waitcnt lgkmcnt(1)
	v_lshlrev_b64 v[6:7], 13, v[36:37]
	v_lshl_add_u64 v[6:7], s[16:17], 0, v[6:7]
	v_lshl_add_u64 v[40:41], v[90:91], 2, v[6:7]
	global_load_dwordx4 v[26:29], v[40:41], off offset:16 nt
	global_load_dwordx4 v[30:33], v[40:41], off nt
	s_waitcnt lgkmcnt(0)
	global_load_dwordx4 v[6:9], v[40:41], off offset:528 nt
	global_load_dwordx4 v[22:25], v[40:41], off offset:512 nt
	v_lshl_add_u64 v[42:43], v[34:35], 2, s[18:19]
	s_nop 1
	v_mov_b32_e32 v42, v246
	v_lshlrev_b64 v[44:45], 12, v[34:35]
	v_lshl_add_u64 v[44:45], s[22:23], 0, v[44:45]
	v_lshl_add_u64 v[44:45], v[90:91], 1, v[44:45]
	s_waitcnt vmcnt(12)
	v_pk_mul_f32 v[68:69], v[42:43], v[68:69] op_sel_hi:[0,1]
	v_pk_mul_f32 v[64:65], v[42:43], v[64:65] op_sel_hi:[0,1]
	v_pk_mul_f32 v[62:63], v[42:43], v[62:63] op_sel_hi:[0,1]
	v_pk_mul_f32 v[66:67], v[42:43], v[66:67] op_sel_hi:[0,1]
	v_pk_mul_f32 v[74:75], v[42:43], v[74:75] op_sel_hi:[0,1]
	v_pk_mul_f32 v[70:71], v[42:43], v[70:71] op_sel_hi:[0,1]
	v_pk_fma_f32 v[14:15], v[94:95], v[68:69], v[14:15]
	v_pk_mul_f32 v[76:77], v[42:43], v[76:77] op_sel_hi:[0,1]
	v_pk_mul_f32 v[42:43], v[42:43], v[72:73] op_sel_hi:[0,1]
	v_pk_fma_f32 v[20:21], v[86:87], v[62:63], v[20:21]
	v_pk_fma_f32 v[18:19], v[88:89], v[64:65], v[18:19]
	v_pk_fma_f32 v[16:17], v[92:93], v[66:67], v[16:17]
	v_pk_fma_f32 v[12:13], v[104:105], v[70:71], v[12:13]
	v_pk_fma_f32 v[10:11], v[106:107], v[74:75], v[10:11]
	v_mul_f32_e32 v112, v15, v15
	v_pk_fma_f32 v[4:5], v[110:111], v[42:43], v[4:5]
	v_pk_fma_f32 v[2:3], v[108:109], v[76:77], v[2:3]
	global_store_dwordx4 v[38:39], v[18:21], off nt
	global_store_dwordx4 v[38:39], v[14:17], off offset:16 nt
	v_mul_f32_e32 v76, v19, v19
	v_mul_f32_e32 v77, v21, v21
	v_mul_f32_e32 v113, v17, v17
	v_pk_mul_f32 v[42:43], v[78:79], v[20:21]
	v_pk_mul_f32 v[62:63], v[80:81], v[18:19]
	v_pk_mul_f32 v[66:67], v[84:85], v[14:15]
	v_mul_f32_e32 v19, v11, v11
	v_mul_f32_e32 v21, v13, v13
	v_fmac_f32_e32 v112, v14, v14
	v_cvt_pk_bf16_f32 v14, v62, v63
	v_pk_mul_f32 v[64:65], v[82:83], v[16:17]
	v_mul_f32_e32 v114, v3, v3
	v_mul_f32_e32 v115, v5, v5
	v_fmac_f32_e32 v76, v18, v18
	v_fmac_f32_e32 v77, v20, v20
	v_fmac_f32_e32 v113, v16, v16
	v_cvt_pk_bf16_f32 v15, v42, v43
	v_cvt_pk_bf16_f32 v16, v66, v67
	v_cvt_pk_bf16_f32 v17, v64, v65
	v_fmac_f32_e32 v19, v10, v10
	v_fmac_f32_e32 v21, v12, v12
	global_store_dwordx4 v[44:45], v[14:17], off
	v_lshlrev_b32_e32 v20, 16, v14
	v_pk_mul_f32 v[72:73], v[100:101], v[4:5]
	v_and_b32_e32 v14, 0xffff0000, v14
	v_pk_mul_f32 v[74:75], v[102:103], v[2:3]
	v_fmac_f32_e32 v114, v2, v2
	v_fmac_f32_e32 v115, v4, v4
	v_add_f32_e32 v18, v76, v77
	v_lshlrev_b32_e32 v42, 16, v15
	v_and_b32_e32 v15, 0xffff0000, v15
	global_store_dwordx4 v[38:39], v[10:13], off offset:512 nt
	global_store_dwordx4 v[38:39], v[2:5], off offset:528 nt
	v_lshlrev_b32_e32 v43, 16, v16
	v_and_b32_e32 v16, 0xffff0000, v16
	v_add_f32_e32 v2, v19, v21
	v_max3_f32 v4, |v20|, 0, |v14|
	v_add_f32_e32 v3, v112, v18
	v_add_f32_e32 v2, v114, v2
	v_max3_f32 v4, v4, |v42|, |v15|
	v_lshlrev_b32_e32 v62, 16, v17
	v_and_b32_e32 v17, 0xffff0000, v17
	v_add_f32_e32 v3, v113, v3
	v_add_f32_e32 v2, v115, v2
	v_max3_f32 v4, v4, |v43|, |v16|
	v_pk_mul_f32 v[70:71], v[98:99], v[10:11]
	v_add_f32_e32 v2, v3, v2
	v_cvt_pk_bf16_f32 v10, v70, v71
	v_max3_f32 v3, v4, |v62|, |v17|
	v_lshlrev_b32_e32 v5, 16, v10
	v_and_b32_e32 v14, 0xffff0000, v10
	v_pk_mul_f32 v[68:69], v[96:97], v[12:13]
	v_max3_f32 v3, v3, |v5|, |v14|
	v_cvt_pk_bf16_f32 v11, v68, v69
	v_cvt_pk_bf16_f32 v12, v74, v75
	v_cvt_pk_bf16_f32 v13, v72, v73
	ds_bpermute_b32 v4, v233, v2
	v_lshlrev_b32_e32 v18, 16, v11
	v_and_b32_e32 v19, 0xffff0000, v11
	v_lshlrev_b32_e32 v20, 16, v12
	v_and_b32_e32 v21, 0xffff0000, v12
	v_max3_f32 v3, v3, |v18|, |v19|
	v_lshlrev_b32_e32 v38, 16, v13
	v_and_b32_e32 v39, 0xffff0000, v13
	v_max3_f32 v3, v3, |v20|, |v21|
	v_max3_f32 v5, v3, |v38|, |v39|
	ds_bpermute_b32 v14, v233, v5
	s_waitcnt lgkmcnt(1)
	v_add_f32_e32 v2, v2, v4
	ds_bpermute_b32 v3, v216, v2
	global_store_dwordx4 v[44:45], v[10:13], off offset:256
	s_waitcnt lgkmcnt(1)
	v_max_f32_e32 v4, v14, v14
	v_max_f32_e32 v4, v5, v4
	ds_bpermute_b32 v5, v216, v4
	s_and_saveexec_b64 s[42:43], s[0:1]
	s_cbranch_execz .LBB0_2782
	s_waitcnt lgkmcnt(0)
	v_max_f32_e32 v5, v5, v5
	v_max_f32_e32 v4, v4, v4
	v_add_f32_e32 v11, v2, v3
	v_lshlrev_b64 v[2:3], 7, v[34:35]
	v_max_f32_e32 v10, v4, v5
	v_lshl_add_u64 v[4:5], s[26:27], 0, v[2:3]
	s_lshl_b64 s[82:83], s[40:41], 2
	v_lshl_add_u64 v[2:3], s[28:29], 0, v[2:3]
	v_lshl_add_u64 v[4:5], v[4:5], 0, s[82:83]
	s_lshl_b32 s12, s63, 2
	v_lshl_add_u64 v[2:3], v[2:3], 0, s[82:83]
	v_lshl_add_u64 v[4:5], v[4:5], 0, s[12:13]
	v_lshl_add_u64 v[2:3], v[2:3], 0, s[12:13]
	global_store_dword v[4:5], v11, off
	global_store_dword v[2:3], v10, off
.LBB0_2782:
	s_or_b64 exec, exec, s[42:43]
	s_waitcnt lgkmcnt(1)
	v_lshl_add_u64 v[2:3], v[36:37], 2, s[18:19]
	s_nop 1
	v_mov_b32_e32 v2, v247
	s_waitcnt lgkmcnt(0)
	v_lshlrev_b64 v[4:5], 12, v[36:37]
	v_lshl_add_u64 v[4:5], s[22:23], 0, v[4:5]
	v_lshl_add_u64 v[18:19], v[90:91], 1, v[4:5]
	s_waitcnt vmcnt(8)
	v_pk_mul_f32 v[10:11], v[2:3], v[48:49] op_sel_hi:[0,1]
	v_pk_mul_f32 v[4:5], v[2:3], v[46:47] op_sel_hi:[0,1]
	v_pk_mul_f32 v[14:15], v[2:3], v[52:53] op_sel_hi:[0,1]
	v_pk_mul_f32 v[12:13], v[2:3], v[50:51] op_sel_hi:[0,1]
	v_pk_mul_f32 v[20:21], v[2:3], v[58:59] op_sel_hi:[0,1]
	v_pk_mul_f32 v[16:17], v[2:3], v[54:55] op_sel_hi:[0,1]
	v_pk_mul_f32 v[34:35], v[2:3], v[60:61] op_sel_hi:[0,1]
	v_pk_mul_f32 v[38:39], v[2:3], v[56:57] op_sel_hi:[0,1]
	v_pk_fma_f32 v[2:3], v[88:89], v[10:11], v[30:31]
	v_pk_fma_f32 v[4:5], v[86:87], v[4:5], v[32:33]
	v_pk_fma_f32 v[12:13], v[92:93], v[12:13], v[28:29]
	v_pk_fma_f32 v[8:9], v[110:111], v[38:39], v[8:9]
	v_mul_f32_e32 v38, v3, v3
	v_pk_fma_f32 v[10:11], v[94:95], v[14:15], v[26:27]
	v_pk_fma_f32 v[14:15], v[106:107], v[20:21], v[22:23]
	global_store_dwordx4 v[40:41], v[2:5], off nt
	global_store_dwordx4 v[40:41], v[10:13], off offset:16 nt
	v_mul_f32_e32 v39, v5, v5
	v_mul_f32_e32 v43, v13, v13
	v_pk_mul_f32 v[22:23], v[80:81], v[2:3]
	v_fmac_f32_e32 v38, v2, v2
	v_cvt_pk_bf16_f32 v2, v22, v23
	v_pk_fma_f32 v[16:17], v[104:105], v[16:17], v[24:25]
	v_pk_mul_f32 v[20:21], v[78:79], v[4:5]
	v_pk_mul_f32 v[24:25], v[82:83], v[12:13]
	v_pk_mul_f32 v[26:27], v[84:85], v[10:11]
	v_fmac_f32_e32 v39, v4, v4
	v_fmac_f32_e32 v43, v12, v12
	v_cvt_pk_bf16_f32 v3, v20, v21
	v_cvt_pk_bf16_f32 v4, v26, v27
	v_cvt_pk_bf16_f32 v5, v24, v25
	global_store_dwordx4 v[18:19], v[2:5], off
	v_lshlrev_b32_e32 v12, 16, v2
	v_lshlrev_b32_e32 v20, 16, v3
	v_and_b32_e32 v2, 0xffff0000, v2
	v_and_b32_e32 v3, 0xffff0000, v3
	v_max3_f32 v2, |v12|, 0, |v2|
	v_pk_fma_f32 v[6:7], v[108:109], v[34:35], v[6:7]
	v_mul_f32_e32 v42, v11, v11
	v_mul_f32_e32 v11, v15, v15
	v_mul_f32_e32 v13, v17, v17
	v_lshlrev_b32_e32 v21, 16, v4
	v_and_b32_e32 v4, 0xffff0000, v4
	v_max3_f32 v2, v2, |v20|, |v3|
	v_mul_f32_e32 v44, v7, v7
	v_fmac_f32_e32 v11, v14, v14
	v_fmac_f32_e32 v13, v16, v16
	v_lshlrev_b32_e32 v22, 16, v5
	v_and_b32_e32 v5, 0xffff0000, v5
	v_max3_f32 v2, v2, |v21|, |v4|
	v_pk_mul_f32 v[30:31], v[98:99], v[14:15]
	v_pk_mul_f32 v[34:35], v[102:103], v[6:7]
	v_fmac_f32_e32 v44, v6, v6
	global_store_dwordx4 v[40:41], v[14:17], off offset:512 nt
	global_store_dwordx4 v[40:41], v[6:9], off offset:528 nt
	v_add_f32_e32 v11, v11, v13
	v_max3_f32 v2, v2, |v22|, |v5|
	v_cvt_pk_bf16_f32 v6, v30, v31
	v_mul_f32_e32 v45, v9, v9
	v_lshlrev_b32_e32 v12, 16, v6
	v_and_b32_e32 v13, 0xffff0000, v6
	v_pk_mul_f32 v[28:29], v[96:97], v[16:17]
	v_fmac_f32_e32 v42, v10, v10
	v_add_f32_e32 v10, v38, v39
	v_cvt_pk_bf16_f32 v7, v28, v29
	v_max3_f32 v2, v2, |v12|, |v13|
	v_lshlrev_b32_e32 v14, 16, v7
	v_and_b32_e32 v15, 0xffff0000, v7
	v_pk_mul_f32 v[32:33], v[100:101], v[8:9]
	v_fmac_f32_e32 v45, v8, v8
	v_cvt_pk_bf16_f32 v8, v34, v35
	v_add_f32_e32 v10, v42, v10
	v_add_f32_e32 v11, v44, v11
	v_lshlrev_b32_e32 v16, 16, v8
	v_and_b32_e32 v17, 0xffff0000, v8
	v_max3_f32 v2, v2, |v14|, |v15|
	v_cvt_pk_bf16_f32 v9, v32, v33
	v_add_f32_e32 v10, v43, v10
	v_lshlrev_b32_e32 v23, 16, v9
	v_and_b32_e32 v24, 0xffff0000, v9
	v_add_f32_e32 v3, v45, v11
	v_max3_f32 v2, v2, |v16|, |v17|
	v_add_f32_e32 v3, v10, v3
	v_max3_f32 v5, v2, |v23|, |v24|
	ds_bpermute_b32 v4, v233, v3
	ds_bpermute_b32 v10, v233, v5
	global_store_dwordx4 v[18:19], v[6:9], off offset:256
	s_waitcnt lgkmcnt(1)
	v_add_f32_e32 v2, v3, v4
	s_waitcnt lgkmcnt(0)
	v_max_f32_e32 v4, v10, v10
	v_max_f32_e32 v4, v5, v4
	ds_bpermute_b32 v3, v216, v2
	ds_bpermute_b32 v5, v216, v4
	s_and_saveexec_b64 s[42:43], s[0:1]
	s_cbranch_execz .LBB0_2784
	s_waitcnt lgkmcnt(0)
	v_max_f32_e32 v5, v5, v5
	v_max_f32_e32 v4, v4, v4
	v_add_f32_e32 v7, v2, v3
	v_lshlrev_b64 v[2:3], 7, v[36:37]
	v_max_f32_e32 v6, v4, v5
	v_lshl_add_u64 v[4:5], s[26:27], 0, v[2:3]
	s_lshl_b64 s[40:41], s[40:41], 2
	v_lshl_add_u64 v[2:3], s[28:29], 0, v[2:3]
	v_lshl_add_u64 v[4:5], v[4:5], 0, s[40:41]
	s_lshl_b32 s12, s63, 2
	v_lshl_add_u64 v[2:3], v[2:3], 0, s[40:41]
	v_lshl_add_u64 v[4:5], v[4:5], 0, s[12:13]
	v_lshl_add_u64 v[2:3], v[2:3], 0, s[12:13]
	global_store_dword v[4:5], v7, off
	global_store_dword v[2:3], v6, off

.LBB0_3617:
	s_lshr_b32 s40, s69, 4
	s_add_i32 s40, s40, -1
	s_cmp_gt_i32 s69, 31
	s_cselect_b32 s40, s40, 0
	v_lshl_or_b32 v90, s12, 8, v230
	s_mul_i32 s43, s40, 0xc000
	s_mul_hi_i32 s42, s40, 0xc000
	s_add_u32 s40, s55, s43
	v_ashrrev_i32_e32 v91, 31, v90
	s_addc_u32 s41, s56, s42
	v_lshlrev_b64 v[36:37], 2, v[90:91]
	v_lshl_add_u64 v[26:27], s[40:41], 0, v[36:37]
	v_lshl_add_u64 v[28:29], s[20:21], 0, v[36:37]
	s_waitcnt lgkmcnt(0)
	global_load_dwordx4 v[2:5], v[26:27], off offset:16
	global_load_dwordx4 v[6:9], v[26:27], off
	global_load_dwordx4 v[10:13], v[28:29], off offset:16
	global_load_dwordx4 v[14:17], v[28:29], off
	s_add_u32 s40, s48, s43
	v_lshl_add_u64 v[30:31], s[24:25], 0, v[36:37]
	s_addc_u32 s41, s49, s42
	v_lshl_add_u64 v[32:33], s[40:41], 0, v[36:37]
	v_lshl_add_u32 v210, s69, 8, v228
	v_ashrrev_i32_e32 v211, 31, v210
	v_or_b32_e32 v34, 16, v210
	v_ashrrev_i32_e32 v35, 31, v34
	s_lshl_b32 s40, s12, 2
	s_ashr_i32 s41, s40, 31
	s_waitcnt vmcnt(0)
	v_pk_mul_f32 v[92:93], v[4:5], v[12:13]
	v_pk_mul_f32 v[86:87], v[8:9], v[16:17]
	v_pk_mul_f32 v[88:89], v[6:7], v[14:15]
	global_load_dwordx4 v[6:9], v[30:31], off offset:16
	global_load_dwordx4 v[14:17], v[30:31], off
	global_load_dwordx4 v[18:21], v[32:33], off offset:16
	global_load_dwordx4 v[22:25], v[32:33], off
	v_pk_mul_f32 v[94:95], v[2:3], v[10:11]
	s_waitcnt vmcnt(0)
	v_pk_add_f32 v[2:3], v[20:21], 1.0 op_sel_hi:[1,0]
	v_pk_add_f32 v[24:25], v[24:25], 1.0 op_sel_hi:[1,0]
	v_pk_add_f32 v[22:23], v[22:23], 1.0 op_sel_hi:[1,0]
	v_pk_add_f32 v[4:5], v[18:19], 1.0 op_sel_hi:[1,0]
	v_pk_mul_f32 v[78:79], v[16:17], v[24:25]
	v_pk_mul_f32 v[80:81], v[14:15], v[22:23]
	v_pk_mul_f32 v[82:83], v[8:9], v[2:3]
	v_pk_mul_f32 v[84:85], v[6:7], v[4:5]
	global_load_dwordx4 v[2:5], v[26:27], off offset:528
	global_load_dwordx4 v[6:9], v[26:27], off offset:512
	global_load_dwordx4 v[10:13], v[28:29], off offset:528
	global_load_dwordx4 v[14:17], v[28:29], off offset:512
	s_waitcnt vmcnt(0)
	v_pk_mul_f32 v[108:109], v[2:3], v[10:11]
	v_pk_mul_f32 v[104:105], v[8:9], v[16:17]
	v_pk_mul_f32 v[106:107], v[6:7], v[14:15]
	global_load_dwordx4 v[6:9], v[30:31], off offset:528
	global_load_dwordx4 v[14:17], v[30:31], off offset:512
	global_load_dwordx4 v[18:21], v[32:33], off offset:528
	global_load_dwordx4 v[22:25], v[32:33], off offset:512
	v_pk_mul_f32 v[110:111], v[4:5], v[12:13]
	s_waitcnt vmcnt(0)
	v_pk_add_f32 v[2:3], v[20:21], 1.0 op_sel_hi:[1,0]
	s_nop 0
	v_pk_mul_f32 v[100:101], v[8:9], v[2:3]
	v_lshlrev_b64 v[2:3], 13, v[210:211]
	v_lshl_add_u64 v[2:3], s[16:17], 0, v[2:3]
	v_lshl_add_u64 v[38:39], v[2:3], 0, v[36:37]
	v_lshlrev_b64 v[2:3], 13, v[34:35]
	v_lshl_add_u64 v[2:3], s[16:17], 0, v[2:3]
	v_pk_add_f32 v[24:25], v[24:25], 1.0 op_sel_hi:[1,0]
	v_pk_add_f32 v[22:23], v[22:23], 1.0 op_sel_hi:[1,0]
	v_pk_add_f32 v[4:5], v[18:19], 1.0 op_sel_hi:[1,0]
	v_lshl_add_u64 v[36:37], v[2:3], 0, v[36:37]
	v_pk_mul_f32 v[96:97], v[16:17], v[24:25]
	v_pk_mul_f32 v[98:99], v[14:15], v[22:23]
	v_pk_mul_f32 v[102:103], v[6:7], v[4:5]
	v_lshl_add_u64 v[196:197], v[210:211], 2, s[18:19]
	global_load_dword v240, v[196:197], off
	global_load_dword v241, v[196:197], off offset:64
	global_load_dword v242, v[196:197], off offset:128
	global_load_dword v243, v[196:197], off offset:192
	global_load_dword v244, v[196:197], off offset:512
	global_load_dword v245, v[196:197], off offset:576
	global_load_dword v246, v[196:197], off offset:640
	global_load_dword v247, v[196:197], off offset:704
	global_load_dwordx4 v[22:25], v[38:39], off offset:16 nt
	global_load_dwordx4 v[30:33], v[38:39], off nt
	global_load_dwordx4 v[18:21], v[38:39], off offset:528 nt
	global_load_dwordx4 v[26:29], v[38:39], off offset:512 nt
	global_load_dwordx4 v[10:13], v[36:37], off offset:16 nt
	global_load_dwordx4 v[14:17], v[36:37], off nt
	global_load_dwordx4 v[2:5], v[36:37], off offset:528 nt
	global_load_dwordx4 v[6:9], v[36:37], off offset:512 nt
	v_lshl_add_u64 v[196:197], v[210:211], 2, s[18:19]
	s_nop 0
	v_and_b32_e32 v44, 64, v232
	v_xor_b32_e32 v41, 16, v232
	v_add_u32_e32 v234, 64, v44
	v_cmp_lt_i32_e32 vcc, v41, v234
	v_lshlrev_b64 v[42:43], 12, v[210:211]
	v_lshl_add_u64 v[42:43], s[22:23], 0, v[42:43]
	v_cndmask_b32_e32 v41, v232, v41, vcc
	v_lshlrev_b32_e32 v233, 2, v41
	v_lshl_add_u64 v[42:43], v[90:91], 1, v[42:43]
	s_waitcnt vmcnt(4)
	v_mov_b32_e32 v40, v240
	v_pk_mul_f32 v[44:45], v[40:41], v[214:215] op_sel_hi:[0,1]
	v_pk_mul_f32 v[212:213], v[40:41], v[212:213] op_sel_hi:[0,1]
	v_pk_mul_f32 v[214:215], v[40:41], v[218:219] op_sel_hi:[0,1]
	v_pk_mul_f32 v[218:219], v[40:41], v[222:223] op_sel_hi:[0,1]
	v_pk_mul_f32 v[220:221], v[40:41], v[220:221] op_sel_hi:[0,1]
	v_pk_mul_f32 v[216:217], v[40:41], v[216:217] op_sel_hi:[0,1]
	v_pk_mul_f32 v[222:223], v[40:41], v[226:227] op_sel_hi:[0,1]
	v_pk_mul_f32 v[40:41], v[40:41], v[224:225] op_sel_hi:[0,1]
	v_pk_fma_f32 v[32:33], v[86:87], v[212:213], v[32:33]
	v_pk_fma_f32 v[30:31], v[88:89], v[44:45], v[30:31]
	v_pk_fma_f32 v[28:29], v[104:105], v[220:221], v[28:29]
	v_pk_fma_f32 v[26:27], v[106:107], v[218:219], v[26:27]
	v_pk_fma_f32 v[24:25], v[92:93], v[216:217], v[24:25]
	v_pk_fma_f32 v[22:23], v[94:95], v[214:215], v[22:23]
	v_pk_fma_f32 v[20:21], v[110:111], v[40:41], v[20:21]
	v_pk_fma_f32 v[18:19], v[108:109], v[222:223], v[18:19]
	global_store_dwordx4 v[38:39], v[30:33], off nt
	global_store_dwordx4 v[38:39], v[22:25], off offset:16 nt
	v_mul_f32_e32 v224, v31, v31
	v_mul_f32_e32 v225, v33, v33
	v_pk_mul_f32 v[40:41], v[78:79], v[32:33]
	v_pk_mul_f32 v[44:45], v[80:81], v[30:31]
	v_mul_f32_e32 v31, v27, v27
	v_mul_f32_e32 v33, v29, v29
	v_mul_f32_e32 v226, v23, v23
	v_mul_f32_e32 v227, v25, v25
	v_mul_f32_e32 v235, v19, v19
	v_fmac_f32_e32 v224, v30, v30
	v_fmac_f32_e32 v225, v32, v32
	v_fmac_f32_e32 v31, v26, v26
	v_fmac_f32_e32 v33, v28, v28
	v_pk_mul_f32 v[212:213], v[82:83], v[24:25]
	v_pk_mul_f32 v[214:215], v[84:85], v[22:23]
	v_mul_f32_e32 v236, v21, v21
	v_pk_mul_f32 v[222:223], v[102:103], v[18:19]
	v_fmac_f32_e32 v226, v22, v22
	v_fmac_f32_e32 v227, v24, v24
	v_cvt_pk_bf16_f32 v22, v44, v45
	v_cvt_pk_bf16_f32 v23, v40, v41
	v_cvt_pk_bf16_f32 v24, v214, v215
	v_cvt_pk_bf16_f32 v25, v212, v213
	v_fmac_f32_e32 v235, v18, v18
	v_add_f32_e32 v30, v224, v225
	global_store_dwordx4 v[42:43], v[22:25], off
	v_lshlrev_b32_e32 v32, 16, v22
	v_and_b32_e32 v40, 0xffff0000, v22
	global_store_dwordx4 v[38:39], v[26:29], off offset:512 nt
	global_store_dwordx4 v[38:39], v[18:21], off offset:528 nt
	v_pk_mul_f32 v[220:221], v[100:101], v[20:21]
	v_fmac_f32_e32 v236, v20, v20
	v_add_f32_e32 v18, v31, v33
	v_lshlrev_b32_e32 v41, 16, v23
	v_and_b32_e32 v44, 0xffff0000, v23
	v_add_f32_e32 v19, v226, v30
	v_max3_f32 v20, |v32|, 0, |v40|
	v_add_f32_e32 v18, v235, v18
	v_lshlrev_b32_e32 v45, 16, v24
	v_and_b32_e32 v212, 0xffff0000, v24
	v_add_f32_e32 v19, v227, v19
	v_max3_f32 v20, v20, |v41|, |v44|
	v_add_f32_e32 v18, v236, v18
	v_lshlrev_b32_e32 v213, 16, v25
	v_and_b32_e32 v214, 0xffff0000, v25
	v_max3_f32 v20, v20, |v45|, |v212|
	v_add_f32_e32 v18, v19, v18
	v_pk_mul_f32 v[218:219], v[98:99], v[26:27]
	v_max3_f32 v19, v20, |v213|, |v214|
	v_cvt_pk_bf16_f32 v22, v218, v219
	ds_bpermute_b32 v20, v233, v18
	v_lshlrev_b32_e32 v21, 16, v22
	v_and_b32_e32 v26, 0xffff0000, v22
	v_pk_mul_f32 v[216:217], v[96:97], v[28:29]
	v_max3_f32 v19, v19, |v21|, |v26|
	v_cvt_pk_bf16_f32 v23, v216, v217
	v_cvt_pk_bf16_f32 v24, v222, v223
	v_cvt_pk_bf16_f32 v25, v220, v221
	s_waitcnt lgkmcnt(0)
	v_add_f32_e32 v18, v18, v20
	v_lshlrev_b32_e32 v27, 16, v23
	v_and_b32_e32 v28, 0xffff0000, v23
	v_lshlrev_b32_e32 v29, 16, v24
	v_and_b32_e32 v30, 0xffff0000, v24
	v_max3_f32 v19, v19, |v27|, |v28|
	v_max3_f32 v19, v19, |v29|, |v30|
	v_lshlrev_b32_e32 v21, 16, v25
	v_and_b32_e32 v26, 0xffff0000, v25
	v_max3_f32 v21, v19, |v21|, |v26|
	ds_bpermute_b32 v20, v233, v21
	v_xor_b32_e32 v19, 32, v232
	v_cmp_lt_i32_e32 vcc, v19, v234
	global_store_dwordx4 v[42:43], v[22:25], off offset:256
	s_waitcnt lgkmcnt(0)
	v_max_f32_e32 v20, v20, v20
	v_cndmask_b32_e32 v19, v232, v19, vcc
	v_lshlrev_b32_e32 v216, 2, v19
	v_max_f32_e32 v20, v21, v20
	ds_bpermute_b32 v19, v216, v18
	ds_bpermute_b32 v21, v216, v20
	s_and_saveexec_b64 s[42:43], s[0:1]
	s_cbranch_execz .LBB0_3619
	s_waitcnt lgkmcnt(0)
	v_max_f32_e32 v21, v21, v21
	v_max_f32_e32 v20, v20, v20
	v_add_f32_e32 v23, v18, v19
	v_lshlrev_b64 v[18:19], 7, v[210:211]
	v_max_f32_e32 v22, v20, v21
	v_lshl_add_u64 v[20:21], s[26:27], 0, v[18:19]
	s_lshl_b64 s[70:71], s[40:41], 2
	v_lshl_add_u64 v[18:19], s[28:29], 0, v[18:19]
	v_lshl_add_u64 v[20:21], v[20:21], 0, s[70:71]
	s_lshl_b32 s12, s59, 2
	v_lshl_add_u64 v[18:19], v[18:19], 0, s[70:71]
	v_lshl_add_u64 v[20:21], v[20:21], 0, s[12:13]
	v_lshl_add_u64 v[18:19], v[18:19], 0, s[12:13]
	global_store_dword v[20:21], v23, off
	global_store_dword v[18:19], v22, off
.LBB0_3619:
	s_or_b64 exec, exec, s[42:43]
	v_or_b32_e32 v212, 32, v210
	v_ashrrev_i32_e32 v213, 31, v212
	s_waitcnt lgkmcnt(1)
	v_lshlrev_b64 v[18:19], 13, v[212:213]
	v_lshl_add_u64 v[18:19], s[16:17], 0, v[18:19]
	v_lshl_add_u64 v[214:215], v[90:91], 2, v[18:19]
	global_load_dwordx4 v[26:29], v[214:215], off offset:16 nt
	global_load_dwordx4 v[30:33], v[214:215], off nt
	s_waitcnt lgkmcnt(0)
	global_load_dwordx4 v[18:21], v[214:215], off offset:528 nt
	global_load_dwordx4 v[22:25], v[214:215], off offset:512 nt
	v_lshl_add_u64 v[38:39], v[34:35], 2, s[18:19]
	s_nop 1
	v_mov_b32_e32 v38, v241
	v_lshlrev_b64 v[40:41], 12, v[34:35]
	v_lshl_add_u64 v[40:41], s[22:23], 0, v[40:41]
	v_lshl_add_u64 v[40:41], v[90:91], 1, v[40:41]
	s_waitcnt vmcnt(12)
	v_pk_mul_f32 v[44:45], v[38:39], v[192:193] op_sel_hi:[0,1]
	v_pk_mul_f32 v[192:193], v[38:39], v[200:201] op_sel_hi:[0,1]
	v_pk_mul_f32 v[42:43], v[38:39], v[194:195] op_sel_hi:[0,1]
	v_pk_mul_f32 v[194:195], v[38:39], v[198:199] op_sel_hi:[0,1]
	v_pk_mul_f32 v[198:199], v[38:39], v[206:207] op_sel_hi:[0,1]
	v_pk_mul_f32 v[200:201], v[38:39], v[202:203] op_sel_hi:[0,1]
	v_pk_fma_f32 v[10:11], v[94:95], v[192:193], v[10:11]
	v_pk_mul_f32 v[202:203], v[38:39], v[208:209] op_sel_hi:[0,1]
	v_pk_mul_f32 v[38:39], v[38:39], v[204:205] op_sel_hi:[0,1]
	v_pk_fma_f32 v[16:17], v[86:87], v[44:45], v[16:17]
	v_pk_fma_f32 v[14:15], v[88:89], v[42:43], v[14:15]
	v_pk_fma_f32 v[12:13], v[92:93], v[194:195], v[12:13]
	v_pk_fma_f32 v[8:9], v[104:105], v[200:201], v[8:9]
	v_pk_fma_f32 v[6:7], v[106:107], v[198:199], v[6:7]
	v_mul_f32_e32 v206, v11, v11
	v_pk_fma_f32 v[4:5], v[110:111], v[38:39], v[4:5]
	v_pk_fma_f32 v[2:3], v[108:109], v[202:203], v[2:3]
	global_store_dwordx4 v[36:37], v[14:17], off nt
	global_store_dwordx4 v[36:37], v[10:13], off offset:16 nt
	v_mul_f32_e32 v204, v15, v15
	v_mul_f32_e32 v205, v17, v17
	v_mul_f32_e32 v207, v13, v13
	v_pk_mul_f32 v[38:39], v[78:79], v[16:17]
	v_pk_mul_f32 v[42:43], v[80:81], v[14:15]
	v_pk_mul_f32 v[192:193], v[84:85], v[10:11]
	v_mul_f32_e32 v15, v7, v7
	v_mul_f32_e32 v17, v9, v9
	v_fmac_f32_e32 v206, v10, v10
	v_cvt_pk_bf16_f32 v10, v42, v43
	v_pk_mul_f32 v[44:45], v[82:83], v[12:13]
	v_mul_f32_e32 v208, v3, v3
	v_mul_f32_e32 v209, v5, v5
	v_fmac_f32_e32 v204, v14, v14
	v_fmac_f32_e32 v205, v16, v16
	v_fmac_f32_e32 v207, v12, v12
	v_cvt_pk_bf16_f32 v11, v38, v39
	v_cvt_pk_bf16_f32 v12, v192, v193
	v_cvt_pk_bf16_f32 v13, v44, v45
	v_fmac_f32_e32 v15, v6, v6
	v_fmac_f32_e32 v17, v8, v8
	global_store_dwordx4 v[40:41], v[10:13], off
	v_lshlrev_b32_e32 v16, 16, v10
	v_pk_mul_f32 v[200:201], v[100:101], v[4:5]
	v_and_b32_e32 v10, 0xffff0000, v10
	v_pk_mul_f32 v[202:203], v[102:103], v[2:3]
	v_fmac_f32_e32 v208, v2, v2
	v_fmac_f32_e32 v209, v4, v4
	v_add_f32_e32 v14, v204, v205
	v_lshlrev_b32_e32 v38, 16, v11
	v_and_b32_e32 v11, 0xffff0000, v11
	global_store_dwordx4 v[36:37], v[6:9], off offset:512 nt
	global_store_dwordx4 v[36:37], v[2:5], off offset:528 nt
	v_lshlrev_b32_e32 v39, 16, v12
	v_and_b32_e32 v12, 0xffff0000, v12
	v_add_f32_e32 v2, v15, v17
	v_max3_f32 v4, |v16|, 0, |v10|
	v_add_f32_e32 v3, v206, v14
	v_add_f32_e32 v2, v208, v2
	v_max3_f32 v4, v4, |v38|, |v11|
	v_lshlrev_b32_e32 v42, 16, v13
	v_and_b32_e32 v13, 0xffff0000, v13
	v_add_f32_e32 v3, v207, v3
	v_add_f32_e32 v2, v209, v2
	v_max3_f32 v4, v4, |v39|, |v12|
	v_pk_mul_f32 v[198:199], v[98:99], v[6:7]
	v_add_f32_e32 v2, v3, v2
	v_cvt_pk_bf16_f32 v6, v198, v199
	v_max3_f32 v3, v4, |v42|, |v13|
	v_lshlrev_b32_e32 v5, 16, v6
	v_and_b32_e32 v10, 0xffff0000, v6
	v_pk_mul_f32 v[194:195], v[96:97], v[8:9]
	v_max3_f32 v3, v3, |v5|, |v10|
	v_cvt_pk_bf16_f32 v7, v194, v195
	v_cvt_pk_bf16_f32 v8, v202, v203
	v_cvt_pk_bf16_f32 v9, v200, v201
	ds_bpermute_b32 v4, v233, v2
	v_lshlrev_b32_e32 v14, 16, v7
	v_and_b32_e32 v15, 0xffff0000, v7
	v_lshlrev_b32_e32 v16, 16, v8
	v_and_b32_e32 v17, 0xffff0000, v8
	v_max3_f32 v3, v3, |v14|, |v15|
	v_lshlrev_b32_e32 v36, 16, v9
	v_and_b32_e32 v37, 0xffff0000, v9
	v_max3_f32 v3, v3, |v16|, |v17|
	v_max3_f32 v5, v3, |v36|, |v37|
	ds_bpermute_b32 v10, v233, v5
	s_waitcnt lgkmcnt(1)
	v_add_f32_e32 v2, v2, v4
	ds_bpermute_b32 v3, v216, v2
	global_store_dwordx4 v[40:41], v[6:9], off offset:256
	s_waitcnt lgkmcnt(1)
	v_max_f32_e32 v4, v10, v10
	v_max_f32_e32 v4, v5, v4
	ds_bpermute_b32 v5, v216, v4
	s_and_saveexec_b64 s[42:43], s[0:1]
	s_cbranch_execz .LBB0_3621
	s_waitcnt lgkmcnt(0)
	v_max_f32_e32 v5, v5, v5
	v_max_f32_e32 v4, v4, v4
	v_add_f32_e32 v7, v2, v3
	v_lshlrev_b64 v[2:3], 7, v[34:35]
	v_max_f32_e32 v6, v4, v5
	v_lshl_add_u64 v[4:5], s[26:27], 0, v[2:3]
	s_lshl_b64 s[70:71], s[40:41], 2
	v_lshl_add_u64 v[2:3], s[28:29], 0, v[2:3]
	v_lshl_add_u64 v[4:5], v[4:5], 0, s[70:71]
	s_lshl_b32 s12, s59, 2
	v_lshl_add_u64 v[2:3], v[2:3], 0, s[70:71]
	v_lshl_add_u64 v[4:5], v[4:5], 0, s[12:13]
	v_lshl_add_u64 v[2:3], v[2:3], 0, s[12:13]
	global_store_dword v[4:5], v7, off
	global_store_dword v[2:3], v6, off
.LBB0_3621:
	s_or_b64 exec, exec, s[42:43]
	v_or_b32_e32 v192, 48, v210
	v_ashrrev_i32_e32 v193, 31, v192
	s_waitcnt lgkmcnt(1)
	v_lshlrev_b64 v[2:3], 13, v[192:193]
	v_lshl_add_u64 v[2:3], s[16:17], 0, v[2:3]
	v_lshl_add_u64 v[194:195], v[90:91], 2, v[2:3]
	global_load_dwordx4 v[38:41], v[194:195], off offset:16 nt
	global_load_dwordx4 v[42:45], v[194:195], off nt
	global_load_dwordx4 v[6:9], v[194:195], off offset:528 nt
	global_load_dwordx4 v[34:37], v[194:195], off offset:512 nt
	v_lshl_add_u64 v[2:3], v[212:213], 2, s[18:19]
	s_nop 1
	v_mov_b32_e32 v2, v242
	s_waitcnt lgkmcnt(0)
	v_lshlrev_b64 v[4:5], 12, v[212:213]
	v_lshl_add_u64 v[4:5], s[22:23], 0, v[4:5]
	v_lshl_add_u64 v[198:199], v[90:91], 1, v[4:5]
	s_waitcnt vmcnt(12)
	v_pk_mul_f32 v[10:11], v[2:3], v[178:179] op_sel_hi:[0,1]
	v_pk_mul_f32 v[4:5], v[2:3], v[176:177] op_sel_hi:[0,1]
	v_pk_mul_f32 v[14:15], v[2:3], v[182:183] op_sel_hi:[0,1]
	v_pk_mul_f32 v[12:13], v[2:3], v[180:181] op_sel_hi:[0,1]
	v_pk_mul_f32 v[176:177], v[2:3], v[188:189] op_sel_hi:[0,1]
	v_pk_mul_f32 v[16:17], v[2:3], v[184:185] op_sel_hi:[0,1]
	v_pk_mul_f32 v[178:179], v[2:3], v[190:191] op_sel_hi:[0,1]
	v_pk_mul_f32 v[180:181], v[2:3], v[186:187] op_sel_hi:[0,1]
	v_pk_fma_f32 v[2:3], v[88:89], v[10:11], v[30:31]
	v_pk_fma_f32 v[4:5], v[86:87], v[4:5], v[32:33]
	v_pk_fma_f32 v[20:21], v[110:111], v[180:181], v[20:21]
	v_mul_f32_e32 v180, v3, v3
	v_pk_fma_f32 v[12:13], v[92:93], v[12:13], v[28:29]
	v_pk_fma_f32 v[10:11], v[94:95], v[14:15], v[26:27]
	v_pk_fma_f32 v[16:17], v[104:105], v[16:17], v[24:25]
	v_pk_fma_f32 v[14:15], v[106:107], v[176:177], v[22:23]
	global_store_dwordx4 v[214:215], v[2:5], off nt
	global_store_dwordx4 v[214:215], v[10:13], off offset:16 nt
	v_mul_f32_e32 v181, v5, v5
	v_pk_mul_f32 v[22:23], v[78:79], v[4:5]
	v_pk_mul_f32 v[24:25], v[80:81], v[2:3]
	v_fmac_f32_e32 v180, v2, v2
	v_cvt_pk_bf16_f32 v2, v24, v25
	v_pk_mul_f32 v[26:27], v[82:83], v[12:13]
	v_pk_mul_f32 v[28:29], v[84:85], v[10:11]
	v_fmac_f32_e32 v181, v4, v4
	v_cvt_pk_bf16_f32 v3, v22, v23
	v_cvt_pk_bf16_f32 v4, v28, v29
	v_cvt_pk_bf16_f32 v5, v26, v27
	global_store_dwordx4 v[198:199], v[2:5], off
	v_lshlrev_b32_e32 v23, 16, v2
	v_lshlrev_b32_e32 v24, 16, v3
	v_and_b32_e32 v2, 0xffff0000, v2
	v_and_b32_e32 v3, 0xffff0000, v3
	v_max3_f32 v2, |v23|, 0, |v2|
	v_lshlrev_b32_e32 v25, 16, v4
	v_and_b32_e32 v4, 0xffff0000, v4
	v_max3_f32 v2, v2, |v24|, |v3|
	v_pk_fma_f32 v[18:19], v[108:109], v[178:179], v[18:19]
	v_mul_f32_e32 v182, v11, v11
	v_mul_f32_e32 v183, v13, v13
	v_mul_f32_e32 v11, v15, v15
	v_mul_f32_e32 v13, v17, v17
	v_lshlrev_b32_e32 v26, 16, v5
	v_and_b32_e32 v5, 0xffff0000, v5
	v_max3_f32 v2, v2, |v25|, |v4|
	v_mul_f32_e32 v184, v19, v19
	v_pk_mul_f32 v[30:31], v[96:97], v[16:17]
	v_pk_mul_f32 v[32:33], v[98:99], v[14:15]
	v_fmac_f32_e32 v182, v10, v10
	v_fmac_f32_e32 v11, v14, v14
	v_fmac_f32_e32 v13, v16, v16
	global_store_dwordx4 v[214:215], v[14:17], off offset:512 nt
	global_store_dwordx4 v[214:215], v[18:21], off offset:528 nt
	v_cvt_pk_bf16_f32 v10, v32, v33
	v_max3_f32 v2, v2, |v26|, |v5|
	v_lshlrev_b32_e32 v16, 16, v10
	v_and_b32_e32 v17, 0xffff0000, v10
	v_mul_f32_e32 v185, v21, v21
	v_pk_mul_f32 v[178:179], v[102:103], v[18:19]
	v_fmac_f32_e32 v184, v18, v18
	v_add_f32_e32 v22, v180, v181
	v_add_f32_e32 v14, v11, v13
	v_cvt_pk_bf16_f32 v11, v30, v31
	v_max3_f32 v2, v2, |v16|, |v17|
	v_lshlrev_b32_e32 v18, 16, v11
	v_and_b32_e32 v19, 0xffff0000, v11
	v_pk_mul_f32 v[176:177], v[100:101], v[20:21]
	v_fmac_f32_e32 v183, v12, v12
	v_fmac_f32_e32 v185, v20, v20
	v_cvt_pk_bf16_f32 v12, v178, v179
	v_add_f32_e32 v15, v182, v22
	v_add_f32_e32 v14, v184, v14
	v_lshlrev_b32_e32 v20, 16, v12
	v_and_b32_e32 v21, 0xffff0000, v12
	v_max3_f32 v2, v2, |v18|, |v19|
	v_cvt_pk_bf16_f32 v13, v176, v177
	v_add_f32_e32 v15, v183, v15
	v_lshlrev_b32_e32 v22, 16, v13
	v_and_b32_e32 v23, 0xffff0000, v13
	v_add_f32_e32 v3, v185, v14
	v_max3_f32 v2, v2, |v20|, |v21|
	v_add_f32_e32 v3, v15, v3
	v_max3_f32 v5, v2, |v22|, |v23|
	ds_bpermute_b32 v4, v233, v3
	ds_bpermute_b32 v14, v233, v5
	global_store_dwordx4 v[198:199], v[10:13], off offset:256
	s_waitcnt lgkmcnt(1)
	v_add_f32_e32 v2, v3, v4
	s_waitcnt lgkmcnt(0)
	v_max_f32_e32 v4, v14, v14
	v_max_f32_e32 v4, v5, v4
	ds_bpermute_b32 v3, v216, v2
	ds_bpermute_b32 v5, v216, v4
	s_and_saveexec_b64 s[42:43], s[0:1]
	s_cbranch_execz .LBB0_3623
	s_waitcnt lgkmcnt(0)
	v_max_f32_e32 v5, v5, v5
	v_max_f32_e32 v4, v4, v4
	v_add_f32_e32 v11, v2, v3
	v_lshlrev_b64 v[2:3], 7, v[212:213]
	v_max_f32_e32 v10, v4, v5
	v_lshl_add_u64 v[4:5], s[26:27], 0, v[2:3]
	s_lshl_b64 s[70:71], s[40:41], 2
	v_lshl_add_u64 v[2:3], s[28:29], 0, v[2:3]
	v_lshl_add_u64 v[4:5], v[4:5], 0, s[70:71]
	s_lshl_b32 s12, s59, 2
	v_lshl_add_u64 v[2:3], v[2:3], 0, s[70:71]
	v_lshl_add_u64 v[4:5], v[4:5], 0, s[12:13]
	v_lshl_add_u64 v[2:3], v[2:3], 0, s[12:13]
	global_store_dword v[4:5], v11, off
	global_store_dword v[2:3], v10, off
.LBB0_3623:
	s_or_b64 exec, exec, s[42:43]
	v_add_u32_e32 v176, 0x80, v210
	v_ashrrev_i32_e32 v177, 31, v176
	s_waitcnt lgkmcnt(1)
	v_lshlrev_b64 v[2:3], 13, v[176:177]
	v_lshl_add_u64 v[2:3], s[16:17], 0, v[2:3]
	v_lshl_add_u64 v[178:179], v[90:91], 2, v[2:3]
	global_load_dwordx4 v[14:17], v[178:179], off offset:16 nt
	global_load_dwordx4 v[18:21], v[178:179], off nt
	s_waitcnt lgkmcnt(0)
	global_load_dwordx4 v[2:5], v[178:179], off offset:528 nt
	global_load_dwordx4 v[10:13], v[178:179], off offset:512 nt
	v_lshl_add_u64 v[22:23], v[192:193], 2, s[18:19]
	s_nop 1
	v_mov_b32_e32 v22, v243
	v_lshlrev_b64 v[24:25], 12, v[192:193]
	v_lshl_add_u64 v[24:25], s[22:23], 0, v[24:25]
	v_lshl_add_u64 v[180:181], v[90:91], 1, v[24:25]
	s_waitcnt vmcnt(12)
	v_pk_mul_f32 v[26:27], v[22:23], v[162:163] op_sel_hi:[0,1]
	v_pk_mul_f32 v[24:25], v[22:23], v[160:161] op_sel_hi:[0,1]
	v_pk_mul_f32 v[30:31], v[22:23], v[166:167] op_sel_hi:[0,1]
	v_pk_mul_f32 v[28:29], v[22:23], v[164:165] op_sel_hi:[0,1]
	v_pk_mul_f32 v[160:161], v[22:23], v[172:173] op_sel_hi:[0,1]
	v_pk_mul_f32 v[32:33], v[22:23], v[168:169] op_sel_hi:[0,1]
	v_pk_mul_f32 v[162:163], v[22:23], v[174:175] op_sel_hi:[0,1]
	v_pk_mul_f32 v[164:165], v[22:23], v[170:171] op_sel_hi:[0,1]
	v_pk_fma_f32 v[24:25], v[86:87], v[24:25], v[44:45]
	v_pk_fma_f32 v[22:23], v[88:89], v[26:27], v[42:43]
	v_pk_fma_f32 v[28:29], v[92:93], v[28:29], v[40:41]
	v_pk_fma_f32 v[26:27], v[94:95], v[30:31], v[38:39]
	v_pk_fma_f32 v[32:33], v[104:105], v[32:33], v[36:37]
	v_pk_fma_f32 v[30:31], v[106:107], v[160:161], v[34:35]
	v_pk_fma_f32 v[8:9], v[110:111], v[164:165], v[8:9]
	v_pk_fma_f32 v[6:7], v[108:109], v[162:163], v[6:7]
	global_store_dwordx4 v[194:195], v[22:25], off nt
	global_store_dwordx4 v[194:195], v[26:29], off offset:16 nt
	v_mul_f32_e32 v164, v23, v23
	v_mul_f32_e32 v165, v25, v25
	v_mul_f32_e32 v166, v27, v27
	v_mul_f32_e32 v167, v29, v29
	v_pk_mul_f32 v[34:35], v[78:79], v[24:25]
	v_pk_mul_f32 v[38:39], v[82:83], v[28:29]
	v_pk_mul_f32 v[40:41], v[84:85], v[26:27]
	v_mul_f32_e32 v27, v31, v31
	v_mul_f32_e32 v29, v33, v33
	v_pk_mul_f32 v[36:37], v[80:81], v[22:23]
	v_mul_f32_e32 v168, v7, v7
	v_mul_f32_e32 v169, v9, v9
	v_fmac_f32_e32 v164, v22, v22
	v_fmac_f32_e32 v165, v24, v24
	v_fmac_f32_e32 v167, v28, v28
	v_cvt_pk_bf16_f32 v22, v36, v37
	v_cvt_pk_bf16_f32 v23, v34, v35
	v_fmac_f32_e32 v27, v30, v30
	v_fmac_f32_e32 v29, v32, v32
	v_lshlrev_b32_e32 v28, 16, v22
	v_and_b32_e32 v34, 0xffff0000, v22
	v_pk_mul_f32 v[160:161], v[100:101], v[8:9]
	v_pk_mul_f32 v[162:163], v[102:103], v[6:7]
	v_fmac_f32_e32 v166, v26, v26
	v_cvt_pk_bf16_f32 v24, v40, v41
	v_cvt_pk_bf16_f32 v25, v38, v39
	v_fmac_f32_e32 v168, v6, v6
	v_fmac_f32_e32 v169, v8, v8
	v_add_f32_e32 v26, v164, v165
	global_store_dwordx4 v[180:181], v[22:25], off
	v_lshlrev_b32_e32 v35, 16, v23
	v_and_b32_e32 v36, 0xffff0000, v23
	global_store_dwordx4 v[194:195], v[30:33], off offset:512 nt
	global_store_dwordx4 v[194:195], v[6:9], off offset:528 nt
	v_lshlrev_b32_e32 v37, 16, v24
	v_and_b32_e32 v38, 0xffff0000, v24
	v_add_f32_e32 v6, v27, v29
	v_max3_f32 v8, |v28|, 0, |v34|
	v_add_f32_e32 v7, v166, v26
	v_add_f32_e32 v6, v168, v6
	v_max3_f32 v8, v8, |v35|, |v36|
	v_lshlrev_b32_e32 v39, 16, v25
	v_and_b32_e32 v40, 0xffff0000, v25
	v_add_f32_e32 v7, v167, v7
	v_add_f32_e32 v6, v169, v6
	v_max3_f32 v8, v8, |v37|, |v38|
	v_pk_mul_f32 v[44:45], v[98:99], v[30:31]
	v_add_f32_e32 v6, v7, v6
	v_cvt_pk_bf16_f32 v22, v44, v45
	v_max3_f32 v7, v8, |v39|, |v40|
	v_lshlrev_b32_e32 v9, 16, v22
	v_and_b32_e32 v26, 0xffff0000, v22
	v_pk_mul_f32 v[42:43], v[96:97], v[32:33]
	v_max3_f32 v7, v7, |v9|, |v26|
	v_cvt_pk_bf16_f32 v23, v42, v43
	v_cvt_pk_bf16_f32 v24, v162, v163
	v_cvt_pk_bf16_f32 v25, v160, v161
	ds_bpermute_b32 v8, v233, v6
	v_lshlrev_b32_e32 v27, 16, v23
	v_and_b32_e32 v28, 0xffff0000, v23
	v_lshlrev_b32_e32 v29, 16, v24
	v_and_b32_e32 v30, 0xffff0000, v24
	v_max3_f32 v7, v7, |v27|, |v28|
	v_lshlrev_b32_e32 v31, 16, v25
	v_and_b32_e32 v32, 0xffff0000, v25
	v_max3_f32 v7, v7, |v29|, |v30|
	v_max3_f32 v9, v7, |v31|, |v32|
	ds_bpermute_b32 v26, v233, v9
	s_waitcnt lgkmcnt(1)
	v_add_f32_e32 v6, v6, v8
	ds_bpermute_b32 v7, v216, v6
	global_store_dwordx4 v[180:181], v[22:25], off offset:256
	s_waitcnt lgkmcnt(1)
	v_max_f32_e32 v8, v26, v26
	v_max_f32_e32 v8, v9, v8
	ds_bpermute_b32 v9, v216, v8
	s_and_saveexec_b64 s[42:43], s[0:1]
	s_cbranch_execz .LBB0_3625
	s_waitcnt lgkmcnt(0)
	v_max_f32_e32 v9, v9, v9
	v_max_f32_e32 v8, v8, v8
	v_add_f32_e32 v23, v6, v7
	v_lshlrev_b64 v[6:7], 7, v[192:193]
	v_max_f32_e32 v22, v8, v9
	v_lshl_add_u64 v[8:9], s[26:27], 0, v[6:7]
	s_lshl_b64 s[70:71], s[40:41], 2
	v_lshl_add_u64 v[6:7], s[28:29], 0, v[6:7]
	v_lshl_add_u64 v[8:9], v[8:9], 0, s[70:71]
	s_lshl_b32 s12, s59, 2
	v_lshl_add_u64 v[6:7], v[6:7], 0, s[70:71]
	v_lshl_add_u64 v[8:9], v[8:9], 0, s[12:13]
	v_lshl_add_u64 v[6:7], v[6:7], 0, s[12:13]
	global_store_dword v[8:9], v23, off
	global_store_dword v[6:7], v22, off
.LBB0_3625:
	s_or_b64 exec, exec, s[42:43]
	v_or_b32_e32 v36, 16, v176
	v_ashrrev_i32_e32 v37, 31, v36
	s_waitcnt lgkmcnt(1)
	v_lshlrev_b64 v[6:7], 13, v[36:37]
	v_lshl_add_u64 v[6:7], s[16:17], 0, v[6:7]
	v_lshl_add_u64 v[40:41], v[90:91], 2, v[6:7]
	global_load_dwordx4 v[26:29], v[40:41], off offset:16 nt
	global_load_dwordx4 v[30:33], v[40:41], off nt
	s_waitcnt lgkmcnt(0)
	global_load_dwordx4 v[6:9], v[40:41], off offset:528 nt
	global_load_dwordx4 v[22:25], v[40:41], off offset:512 nt
	s_nop 1
	v_mov_b32_e32 v34, v244
	v_lshlrev_b64 v[38:39], 12, v[176:177]
	v_lshl_add_u64 v[38:39], s[22:23], 0, v[38:39]
	v_lshl_add_u64 v[38:39], v[90:91], 1, v[38:39]
	s_waitcnt vmcnt(12)
	v_pk_mul_f32 v[44:45], v[34:35], v[128:129] op_sel_hi:[0,1]
	v_pk_mul_f32 v[128:129], v[34:35], v[150:151] op_sel_hi:[0,1]
	v_pk_mul_f32 v[42:43], v[34:35], v[146:147] op_sel_hi:[0,1]
	v_pk_mul_f32 v[146:147], v[34:35], v[148:149] op_sel_hi:[0,1]
	v_pk_mul_f32 v[148:149], v[34:35], v[156:157] op_sel_hi:[0,1]
	v_pk_mul_f32 v[150:151], v[34:35], v[152:153] op_sel_hi:[0,1]
	v_pk_fma_f32 v[14:15], v[94:95], v[128:129], v[14:15]
	v_pk_mul_f32 v[152:153], v[34:35], v[158:159] op_sel_hi:[0,1]
	v_pk_mul_f32 v[34:35], v[34:35], v[154:155] op_sel_hi:[0,1]
	v_pk_fma_f32 v[20:21], v[86:87], v[44:45], v[20:21]
	v_pk_fma_f32 v[18:19], v[88:89], v[42:43], v[18:19]
	v_pk_fma_f32 v[16:17], v[92:93], v[146:147], v[16:17]
	v_pk_fma_f32 v[12:13], v[104:105], v[150:151], v[12:13]
	v_pk_fma_f32 v[10:11], v[106:107], v[148:149], v[10:11]
	v_mul_f32_e32 v156, v15, v15
	v_pk_fma_f32 v[4:5], v[110:111], v[34:35], v[4:5]
	v_pk_fma_f32 v[2:3], v[108:109], v[152:153], v[2:3]
	global_store_dwordx4 v[178:179], v[18:21], off nt
	global_store_dwordx4 v[178:179], v[14:17], off offset:16 nt
	v_mul_f32_e32 v154, v19, v19
	v_mul_f32_e32 v155, v21, v21
	v_mul_f32_e32 v157, v17, v17
	v_pk_mul_f32 v[34:35], v[78:79], v[20:21]
	v_pk_mul_f32 v[42:43], v[80:81], v[18:19]
	v_pk_mul_f32 v[128:129], v[84:85], v[14:15]
	v_mul_f32_e32 v19, v11, v11
	v_mul_f32_e32 v21, v13, v13
	v_fmac_f32_e32 v156, v14, v14
	v_cvt_pk_bf16_f32 v14, v42, v43
	v_pk_mul_f32 v[44:45], v[82:83], v[16:17]
	v_mul_f32_e32 v158, v3, v3
	v_mul_f32_e32 v159, v5, v5
	v_fmac_f32_e32 v154, v18, v18
	v_fmac_f32_e32 v155, v20, v20
	v_fmac_f32_e32 v157, v16, v16
	v_cvt_pk_bf16_f32 v15, v34, v35
	v_cvt_pk_bf16_f32 v16, v128, v129
	v_cvt_pk_bf16_f32 v17, v44, v45
	v_fmac_f32_e32 v19, v10, v10
	v_fmac_f32_e32 v21, v12, v12
	global_store_dwordx4 v[38:39], v[14:17], off
	v_lshlrev_b32_e32 v20, 16, v14
	v_pk_mul_f32 v[150:151], v[100:101], v[4:5]
	v_and_b32_e32 v14, 0xffff0000, v14
	v_pk_mul_f32 v[152:153], v[102:103], v[2:3]
	v_fmac_f32_e32 v158, v2, v2
	v_fmac_f32_e32 v159, v4, v4
	v_add_f32_e32 v18, v154, v155
	v_lshlrev_b32_e32 v34, 16, v15
	v_and_b32_e32 v15, 0xffff0000, v15
	global_store_dwordx4 v[178:179], v[10:13], off offset:512 nt
	global_store_dwordx4 v[178:179], v[2:5], off offset:528 nt
	v_lshlrev_b32_e32 v35, 16, v16
	v_and_b32_e32 v16, 0xffff0000, v16
	v_add_f32_e32 v2, v19, v21
	v_max3_f32 v4, |v20|, 0, |v14|
	v_add_f32_e32 v3, v156, v18
	v_add_f32_e32 v2, v158, v2
	v_max3_f32 v4, v4, |v34|, |v15|
	v_lshlrev_b32_e32 v42, 16, v17
	v_and_b32_e32 v17, 0xffff0000, v17
	v_add_f32_e32 v3, v157, v3
	v_add_f32_e32 v2, v159, v2
	v_max3_f32 v4, v4, |v35|, |v16|
	v_pk_mul_f32 v[148:149], v[98:99], v[10:11]
	v_add_f32_e32 v2, v3, v2
	v_cvt_pk_bf16_f32 v10, v148, v149
	v_max3_f32 v3, v4, |v42|, |v17|
	v_lshlrev_b32_e32 v5, 16, v10
	v_and_b32_e32 v14, 0xffff0000, v10
	v_pk_mul_f32 v[146:147], v[96:97], v[12:13]
	v_max3_f32 v3, v3, |v5|, |v14|
	v_cvt_pk_bf16_f32 v11, v146, v147
	v_cvt_pk_bf16_f32 v12, v152, v153
	v_cvt_pk_bf16_f32 v13, v150, v151
	ds_bpermute_b32 v4, v233, v2
	v_lshlrev_b32_e32 v18, 16, v11
	v_and_b32_e32 v19, 0xffff0000, v11
	v_lshlrev_b32_e32 v20, 16, v12
	v_and_b32_e32 v21, 0xffff0000, v12
	v_max3_f32 v3, v3, |v18|, |v19|
	v_lshlrev_b32_e32 v43, 16, v13
	v_and_b32_e32 v44, 0xffff0000, v13
	v_max3_f32 v3, v3, |v20|, |v21|
	v_max3_f32 v5, v3, |v43|, |v44|
	ds_bpermute_b32 v14, v233, v5
	s_waitcnt lgkmcnt(1)
	v_add_f32_e32 v2, v2, v4
	ds_bpermute_b32 v3, v216, v2
	global_store_dwordx4 v[38:39], v[10:13], off offset:256
	s_waitcnt lgkmcnt(1)
	v_max_f32_e32 v4, v14, v14
	v_max_f32_e32 v4, v5, v4
	ds_bpermute_b32 v5, v216, v4
	s_and_saveexec_b64 s[42:43], s[0:1]
	s_cbranch_execz .LBB0_3627
	s_waitcnt lgkmcnt(0)
	v_max_f32_e32 v5, v5, v5
	v_max_f32_e32 v4, v4, v4
	v_add_f32_e32 v11, v2, v3
	v_lshlrev_b64 v[2:3], 7, v[176:177]
	v_max_f32_e32 v10, v4, v5
	v_lshl_add_u64 v[4:5], s[26:27], 0, v[2:3]
	s_lshl_b64 s[70:71], s[40:41], 2
	v_lshl_add_u64 v[2:3], s[28:29], 0, v[2:3]
	v_lshl_add_u64 v[4:5], v[4:5], 0, s[70:71]
	s_lshl_b32 s12, s59, 2
	v_lshl_add_u64 v[2:3], v[2:3], 0, s[70:71]
	v_lshl_add_u64 v[4:5], v[4:5], 0, s[12:13]
	v_lshl_add_u64 v[2:3], v[2:3], 0, s[12:13]
	global_store_dword v[4:5], v11, off
	global_store_dword v[2:3], v10, off
.LBB0_3627:
	s_or_b64 exec, exec, s[42:43]
	v_or_b32_e32 v34, 32, v176
	v_ashrrev_i32_e32 v35, 31, v34
	s_waitcnt lgkmcnt(1)
	v_lshlrev_b64 v[2:3], 13, v[34:35]
	v_lshl_add_u64 v[2:3], s[16:17], 0, v[2:3]
	v_lshl_add_u64 v[38:39], v[90:91], 2, v[2:3]
	global_load_dwordx4 v[14:17], v[38:39], off offset:16 nt
	global_load_dwordx4 v[18:21], v[38:39], off nt
	s_waitcnt lgkmcnt(0)
	global_load_dwordx4 v[2:5], v[38:39], off offset:528 nt
	global_load_dwordx4 v[10:13], v[38:39], off offset:512 nt
	v_lshl_add_u64 v[42:43], v[36:37], 2, s[18:19]
	s_nop 1
	v_mov_b32_e32 v42, v245
	v_lshlrev_b64 v[44:45], 12, v[36:37]
	v_lshl_add_u64 v[44:45], s[22:23], 0, v[44:45]
	v_lshl_add_u64 v[44:45], v[90:91], 1, v[44:45]
	s_waitcnt vmcnt(12)
	v_pk_mul_f32 v[118:119], v[42:43], v[118:119] op_sel_hi:[0,1]
	v_pk_mul_f32 v[114:115], v[42:43], v[114:115] op_sel_hi:[0,1]
	v_pk_mul_f32 v[112:113], v[42:43], v[112:113] op_sel_hi:[0,1]
	v_pk_mul_f32 v[116:117], v[42:43], v[116:117] op_sel_hi:[0,1]
	v_pk_mul_f32 v[124:125], v[42:43], v[124:125] op_sel_hi:[0,1]
	v_pk_mul_f32 v[120:121], v[42:43], v[120:121] op_sel_hi:[0,1]
	v_pk_fma_f32 v[26:27], v[94:95], v[118:119], v[26:27]
	v_pk_mul_f32 v[126:127], v[42:43], v[126:127] op_sel_hi:[0,1]
	v_pk_mul_f32 v[42:43], v[42:43], v[122:123] op_sel_hi:[0,1]
	v_pk_fma_f32 v[32:33], v[86:87], v[112:113], v[32:33]
	v_pk_fma_f32 v[30:31], v[88:89], v[114:115], v[30:31]
	v_pk_fma_f32 v[28:29], v[92:93], v[116:117], v[28:29]
	v_pk_fma_f32 v[24:25], v[104:105], v[120:121], v[24:25]
	v_pk_fma_f32 v[22:23], v[106:107], v[124:125], v[22:23]
	v_mul_f32_e32 v128, v27, v27
	v_pk_fma_f32 v[8:9], v[110:111], v[42:43], v[8:9]
	v_pk_fma_f32 v[6:7], v[108:109], v[126:127], v[6:7]
	global_store_dwordx4 v[40:41], v[30:33], off nt
	global_store_dwordx4 v[40:41], v[26:29], off offset:16 nt
	v_mul_f32_e32 v126, v31, v31
	v_mul_f32_e32 v127, v33, v33
	v_mul_f32_e32 v129, v29, v29
	v_pk_mul_f32 v[42:43], v[78:79], v[32:33]
	v_pk_mul_f32 v[112:113], v[80:81], v[30:31]
	v_pk_mul_f32 v[116:117], v[84:85], v[26:27]
	v_mul_f32_e32 v31, v23, v23
	v_mul_f32_e32 v33, v25, v25
	v_fmac_f32_e32 v128, v26, v26
	v_cvt_pk_bf16_f32 v26, v112, v113
	v_pk_mul_f32 v[114:115], v[82:83], v[28:29]
	v_mul_f32_e32 v146, v7, v7
	v_mul_f32_e32 v147, v9, v9
	v_fmac_f32_e32 v126, v30, v30
	v_fmac_f32_e32 v127, v32, v32
	v_fmac_f32_e32 v129, v28, v28
	v_cvt_pk_bf16_f32 v27, v42, v43
	v_cvt_pk_bf16_f32 v28, v116, v117
	v_cvt_pk_bf16_f32 v29, v114, v115
	v_fmac_f32_e32 v31, v22, v22
	v_fmac_f32_e32 v33, v24, v24
	global_store_dwordx4 v[44:45], v[26:29], off
	v_lshlrev_b32_e32 v32, 16, v26
	v_pk_mul_f32 v[122:123], v[100:101], v[8:9]
	v_and_b32_e32 v26, 0xffff0000, v26
	v_pk_mul_f32 v[124:125], v[102:103], v[6:7]
	v_fmac_f32_e32 v146, v6, v6
	v_fmac_f32_e32 v147, v8, v8
	v_add_f32_e32 v30, v126, v127
	v_lshlrev_b32_e32 v42, 16, v27
	v_and_b32_e32 v27, 0xffff0000, v27
	global_store_dwordx4 v[40:41], v[22:25], off offset:512 nt
	global_store_dwordx4 v[40:41], v[6:9], off offset:528 nt
	v_lshlrev_b32_e32 v43, 16, v28
	v_and_b32_e32 v28, 0xffff0000, v28
	v_add_f32_e32 v6, v31, v33
	v_max3_f32 v8, |v32|, 0, |v26|
	v_add_f32_e32 v7, v128, v30
	v_add_f32_e32 v6, v146, v6
	v_max3_f32 v8, v8, |v42|, |v27|
	v_lshlrev_b32_e32 v112, 16, v29
	v_and_b32_e32 v29, 0xffff0000, v29
	v_add_f32_e32 v7, v129, v7
	v_add_f32_e32 v6, v147, v6
	v_max3_f32 v8, v8, |v43|, |v28|
	v_pk_mul_f32 v[120:121], v[98:99], v[22:23]
	v_add_f32_e32 v6, v7, v6
	v_cvt_pk_bf16_f32 v22, v120, v121
	v_max3_f32 v7, v8, |v112|, |v29|
	v_lshlrev_b32_e32 v9, 16, v22
	v_and_b32_e32 v26, 0xffff0000, v22
	v_pk_mul_f32 v[118:119], v[96:97], v[24:25]
	v_max3_f32 v7, v7, |v9|, |v26|
	v_cvt_pk_bf16_f32 v23, v118, v119
	v_cvt_pk_bf16_f32 v24, v124, v125
	v_cvt_pk_bf16_f32 v25, v122, v123
	ds_bpermute_b32 v8, v233, v6
	v_lshlrev_b32_e32 v30, 16, v23
	v_and_b32_e32 v31, 0xffff0000, v23
	v_lshlrev_b32_e32 v32, 16, v24
	v_and_b32_e32 v33, 0xffff0000, v24
	v_max3_f32 v7, v7, |v30|, |v31|
	v_lshlrev_b32_e32 v40, 16, v25
	v_and_b32_e32 v41, 0xffff0000, v25
	v_max3_f32 v7, v7, |v32|, |v33|
	v_max3_f32 v9, v7, |v40|, |v41|
	ds_bpermute_b32 v26, v233, v9
	s_waitcnt lgkmcnt(1)
	v_add_f32_e32 v6, v6, v8
	ds_bpermute_b32 v7, v216, v6
	global_store_dwordx4 v[44:45], v[22:25], off offset:256
	s_waitcnt lgkmcnt(1)
	v_max_f32_e32 v8, v26, v26
	v_max_f32_e32 v8, v9, v8
	ds_bpermute_b32 v9, v216, v8
	s_and_saveexec_b64 s[42:43], s[0:1]
	s_cbranch_execz .LBB0_3629
	s_waitcnt lgkmcnt(0)
	v_max_f32_e32 v9, v9, v9
	v_max_f32_e32 v8, v8, v8
	v_add_f32_e32 v23, v6, v7
	v_lshlrev_b64 v[6:7], 7, v[36:37]
	v_max_f32_e32 v22, v8, v9
	v_lshl_add_u64 v[8:9], s[26:27], 0, v[6:7]
	s_lshl_b64 s[70:71], s[40:41], 2
	v_lshl_add_u64 v[6:7], s[28:29], 0, v[6:7]
	v_lshl_add_u64 v[8:9], v[8:9], 0, s[70:71]
	s_lshl_b32 s12, s59, 2
	v_lshl_add_u64 v[6:7], v[6:7], 0, s[70:71]
	v_lshl_add_u64 v[8:9], v[8:9], 0, s[12:13]
	v_lshl_add_u64 v[6:7], v[6:7], 0, s[12:13]
	global_store_dword v[8:9], v23, off
	global_store_dword v[6:7], v22, off
.LBB0_3629:
	s_or_b64 exec, exec, s[42:43]
	v_or_b32_e32 v36, 48, v176
	v_ashrrev_i32_e32 v37, 31, v36
	s_waitcnt lgkmcnt(1)
	v_lshlrev_b64 v[6:7], 13, v[36:37]
	v_lshl_add_u64 v[6:7], s[16:17], 0, v[6:7]
	v_lshl_add_u64 v[40:41], v[90:91], 2, v[6:7]
	global_load_dwordx4 v[26:29], v[40:41], off offset:16 nt
	global_load_dwordx4 v[30:33], v[40:41], off nt
	s_waitcnt lgkmcnt(0)
	global_load_dwordx4 v[6:9], v[40:41], off offset:528 nt
	global_load_dwordx4 v[22:25], v[40:41], off offset:512 nt
	v_lshl_add_u64 v[42:43], v[34:35], 2, s[18:19]
	s_nop 1
	v_mov_b32_e32 v42, v246
	v_lshlrev_b64 v[44:45], 12, v[34:35]
	v_lshl_add_u64 v[44:45], s[22:23], 0, v[44:45]
	v_lshl_add_u64 v[44:45], v[90:91], 1, v[44:45]
	s_waitcnt vmcnt(12)
	v_pk_mul_f32 v[68:69], v[42:43], v[68:69] op_sel_hi:[0,1]
	v_pk_mul_f32 v[64:65], v[42:43], v[64:65] op_sel_hi:[0,1]
	v_pk_mul_f32 v[62:63], v[42:43], v[62:63] op_sel_hi:[0,1]
	v_pk_mul_f32 v[66:67], v[42:43], v[66:67] op_sel_hi:[0,1]
	v_pk_mul_f32 v[74:75], v[42:43], v[74:75] op_sel_hi:[0,1]
	v_pk_mul_f32 v[70:71], v[42:43], v[70:71] op_sel_hi:[0,1]
	v_pk_fma_f32 v[14:15], v[94:95], v[68:69], v[14:15]
	v_pk_mul_f32 v[76:77], v[42:43], v[76:77] op_sel_hi:[0,1]
	v_pk_mul_f32 v[42:43], v[42:43], v[72:73] op_sel_hi:[0,1]
	v_pk_fma_f32 v[20:21], v[86:87], v[62:63], v[20:21]
	v_pk_fma_f32 v[18:19], v[88:89], v[64:65], v[18:19]
	v_pk_fma_f32 v[16:17], v[92:93], v[66:67], v[16:17]
	v_pk_fma_f32 v[12:13], v[104:105], v[70:71], v[12:13]
	v_pk_fma_f32 v[10:11], v[106:107], v[74:75], v[10:11]
	v_mul_f32_e32 v112, v15, v15
	v_pk_fma_f32 v[4:5], v[110:111], v[42:43], v[4:5]
	v_pk_fma_f32 v[2:3], v[108:109], v[76:77], v[2:3]
	global_store_dwordx4 v[38:39], v[18:21], off nt
	global_store_dwordx4 v[38:39], v[14:17], off offset:16 nt
	v_mul_f32_e32 v76, v19, v19
	v_mul_f32_e32 v77, v21, v21
	v_mul_f32_e32 v113, v17, v17
	v_pk_mul_f32 v[42:43], v[78:79], v[20:21]
	v_pk_mul_f32 v[62:63], v[80:81], v[18:19]
	v_pk_mul_f32 v[66:67], v[84:85], v[14:15]
	v_mul_f32_e32 v19, v11, v11
	v_mul_f32_e32 v21, v13, v13
	v_fmac_f32_e32 v112, v14, v14
	v_cvt_pk_bf16_f32 v14, v62, v63
	v_pk_mul_f32 v[64:65], v[82:83], v[16:17]
	v_mul_f32_e32 v114, v3, v3
	v_mul_f32_e32 v115, v5, v5
	v_fmac_f32_e32 v76, v18, v18
	v_fmac_f32_e32 v77, v20, v20
	v_fmac_f32_e32 v113, v16, v16
	v_cvt_pk_bf16_f32 v15, v42, v43
	v_cvt_pk_bf16_f32 v16, v66, v67
	v_cvt_pk_bf16_f32 v17, v64, v65
	v_fmac_f32_e32 v19, v10, v10
	v_fmac_f32_e32 v21, v12, v12
	global_store_dwordx4 v[44:45], v[14:17], off
	v_lshlrev_b32_e32 v20, 16, v14
	v_pk_mul_f32 v[72:73], v[100:101], v[4:5]
	v_and_b32_e32 v14, 0xffff0000, v14
	v_pk_mul_f32 v[74:75], v[102:103], v[2:3]
	v_fmac_f32_e32 v114, v2, v2
	v_fmac_f32_e32 v115, v4, v4
	v_add_f32_e32 v18, v76, v77
	v_lshlrev_b32_e32 v42, 16, v15
	v_and_b32_e32 v15, 0xffff0000, v15
	global_store_dwordx4 v[38:39], v[10:13], off offset:512 nt
	global_store_dwordx4 v[38:39], v[2:5], off offset:528 nt
	v_lshlrev_b32_e32 v43, 16, v16
	v_and_b32_e32 v16, 0xffff0000, v16
	v_add_f32_e32 v2, v19, v21
	v_max3_f32 v4, |v20|, 0, |v14|
	v_add_f32_e32 v3, v112, v18
	v_add_f32_e32 v2, v114, v2
	v_max3_f32 v4, v4, |v42|, |v15|
	v_lshlrev_b32_e32 v62, 16, v17
	v_and_b32_e32 v17, 0xffff0000, v17
	v_add_f32_e32 v3, v113, v3
	v_add_f32_e32 v2, v115, v2
	v_max3_f32 v4, v4, |v43|, |v16|
	v_pk_mul_f32 v[70:71], v[98:99], v[10:11]
	v_add_f32_e32 v2, v3, v2
	v_cvt_pk_bf16_f32 v10, v70, v71
	v_max3_f32 v3, v4, |v62|, |v17|
	v_lshlrev_b32_e32 v5, 16, v10
	v_and_b32_e32 v14, 0xffff0000, v10
	v_pk_mul_f32 v[68:69], v[96:97], v[12:13]
	v_max3_f32 v3, v3, |v5|, |v14|
	v_cvt_pk_bf16_f32 v11, v68, v69
	v_cvt_pk_bf16_f32 v12, v74, v75
	v_cvt_pk_bf16_f32 v13, v72, v73
	ds_bpermute_b32 v4, v233, v2
	v_lshlrev_b32_e32 v18, 16, v11
	v_and_b32_e32 v19, 0xffff0000, v11
	v_lshlrev_b32_e32 v20, 16, v12
	v_and_b32_e32 v21, 0xffff0000, v12
	v_max3_f32 v3, v3, |v18|, |v19|
	v_lshlrev_b32_e32 v38, 16, v13
	v_and_b32_e32 v39, 0xffff0000, v13
	v_max3_f32 v3, v3, |v20|, |v21|
	v_max3_f32 v5, v3, |v38|, |v39|
	ds_bpermute_b32 v14, v233, v5
	s_waitcnt lgkmcnt(1)
	v_add_f32_e32 v2, v2, v4
	ds_bpermute_b32 v3, v216, v2
	global_store_dwordx4 v[44:45], v[10:13], off offset:256
	s_waitcnt lgkmcnt(1)
	v_max_f32_e32 v4, v14, v14
	v_max_f32_e32 v4, v5, v4
	ds_bpermute_b32 v5, v216, v4
	s_and_saveexec_b64 s[42:43], s[0:1]
	s_cbranch_execz .LBB0_3631
	s_waitcnt lgkmcnt(0)
	v_max_f32_e32 v5, v5, v5
	v_max_f32_e32 v4, v4, v4
	v_add_f32_e32 v11, v2, v3
	v_lshlrev_b64 v[2:3], 7, v[34:35]
	v_max_f32_e32 v10, v4, v5
	v_lshl_add_u64 v[4:5], s[26:27], 0, v[2:3]
	s_lshl_b64 s[70:71], s[40:41], 2
	v_lshl_add_u64 v[2:3], s[28:29], 0, v[2:3]
	v_lshl_add_u64 v[4:5], v[4:5], 0, s[70:71]
	s_lshl_b32 s12, s59, 2
	v_lshl_add_u64 v[2:3], v[2:3], 0, s[70:71]
	v_lshl_add_u64 v[4:5], v[4:5], 0, s[12:13]
	v_lshl_add_u64 v[2:3], v[2:3], 0, s[12:13]
	global_store_dword v[4:5], v11, off
	global_store_dword v[2:3], v10, off
.LBB0_3631:
	s_or_b64 exec, exec, s[42:43]
	s_waitcnt lgkmcnt(1)
	v_lshl_add_u64 v[2:3], v[36:37], 2, s[18:19]
	s_nop 1
	v_mov_b32_e32 v2, v247
	s_waitcnt lgkmcnt(0)
	v_lshlrev_b64 v[4:5], 12, v[36:37]
	v_lshl_add_u64 v[4:5], s[22:23], 0, v[4:5]
	v_lshl_add_u64 v[18:19], v[90:91], 1, v[4:5]
	s_waitcnt vmcnt(8)
	v_pk_mul_f32 v[10:11], v[2:3], v[48:49] op_sel_hi:[0,1]
	v_pk_mul_f32 v[4:5], v[2:3], v[46:47] op_sel_hi:[0,1]
	v_pk_mul_f32 v[14:15], v[2:3], v[52:53] op_sel_hi:[0,1]
	v_pk_mul_f32 v[12:13], v[2:3], v[50:51] op_sel_hi:[0,1]
	v_pk_mul_f32 v[20:21], v[2:3], v[58:59] op_sel_hi:[0,1]
	v_pk_mul_f32 v[16:17], v[2:3], v[54:55] op_sel_hi:[0,1]
	v_pk_mul_f32 v[34:35], v[2:3], v[60:61] op_sel_hi:[0,1]
	v_pk_mul_f32 v[38:39], v[2:3], v[56:57] op_sel_hi:[0,1]
	v_pk_fma_f32 v[2:3], v[88:89], v[10:11], v[30:31]
	v_pk_fma_f32 v[4:5], v[86:87], v[4:5], v[32:33]
	v_pk_fma_f32 v[12:13], v[92:93], v[12:13], v[28:29]
	v_pk_fma_f32 v[8:9], v[110:111], v[38:39], v[8:9]
	v_mul_f32_e32 v38, v3, v3
	v_pk_fma_f32 v[10:11], v[94:95], v[14:15], v[26:27]
	v_pk_fma_f32 v[14:15], v[106:107], v[20:21], v[22:23]
	global_store_dwordx4 v[40:41], v[2:5], off nt
	global_store_dwordx4 v[40:41], v[10:13], off offset:16 nt
	v_mul_f32_e32 v39, v5, v5
	v_mul_f32_e32 v43, v13, v13
	v_pk_mul_f32 v[22:23], v[80:81], v[2:3]
	v_fmac_f32_e32 v38, v2, v2
	v_cvt_pk_bf16_f32 v2, v22, v23
	v_pk_fma_f32 v[16:17], v[104:105], v[16:17], v[24:25]
	v_pk_mul_f32 v[20:21], v[78:79], v[4:5]
	v_pk_mul_f32 v[24:25], v[82:83], v[12:13]
	v_pk_mul_f32 v[26:27], v[84:85], v[10:11]
	v_fmac_f32_e32 v39, v4, v4
	v_fmac_f32_e32 v43, v12, v12
	v_cvt_pk_bf16_f32 v3, v20, v21
	v_cvt_pk_bf16_f32 v4, v26, v27
	v_cvt_pk_bf16_f32 v5, v24, v25
	global_store_dwordx4 v[18:19], v[2:5], off
	v_lshlrev_b32_e32 v12, 16, v2
	v_lshlrev_b32_e32 v20, 16, v3
	v_and_b32_e32 v2, 0xffff0000, v2
	v_and_b32_e32 v3, 0xffff0000, v3
	v_max3_f32 v2, |v12|, 0, |v2|
	v_pk_fma_f32 v[6:7], v[108:109], v[34:35], v[6:7]
	v_mul_f32_e32 v42, v11, v11
	v_mul_f32_e32 v11, v15, v15
	v_mul_f32_e32 v13, v17, v17
	v_lshlrev_b32_e32 v21, 16, v4
	v_and_b32_e32 v4, 0xffff0000, v4
	v_max3_f32 v2, v2, |v20|, |v3|
	v_mul_f32_e32 v44, v7, v7
	v_fmac_f32_e32 v11, v14, v14
	v_fmac_f32_e32 v13, v16, v16
	v_lshlrev_b32_e32 v22, 16, v5
	v_and_b32_e32 v5, 0xffff0000, v5
	v_max3_f32 v2, v2, |v21|, |v4|
	v_pk_mul_f32 v[30:31], v[98:99], v[14:15]
	v_pk_mul_f32 v[34:35], v[102:103], v[6:7]
	v_fmac_f32_e32 v44, v6, v6
	global_store_dwordx4 v[40:41], v[14:17], off offset:512 nt
	global_store_dwordx4 v[40:41], v[6:9], off offset:528 nt
	v_add_f32_e32 v11, v11, v13
	v_max3_f32 v2, v2, |v22|, |v5|
	v_cvt_pk_bf16_f32 v6, v30, v31
	v_mul_f32_e32 v45, v9, v9
	v_lshlrev_b32_e32 v12, 16, v6
	v_and_b32_e32 v13, 0xffff0000, v6
	v_pk_mul_f32 v[28:29], v[96:97], v[16:17]
	v_fmac_f32_e32 v42, v10, v10
	v_add_f32_e32 v10, v38, v39
	v_cvt_pk_bf16_f32 v7, v28, v29
	v_max3_f32 v2, v2, |v12|, |v13|
	v_lshlrev_b32_e32 v14, 16, v7
	v_and_b32_e32 v15, 0xffff0000, v7
	v_pk_mul_f32 v[32:33], v[100:101], v[8:9]
	v_fmac_f32_e32 v45, v8, v8
	v_cvt_pk_bf16_f32 v8, v34, v35
	v_add_f32_e32 v10, v42, v10
	v_add_f32_e32 v11, v44, v11
	v_lshlrev_b32_e32 v16, 16, v8
	v_and_b32_e32 v17, 0xffff0000, v8
	v_max3_f32 v2, v2, |v14|, |v15|
	v_cvt_pk_bf16_f32 v9, v32, v33
	v_add_f32_e32 v10, v43, v10
	v_lshlrev_b32_e32 v23, 16, v9
	v_and_b32_e32 v24, 0xffff0000, v9
	v_add_f32_e32 v3, v45, v11
	v_max3_f32 v2, v2, |v16|, |v17|
	v_add_f32_e32 v3, v10, v3
	v_max3_f32 v5, v2, |v23|, |v24|
	ds_bpermute_b32 v4, v233, v3
	ds_bpermute_b32 v10, v233, v5
	global_store_dwordx4 v[18:19], v[6:9], off offset:256
	s_waitcnt lgkmcnt(1)
	v_add_f32_e32 v2, v3, v4
	s_waitcnt lgkmcnt(0)
	v_max_f32_e32 v4, v10, v10
	v_max_f32_e32 v4, v5, v4
	ds_bpermute_b32 v3, v216, v2
	ds_bpermute_b32 v5, v216, v4
	s_and_saveexec_b64 s[42:43], s[0:1]
	s_cbranch_execz .LBB0_3633
	s_waitcnt lgkmcnt(0)
	v_max_f32_e32 v5, v5, v5
	v_max_f32_e32 v4, v4, v4
	v_add_f32_e32 v7, v2, v3
	v_lshlrev_b64 v[2:3], 7, v[36:37]
	v_max_f32_e32 v6, v4, v5
	v_lshl_add_u64 v[4:5], s[26:27], 0, v[2:3]
	s_lshl_b64 s[40:41], s[40:41], 2
	v_lshl_add_u64 v[2:3], s[28:29], 0, v[2:3]
	v_lshl_add_u64 v[4:5], v[4:5], 0, s[40:41]
	s_lshl_b32 s12, s59, 2
	v_lshl_add_u64 v[2:3], v[2:3], 0, s[40:41]
	v_lshl_add_u64 v[4:5], v[4:5], 0, s[12:13]
	v_lshl_add_u64 v[2:3], v[2:3], 0, s[12:13]
	global_store_dword v[4:5], v7, off
	global_store_dword v[2:3], v6, off
